# GDN intra prep_seg: 11 row loads per segment issued back to back instead of one load + vmcnt(0) each
# speedup vs baseline: 1.0219x; 1.0219x over previous
; #define GAS __attribute__((address_space(1)))
; __device__ __forceinline__ void prep_seg(const bf16_t* QK, const float* cw, const size_t rowbase, const int t0, const int h, const int seg, const int lane, float (&o)[8][8]) {
;     const int rg = lane >> 3, cg = lane & 7, col = seg * 512 + h * 64 + cg * 8;
;     float wt[4][8];
; #pragma unroll
;     for (int j = 0; j < 4; ++j) { const f32x4 a = *(const GAS f32x4*)(cw + j * CONVD + col), b = *(const GAS f32x4*)(cw + j * CONVD + col + 4); wt[j][0] = a.x; wt[j][1] = a.y; wt[j][2] = a.z; wt[j][3] = a.w; wt[j][4] = b.x; wt[j][5] = b.y; wt[j][6] = b.z; wt[j][7] = b.w; }
; #pragma unroll
;     for (int r = 0; r < 8; ++r)
; #pragma unroll
;         for (int e = 0; e < 8; ++e) o[r][e] = 0.f;
; #pragma unroll
;     for (int rr = 0; rr < 11; ++rr) { const int t = t0 + 8 * rg + rr - 3; float x[8];
;         if (t >= 0) unpack8(*(const GAS v4u*)(QK + (rowbase + t) * CONVD + col), x); else {
; #pragma unroll
;             for (int e = 0; e < 8; ++e) x[e] = 0.f; }
.LBB0_908:
	s_or_b64 exec, exec, s[0:1]
	s_lshl_b32 s0, s3, 6
	v_lshlrev_b32_e32 v172, 3, v88
	v_and_or_b32 v89, v172, 56, s0
	v_lshlrev_b32_e32 v64, 2, v89
	v_lshl_add_u64 v[34:35], s[70:71], 0, v[64:65]
	v_add_co_u32_e32 v2, vcc, 0x2000, v34
	s_mov_b64 s[0:1], 0x2000
	s_nop 0
	v_addc_co_u32_e32 v3, vcc, 0, v35, vcc
	global_load_dwordx4 v[8:11], v64, s[70:71] offset:2064
	global_load_dwordx4 v[20:23], v64, s[70:71] offset:2048
	v_lshl_add_u64 v[0:1], v[34:35], 0, s[0:1]
	global_load_dwordx4 v[16:19], v[2:3], off
	global_load_dwordx4 v[12:15], v[0:1], off offset:16
	s_mov_b64 s[0:1], 0x3800
	v_add_co_u32_e32 v2, vcc, 0x3000, v34
	v_lshl_add_u64 v[0:1], v[34:35], 0, s[0:1]
	s_nop 0
	v_addc_co_u32_e32 v3, vcc, 0, v35, vcc
	global_load_dwordx4 v[28:31], v[2:3], off offset:2048
	global_load_dwordx4 v[24:27], v[0:1], off offset:16
	s_mov_b64 s[0:1], 0x5000
	v_add_co_u32_e32 v0, vcc, 0x5000, v34
	v_lshl_add_u64 v[4:5], v[34:35], 0, s[0:1]
	s_nop 0
	v_addc_co_u32_e32 v1, vcc, 0, v35, vcc
	global_load_dwordx4 v[0:3], v[0:1], off
	s_nop 0
	global_load_dwordx4 v[4:7], v[4:5], off offset:16
	ds_read_b32 v33, v210 offset:18684
	v_and_b32_e32 v158, -8, v88
	v_or_b32_e32 v32, 0x200, v89
	v_add_u32_e32 v66, s2, v158
	v_cmp_lt_i32_e64 s[0:1], 2, v66
	v_mov_b32_e32 v60, 0
	v_add_u32_e32 v68, -3, v66
	v_lshlrev_b32_e32 v64, 1, v32
	v_mov_b32_e32 v62, 0
	v_mov_b32_e32 v63, 0
	v_mov_b32_e32 v90, 0
	v_mov_b32_e32 v91, 0
	v_mov_b32_e32 v92, 0
	v_mov_b32_e32 v93, 0
	v_mov_b32_e32 v94, 0
	v_mov_b32_e32 v95, 0
	v_mov_b32_e32 v196, 0
	v_mov_b32_e32 v197, 0
	v_mov_b32_e32 v198, 0
	v_mov_b32_e32 v199, 0
	s_and_saveexec_b64 s[2:3], s[0:1]
	v_mov_b32_e32 v69, v65
	v_lshl_add_u64 v[36:37], s[82:83], 0, v[68:69]
	v_mov_b64_e32 v[38:39], s[46:47]
	v_mad_u64_u32 v[38:39], s[4:5], v36, s72, v[38:39]
	v_mad_i32_i24 v39, v37, s72, v39
	v_lshl_add_u64 v[36:37], v[38:39], 0, v[64:65]
	global_load_dwordx4 v[196:199], v[36:37], off
.LBB0_910:
	s_or_b64 exec, exec, s[2:3]
	v_cmp_lt_i32_e64 s[2:3], 1, v66
	v_add_u32_e32 v70, -2, v66
	v_mov_b32_e32 v61, 0
	v_mov_b32_e32 v96, 0
	v_mov_b32_e32 v97, 0
	v_mov_b32_e32 v98, 0
	v_mov_b32_e32 v99, 0
	v_mov_b32_e32 v100, 0
	v_mov_b32_e32 v101, 0
	v_mov_b32_e32 v204, 0
	v_mov_b32_e32 v205, 0
	v_mov_b32_e32 v206, 0
	v_mov_b32_e32 v207, 0
	s_and_saveexec_b64 s[4:5], s[2:3]
	v_mov_b32_e32 v71, v65
	v_lshl_add_u64 v[36:37], s[82:83], 0, v[70:71]
	v_mov_b64_e32 v[38:39], s[46:47]
	v_mad_u64_u32 v[38:39], s[6:7], v36, s72, v[38:39]
	v_mad_i32_i24 v39, v37, s72, v39
	v_lshl_add_u64 v[36:37], v[38:39], 0, v[64:65]
	global_load_dwordx4 v[204:207], v[36:37], off
.LBB0_912:
	s_or_b64 exec, exec, s[4:5]
	v_cmp_lt_i32_e64 s[4:5], 0, v66
	v_mov_b32_e32 v102, 0
	v_add_u32_e32 v72, -1, v66
	v_mov_b32_e32 v104, 0
	v_mov_b32_e32 v105, 0
	v_mov_b32_e32 v106, 0
	v_mov_b32_e32 v107, 0
	v_mov_b32_e32 v108, 0
	v_mov_b32_e32 v109, 0
	v_mov_b32_e32 v110, 0
	v_mov_b32_e32 v111, 0
	v_mov_b32_e32 v212, 0
	v_mov_b32_e32 v213, 0
	v_mov_b32_e32 v214, 0
	v_mov_b32_e32 v215, 0
	s_and_saveexec_b64 s[6:7], s[4:5]
	v_mov_b32_e32 v73, v65
	v_lshl_add_u64 v[36:37], s[82:83], 0, v[72:73]
	v_mov_b64_e32 v[38:39], s[46:47]
	v_mad_u64_u32 v[38:39], s[8:9], v36, s72, v[38:39]
	v_mad_i32_i24 v39, v37, s72, v39
	v_lshl_add_u64 v[36:37], v[38:39], 0, v[64:65]
	global_load_dwordx4 v[212:215], v[36:37], off
.LBB0_914:
	s_or_b64 exec, exec, s[6:7]
	v_cmp_lt_i32_e64 s[6:7], -1, v66
	v_mov_b32_e32 v103, 0
	v_mov_b32_e32 v122, 0
	v_mov_b32_e32 v123, 0
	v_mov_b32_e32 v124, 0
	v_mov_b32_e32 v125, 0
	v_mov_b32_e32 v118, 0
	v_mov_b32_e32 v119, 0
	v_mov_b32_e32 v216, 0
	v_mov_b32_e32 v217, 0
	v_mov_b32_e32 v218, 0
	v_mov_b32_e32 v219, 0
	s_and_saveexec_b64 s[8:9], s[6:7]
	v_mov_b32_e32 v67, v65
	v_lshl_add_u64 v[36:37], s[82:83], 0, v[66:67]
	v_mov_b64_e32 v[38:39], s[46:47]
	v_mad_u64_u32 v[38:39], s[10:11], v36, s72, v[38:39]
	v_mad_i32_i24 v39, v37, s72, v39
	v_lshl_add_u64 v[36:37], v[38:39], 0, v[64:65]
	global_load_dwordx4 v[216:219], v[36:37], off
.LBB0_916:
	s_or_b64 exec, exec, s[8:9]
	v_or_b32_e32 v74, 1, v66
	v_cmp_lt_i32_e64 s[8:9], -2, v66
	v_mov_b32_e32 v142, 0
	v_mov_b32_e32 v130, 0
	v_mov_b32_e32 v131, 0
	v_mov_b32_e32 v134, 0
	v_mov_b32_e32 v135, 0
	v_mov_b32_e32 v138, 0
	v_mov_b32_e32 v139, 0
	v_mov_b32_e32 v140, 0
	v_mov_b32_e32 v141, 0
	v_mov_b32_e32 v220, 0
	v_mov_b32_e32 v221, 0
	v_mov_b32_e32 v222, 0
	v_mov_b32_e32 v223, 0
	s_and_saveexec_b64 s[10:11], s[8:9]
	v_mov_b32_e32 v75, v65
	v_lshl_add_u64 v[36:37], s[82:83], 0, v[74:75]
	v_mov_b64_e32 v[38:39], s[46:47]
	v_mad_u64_u32 v[38:39], s[12:13], v36, s72, v[38:39]
	v_mad_i32_i24 v39, v37, s72, v39
	v_lshl_add_u64 v[36:37], v[38:39], 0, v[64:65]
	global_load_dwordx4 v[220:223], v[36:37], off
.LBB0_918:
	s_or_b64 exec, exec, s[10:11]
	v_or_b32_e32 v76, 2, v66
	v_cmp_lt_i32_e64 s[10:11], -3, v66
	v_mov_b32_e32 v143, 0
	v_mov_b32_e32 v144, 0
	v_mov_b32_e32 v145, 0
	v_mov_b32_e32 v146, 0
	v_mov_b32_e32 v147, 0
	v_mov_b32_e32 v148, 0
	v_mov_b32_e32 v149, 0
	v_mov_b32_e32 v224, 0
	v_mov_b32_e32 v225, 0
	v_mov_b32_e32 v226, 0
	v_mov_b32_e32 v227, 0
	s_and_saveexec_b64 s[12:13], s[10:11]
	v_mov_b32_e32 v77, v65
	v_lshl_add_u64 v[36:37], s[82:83], 0, v[76:77]
	v_mov_b64_e32 v[38:39], s[46:47]
	v_mad_u64_u32 v[38:39], s[14:15], v36, s72, v[38:39]
	v_mad_i32_i24 v39, v37, s72, v39
	v_lshl_add_u64 v[36:37], v[38:39], 0, v[64:65]
	global_load_dwordx4 v[224:227], v[36:37], off
; #define GAS __attribute__((address_space(1)))
; __device__ __forceinline__ void prep_seg(const bf16_t* QK, const float* cw, const size_t rowbase, const int t0, const int h, const int seg, const int lane, float (&o)[8][8]) {
;     ...
;     for (int rr = 0; rr < 11; ++rr) { const int t = t0 + 8 * rg + rr - 3; float x[8];
;         if (t >= 0) unpack8(*(const GAS v4u*)(QK + (rowbase + t) * CONVD + col), x); else {
; #pragma unroll
;             for (int e = 0; e < 8; ++e) x[e] = 0.f; }
.LBB0_920:
	s_or_b64 exec, exec, s[12:13]
	v_or_b32_e32 v78, 3, v66
	v_cmp_lt_i32_e64 s[12:13], -4, v66
	v_mov_b32_e32 v126, 0
	v_mov_b32_e32 v150, 0
	v_mov_b32_e32 v151, 0
	v_mov_b32_e32 v152, 0
	v_mov_b32_e32 v153, 0
	v_mov_b32_e32 v154, 0
	v_mov_b32_e32 v155, 0
	v_mov_b32_e32 v156, 0
	v_mov_b32_e32 v157, 0
	v_mov_b32_e32 v228, 0
	v_mov_b32_e32 v229, 0
	v_mov_b32_e32 v230, 0
	v_mov_b32_e32 v231, 0
	s_and_saveexec_b64 s[14:15], s[12:13]
	v_mov_b32_e32 v79, v65
	v_lshl_add_u64 v[36:37], s[82:83], 0, v[78:79]
	v_mov_b64_e32 v[38:39], s[46:47]
	v_mad_u64_u32 v[38:39], s[16:17], v36, s72, v[38:39]
	v_mad_i32_i24 v39, v37, s72, v39
	v_lshl_add_u64 v[36:37], v[38:39], 0, v[64:65]
	global_load_dwordx4 v[228:231], v[36:37], off
.LBB0_922:
	s_or_b64 exec, exec, s[14:15]
	v_or_b32_e32 v80, 4, v66
	v_cmp_lt_i32_e64 s[14:15], -5, v66
	v_mov_b32_e32 v127, 0
	v_mov_b32_e32 v128, 0
	v_mov_b32_e32 v129, 0
	v_mov_b32_e32 v132, 0
	v_mov_b32_e32 v133, 0
	v_mov_b32_e32 v136, 0
	v_mov_b32_e32 v137, 0
	v_mov_b32_e32 v232, 0
	v_mov_b32_e32 v233, 0
	v_mov_b32_e32 v234, 0
	v_mov_b32_e32 v235, 0
	s_and_saveexec_b64 s[16:17], s[14:15]
	v_mov_b32_e32 v81, v65
	v_lshl_add_u64 v[36:37], s[82:83], 0, v[80:81]
	v_mov_b64_e32 v[38:39], s[46:47]
	v_mad_u64_u32 v[38:39], s[18:19], v36, s72, v[38:39]
	v_mad_i32_i24 v39, v37, s72, v39
	v_lshl_add_u64 v[36:37], v[38:39], 0, v[64:65]
	global_load_dwordx4 v[232:235], v[36:37], off
.LBB0_924:
	s_or_b64 exec, exec, s[16:17]
	v_or_b32_e32 v82, 5, v66
	v_cmp_lt_i32_e64 s[16:17], -6, v66
	v_mov_b32_e32 v50, 0
	v_mov_b32_e32 v112, 0
	v_mov_b32_e32 v113, 0
	v_mov_b32_e32 v114, 0
	v_mov_b32_e32 v115, 0
	v_mov_b32_e32 v116, 0
	v_mov_b32_e32 v117, 0
	v_mov_b32_e32 v120, 0
	v_mov_b32_e32 v121, 0
	v_mov_b32_e32 v236, 0
	v_mov_b32_e32 v237, 0
	v_mov_b32_e32 v238, 0
	v_mov_b32_e32 v239, 0
	s_and_saveexec_b64 s[18:19], s[16:17]
	v_mov_b32_e32 v83, v65
	v_lshl_add_u64 v[36:37], s[82:83], 0, v[82:83]
	v_mov_b64_e32 v[38:39], s[46:47]
	v_mad_u64_u32 v[38:39], s[20:21], v36, s72, v[38:39]
	v_mad_i32_i24 v39, v37, s72, v39
	v_lshl_add_u64 v[36:37], v[38:39], 0, v[64:65]
	global_load_dwordx4 v[236:239], v[36:37], off
.LBB0_926:
	s_or_b64 exec, exec, s[18:19]
	v_or_b32_e32 v84, 6, v66
	v_cmp_lt_i32_e64 s[18:19], -7, v66
	v_mov_b32_e32 v51, 0
	v_mov_b32_e32 v52, 0
	v_mov_b32_e32 v53, 0
	v_mov_b32_e32 v56, 0
	v_mov_b32_e32 v57, 0
	v_mov_b32_e32 v58, 0
	v_mov_b32_e32 v59, 0
	v_mov_b32_e32 v240, 0
	v_mov_b32_e32 v241, 0
	v_mov_b32_e32 v242, 0
	v_mov_b32_e32 v243, 0
	s_and_saveexec_b64 s[20:21], s[18:19]
	v_mov_b32_e32 v85, v65
	v_lshl_add_u64 v[36:37], s[82:83], 0, v[84:85]
	v_mov_b64_e32 v[38:39], s[46:47]
	v_mad_u64_u32 v[38:39], s[22:23], v36, s72, v[38:39]
	v_mad_i32_i24 v39, v37, s72, v39
	v_lshl_add_u64 v[36:37], v[38:39], 0, v[64:65]
	global_load_dwordx4 v[240:243], v[36:37], off
.LBB0_928:
	s_or_b64 exec, exec, s[20:21]
	v_or_b32_e32 v86, 7, v66
	v_cmp_lt_i32_e64 s[20:21], -8, v66
	v_mov_b32_e32 v32, 0
	v_mov_b32_e32 v36, 0
	v_mov_b32_e32 v37, 0
	v_mov_b32_e32 v38, 0
	v_mov_b32_e32 v39, 0
	v_mov_b32_e32 v40, 0
	v_mov_b32_e32 v41, 0
	v_mov_b32_e32 v42, 0
	v_mov_b32_e32 v43, 0
	v_mov_b32_e32 v244, 0
	v_mov_b32_e32 v245, 0
	v_mov_b32_e32 v246, 0
	v_mov_b32_e32 v247, 0
	s_and_saveexec_b64 s[22:23], s[20:21]
	v_mov_b32_e32 v87, v65
	v_lshl_add_u64 v[36:37], s[82:83], 0, v[86:87]
	v_mov_b64_e32 v[38:39], s[46:47]
	v_mad_u64_u32 v[38:39], s[24:25], v36, s72, v[38:39]
	v_mad_i32_i24 v39, v37, s72, v39
	v_lshl_add_u64 v[36:37], v[38:39], 0, v[64:65]
	global_load_dwordx4 v[244:247], v[36:37], off
.LBB0_930:
	s_or_b64 exec, exec, s[22:23]
	s_waitcnt vmcnt(10)
	v_lshlrev_b32_e32 v62, 16, v196
	v_and_b32_e32 v63, 0xffff0000, v196
	v_lshlrev_b32_e32 v90, 16, v197
	v_and_b32_e32 v91, 0xffff0000, v197
	v_lshlrev_b32_e32 v92, 16, v198
	v_and_b32_e32 v93, 0xffff0000, v198
	v_lshlrev_b32_e32 v94, 16, v199
	v_and_b32_e32 v95, 0xffff0000, v199
	s_waitcnt vmcnt(9)
	v_lshlrev_b32_e32 v60, 16, v204
	v_and_b32_e32 v61, 0xffff0000, v204
	v_lshlrev_b32_e32 v96, 16, v205
	v_and_b32_e32 v97, 0xffff0000, v205
	v_lshlrev_b32_e32 v98, 16, v206
	v_and_b32_e32 v99, 0xffff0000, v206
	v_lshlrev_b32_e32 v100, 16, v207
	v_and_b32_e32 v101, 0xffff0000, v207
	s_waitcnt vmcnt(8)
	v_lshlrev_b32_e32 v104, 16, v212
	v_and_b32_e32 v105, 0xffff0000, v212
	v_lshlrev_b32_e32 v106, 16, v213
	v_and_b32_e32 v107, 0xffff0000, v213
	v_lshlrev_b32_e32 v108, 16, v214
	v_and_b32_e32 v109, 0xffff0000, v214
	v_lshlrev_b32_e32 v110, 16, v215
	v_and_b32_e32 v111, 0xffff0000, v215
	s_waitcnt vmcnt(7)
	v_lshlrev_b32_e32 v102, 16, v216
	v_and_b32_e32 v103, 0xffff0000, v216
	v_lshlrev_b32_e32 v122, 16, v217
	v_and_b32_e32 v123, 0xffff0000, v217
	v_lshlrev_b32_e32 v124, 16, v218
	v_and_b32_e32 v125, 0xffff0000, v218
	v_lshlrev_b32_e32 v118, 16, v219
	v_and_b32_e32 v119, 0xffff0000, v219
	s_waitcnt vmcnt(6)
	v_lshlrev_b32_e32 v130, 16, v220
	v_and_b32_e32 v131, 0xffff0000, v220
	v_lshlrev_b32_e32 v134, 16, v221
	v_and_b32_e32 v135, 0xffff0000, v221
	v_lshlrev_b32_e32 v138, 16, v222
	v_and_b32_e32 v139, 0xffff0000, v222
	v_lshlrev_b32_e32 v140, 16, v223
	v_and_b32_e32 v141, 0xffff0000, v223
	s_waitcnt vmcnt(5)
	v_lshlrev_b32_e32 v142, 16, v224
	v_and_b32_e32 v143, 0xffff0000, v224
	v_lshlrev_b32_e32 v144, 16, v225
	v_and_b32_e32 v145, 0xffff0000, v225
	v_lshlrev_b32_e32 v146, 16, v226
	v_and_b32_e32 v147, 0xffff0000, v226
	v_lshlrev_b32_e32 v148, 16, v227
	v_and_b32_e32 v149, 0xffff0000, v227
	s_waitcnt vmcnt(4)
	v_lshlrev_b32_e32 v150, 16, v228
	v_and_b32_e32 v151, 0xffff0000, v228
	v_lshlrev_b32_e32 v152, 16, v229
	v_and_b32_e32 v153, 0xffff0000, v229
	v_lshlrev_b32_e32 v154, 16, v230
	v_and_b32_e32 v155, 0xffff0000, v230
	v_lshlrev_b32_e32 v156, 16, v231
	v_and_b32_e32 v157, 0xffff0000, v231
	s_waitcnt vmcnt(3)
; #define GAS __attribute__((address_space(1)))
; __device__ __forceinline__ void prep_seg(const bf16_t* QK, const float* cw, const size_t rowbase, const int t0, const int h, const int seg, const int lane, float (&o)[8][8]) {
;     ...
;     for (int rr = 0; rr < 11; ++rr) { const int t = t0 + 8 * rg + rr - 3; float x[8];
;         if (t >= 0) unpack8(*(const GAS v4u*)(QK + (rowbase + t) * CONVD + col), x); else {
; #pragma unroll
;             for (int e = 0; e < 8; ++e) x[e] = 0.f; }
; #pragma unroll
;         for (int j = 0; j < 4; ++j) { const int r = rr - j;
;             if (r >= 0 && r < 8) {
; #pragma unroll
;                 for (int e = 0; e < 8; ++e) o[r][e] += wt[j][e] * x[e]; } } }
	v_lshlrev_b32_e32 v126, 16, v232
	v_and_b32_e32 v127, 0xffff0000, v232
	v_lshlrev_b32_e32 v128, 16, v233
	v_and_b32_e32 v129, 0xffff0000, v233
	v_lshlrev_b32_e32 v132, 16, v234
	v_and_b32_e32 v133, 0xffff0000, v234
	v_lshlrev_b32_e32 v136, 16, v235
	v_and_b32_e32 v137, 0xffff0000, v235
	s_waitcnt vmcnt(2)
	v_lshlrev_b32_e32 v112, 16, v236
	v_and_b32_e32 v113, 0xffff0000, v236
	v_lshlrev_b32_e32 v114, 16, v237
	v_and_b32_e32 v115, 0xffff0000, v237
	v_lshlrev_b32_e32 v116, 16, v238
	v_and_b32_e32 v117, 0xffff0000, v238
	v_lshlrev_b32_e32 v120, 16, v239
	v_and_b32_e32 v121, 0xffff0000, v239
	s_waitcnt vmcnt(1)
	v_lshlrev_b32_e32 v50, 16, v240
	v_and_b32_e32 v51, 0xffff0000, v240
	v_lshlrev_b32_e32 v52, 16, v241
	v_and_b32_e32 v53, 0xffff0000, v241
	v_lshlrev_b32_e32 v56, 16, v242
	v_and_b32_e32 v57, 0xffff0000, v242
	v_lshlrev_b32_e32 v58, 16, v243
	v_and_b32_e32 v59, 0xffff0000, v243
	s_waitcnt vmcnt(0)
	v_lshlrev_b32_e32 v36, 16, v244
	v_and_b32_e32 v37, 0xffff0000, v244
	v_lshlrev_b32_e32 v38, 16, v245
	v_and_b32_e32 v39, 0xffff0000, v245
	v_lshlrev_b32_e32 v40, 16, v246
	v_and_b32_e32 v41, 0xffff0000, v246
	v_lshlrev_b32_e32 v42, 16, v247
	v_and_b32_e32 v43, 0xffff0000, v247
	s_waitcnt vmcnt(6)
	v_pk_fma_f32 v[44:45], v[20:21], v[150:151], 0 op_sel_hi:[1,1,0]
	v_pk_fma_f32 v[160:161], v[20:21], v[126:127], 0 op_sel_hi:[1,1,0]
	v_pk_fma_f32 v[46:47], v[22:23], v[152:153], 0 op_sel_hi:[1,1,0]
	v_pk_fma_f32 v[48:49], v[8:9], v[154:155], 0 op_sel_hi:[1,1,0]
	v_pk_fma_f32 v[162:163], v[22:23], v[128:129], 0 op_sel_hi:[1,1,0]
	v_pk_fma_f32 v[164:165], v[8:9], v[132:133], 0 op_sel_hi:[1,1,0]
	s_waitcnt vmcnt(5)
	v_pk_fma_f32 v[44:45], v[16:17], v[126:127], v[44:45]
	v_pk_fma_f32 v[160:161], v[16:17], v[112:113], v[160:161]
	v_pk_fma_f32 v[54:55], v[10:11], v[156:157], 0 op_sel_hi:[1,1,0]
	v_pk_fma_f32 v[166:167], v[10:11], v[136:137], 0 op_sel_hi:[1,1,0]
	v_pk_fma_f32 v[46:47], v[18:19], v[128:129], v[46:47]
	s_waitcnt vmcnt(4)
	v_pk_fma_f32 v[48:49], v[12:13], v[132:133], v[48:49]
	v_pk_fma_f32 v[162:163], v[18:19], v[114:115], v[162:163]
	v_pk_fma_f32 v[164:165], v[12:13], v[116:117], v[164:165]
	s_waitcnt vmcnt(3)
	v_pk_fma_f32 v[168:169], v[28:29], v[112:113], v[44:45]
	v_pk_fma_f32 v[44:45], v[28:29], v[50:51], v[160:161]
	v_pk_fma_f32 v[160:161], v[20:21], v[142:143], 0 op_sel_hi:[1,1,0]
	v_pk_fma_f32 v[54:55], v[14:15], v[136:137], v[54:55]
	v_pk_fma_f32 v[166:167], v[14:15], v[120:121], v[166:167]
	v_pk_fma_f32 v[170:171], v[30:31], v[114:115], v[46:47]
	s_waitcnt vmcnt(2)
	v_pk_fma_f32 v[174:175], v[24:25], v[116:117], v[48:49]
	v_pk_fma_f32 v[46:47], v[30:31], v[52:53], v[162:163]
	v_pk_fma_f32 v[48:49], v[24:25], v[56:57], v[164:165]
	v_pk_fma_f32 v[162:163], v[22:23], v[144:145], 0 op_sel_hi:[1,1,0]
	v_pk_fma_f32 v[164:165], v[8:9], v[146:147], 0 op_sel_hi:[1,1,0]
	v_pk_fma_f32 v[160:161], v[16:17], v[150:151], v[160:161]
	v_pk_fma_f32 v[176:177], v[26:27], v[120:121], v[54:55]
	v_pk_fma_f32 v[54:55], v[26:27], v[58:59], v[166:167]
	v_pk_fma_f32 v[166:167], v[10:11], v[148:149], 0 op_sel_hi:[1,1,0]
	v_pk_fma_f32 v[162:163], v[18:19], v[152:153], v[162:163]
	v_pk_fma_f32 v[164:165], v[12:13], v[154:155], v[164:165]
	v_pk_fma_f32 v[160:161], v[28:29], v[126:127], v[160:161]
	v_pk_fma_f32 v[166:167], v[14:15], v[156:157], v[166:167]
	v_pk_fma_f32 v[162:163], v[30:31], v[128:129], v[162:163]
	v_pk_fma_f32 v[164:165], v[24:25], v[132:133], v[164:165]
	s_waitcnt vmcnt(1)
	v_pk_fma_f32 v[112:113], v[0:1], v[112:113], v[160:161]
	v_pk_fma_f32 v[160:161], v[20:21], v[130:131], 0 op_sel_hi:[1,1,0]
	v_pk_fma_f32 v[166:167], v[26:27], v[136:137], v[166:167]
	v_pk_fma_f32 v[114:115], v[2:3], v[114:115], v[162:163]
	s_waitcnt vmcnt(0)
	v_pk_fma_f32 v[116:117], v[4:5], v[116:117], v[164:165]
	v_pk_fma_f32 v[162:163], v[22:23], v[134:135], 0 op_sel_hi:[1,1,0]
	v_pk_fma_f32 v[164:165], v[8:9], v[138:139], 0 op_sel_hi:[1,1,0]
	v_pk_fma_f32 v[160:161], v[16:17], v[142:143], v[160:161]
	v_pk_fma_f32 v[120:121], v[6:7], v[120:121], v[166:167]
	v_pk_fma_f32 v[166:167], v[10:11], v[140:141], 0 op_sel_hi:[1,1,0]
	v_pk_fma_f32 v[162:163], v[18:19], v[144:145], v[162:163]
	v_pk_fma_f32 v[164:165], v[12:13], v[146:147], v[164:165]
	v_pk_fma_f32 v[160:161], v[28:29], v[150:151], v[160:161]
	v_pk_fma_f32 v[166:167], v[14:15], v[148:149], v[166:167]
	v_pk_fma_f32 v[162:163], v[30:31], v[152:153], v[162:163]
	v_pk_fma_f32 v[164:165], v[24:25], v[154:155], v[164:165]
	v_pk_fma_f32 v[126:127], v[0:1], v[126:127], v[160:161]
	v_pk_fma_f32 v[160:161], v[20:21], v[102:103], 0 op_sel_hi:[1,1,0]
	v_pk_fma_f32 v[166:167], v[26:27], v[156:157], v[166:167]
	v_pk_fma_f32 v[128:129], v[2:3], v[128:129], v[162:163]
	v_pk_fma_f32 v[132:133], v[4:5], v[132:133], v[164:165]
	v_pk_fma_f32 v[162:163], v[22:23], v[122:123], 0 op_sel_hi:[1,1,0]
	v_pk_fma_f32 v[164:165], v[8:9], v[124:125], 0 op_sel_hi:[1,1,0]
	v_pk_fma_f32 v[160:161], v[16:17], v[130:131], v[160:161]
	v_pk_fma_f32 v[136:137], v[6:7], v[136:137], v[166:167]
	v_pk_fma_f32 v[166:167], v[10:11], v[118:119], 0 op_sel_hi:[1,1,0]
	v_pk_fma_f32 v[162:163], v[18:19], v[134:135], v[162:163]
	v_pk_fma_f32 v[164:165], v[12:13], v[138:139], v[164:165]
	v_pk_fma_f32 v[160:161], v[28:29], v[142:143], v[160:161]
	v_pk_fma_f32 v[166:167], v[14:15], v[140:141], v[166:167]
	v_pk_fma_f32 v[162:163], v[30:31], v[144:145], v[162:163]
	v_pk_fma_f32 v[164:165], v[24:25], v[146:147], v[164:165]
	v_pk_fma_f32 v[150:151], v[0:1], v[150:151], v[160:161]
	v_pk_fma_f32 v[160:161], v[20:21], v[104:105], 0 op_sel_hi:[1,1,0]
	v_pk_fma_f32 v[166:167], v[26:27], v[148:149], v[166:167]
	v_pk_fma_f32 v[152:153], v[2:3], v[152:153], v[162:163]
; __device__ __forceinline__ float silu_f(float x) { return x * __builtin_amdgcn_rcpf(1.f + __builtin_amdgcn_exp2f(-1.4426950408889634f * x)); }
; __device__ __forceinline__ void prep_seg(const bf16_t* QK, const float* cw, const size_t rowbase, const int t0, const int h, const int seg, const int lane, float (&o)[8][8]) {
;     ...
; #pragma unroll
;         for (int j = 0; j < 4; ++j) { const int r = rr - j;
;             if (r >= 0 && r < 8) {
; #pragma unroll
;                 for (int e = 0; e < 8; ++e) o[r][e] += wt[j][e] * x[e]; } } }
; #pragma unroll
;     for (int r = 0; r < 8; ++r) { float ss = 0.f;
; #pragma unroll
;         for (int e = 0; e < 8; ++e) { o[r][e] = silu_f(o[r][e]); ss += o[r][e] * o[r][e]; }
;         if (seg < 2) { ss += __shfl_xor(ss, 1); ss += __shfl_xor(ss, 2); ss += __shfl_xor(ss, 4); const float sc = rsqrtf(ss + 1e-6f) * (seg == 0 ? 0.125f : 1.f);
; #pragma unroll
;             for (int e = 0; e < 8; ++e) o[r][e] *= sc; } }
	v_pk_fma_f32 v[154:155], v[4:5], v[154:155], v[164:165]
	v_pk_fma_f32 v[162:163], v[22:23], v[106:107], 0 op_sel_hi:[1,1,0]
	v_pk_fma_f32 v[164:165], v[8:9], v[108:109], 0 op_sel_hi:[1,1,0]
	v_pk_fma_f32 v[160:161], v[16:17], v[102:103], v[160:161]
	v_pk_fma_f32 v[156:157], v[6:7], v[156:157], v[166:167]
	v_pk_fma_f32 v[166:167], v[10:11], v[110:111], 0 op_sel_hi:[1,1,0]
	v_pk_fma_f32 v[162:163], v[18:19], v[122:123], v[162:163]
	v_pk_fma_f32 v[164:165], v[12:13], v[124:125], v[164:165]
	v_pk_fma_f32 v[160:161], v[28:29], v[130:131], v[160:161]
	v_pk_fma_f32 v[166:167], v[14:15], v[118:119], v[166:167]
	v_pk_fma_f32 v[162:163], v[30:31], v[134:135], v[162:163]
	v_pk_fma_f32 v[164:165], v[24:25], v[138:139], v[164:165]
	v_pk_fma_f32 v[142:143], v[0:1], v[142:143], v[160:161]
	v_pk_fma_f32 v[160:161], v[20:21], v[60:61], 0 op_sel_hi:[1,1,0]
	v_pk_fma_f32 v[20:21], v[20:21], v[62:63], 0 op_sel_hi:[1,1,0]
	v_pk_fma_f32 v[166:167], v[26:27], v[140:141], v[166:167]
	v_pk_fma_f32 v[144:145], v[2:3], v[144:145], v[162:163]
	v_pk_fma_f32 v[146:147], v[4:5], v[146:147], v[164:165]
	v_pk_fma_f32 v[162:163], v[22:23], v[96:97], 0 op_sel_hi:[1,1,0]
	v_pk_fma_f32 v[164:165], v[8:9], v[98:99], 0 op_sel_hi:[1,1,0]
	v_pk_fma_f32 v[160:161], v[16:17], v[104:105], v[160:161]
	v_pk_fma_f32 v[22:23], v[22:23], v[90:91], 0 op_sel_hi:[1,1,0]
	v_pk_fma_f32 v[8:9], v[8:9], v[92:93], 0 op_sel_hi:[1,1,0]
	v_pk_fma_f32 v[16:17], v[16:17], v[60:61], v[20:21]
	v_pk_fma_f32 v[148:149], v[6:7], v[148:149], v[166:167]
	v_pk_fma_f32 v[166:167], v[10:11], v[100:101], 0 op_sel_hi:[1,1,0]
	v_pk_fma_f32 v[162:163], v[18:19], v[106:107], v[162:163]
	v_pk_fma_f32 v[164:165], v[12:13], v[108:109], v[164:165]
	v_pk_fma_f32 v[10:11], v[10:11], v[94:95], 0 op_sel_hi:[1,1,0]
	v_pk_fma_f32 v[18:19], v[18:19], v[96:97], v[22:23]
	v_pk_fma_f32 v[8:9], v[12:13], v[98:99], v[8:9]
	v_pk_fma_f32 v[12:13], v[28:29], v[104:105], v[16:17]
	v_pk_fma_f32 v[166:167], v[14:15], v[110:111], v[166:167]
	v_pk_fma_f32 v[10:11], v[14:15], v[100:101], v[10:11]
	v_pk_fma_f32 v[14:15], v[30:31], v[106:107], v[18:19]
	v_pk_fma_f32 v[8:9], v[24:25], v[108:109], v[8:9]
	v_pk_fma_f32 v[16:17], v[0:1], v[102:103], v[12:13]
	v_pk_fma_f32 v[12:13], v[2:3], v[122:123], v[14:15]
	v_pk_fma_f32 v[14:15], v[4:5], v[124:125], v[8:9]
	v_mul_f32_e32 v8, 0xbfb8aa3b, v16
	v_exp_f32_e32 v18, v8
	v_mul_f32_e32 v8, 0xbfb8aa3b, v17
	v_exp_f32_e32 v19, v8
	v_pk_fma_f32 v[10:11], v[26:27], v[110:111], v[10:11]
	v_pk_fma_f32 v[160:161], v[28:29], v[102:103], v[160:161]
	v_pk_fma_f32 v[8:9], v[6:7], v[118:119], v[10:11]
	v_add_f32_e32 v10, 1.0, v18
	v_mul_f32_e32 v11, 0xbfb8aa3b, v12
	v_rcp_f32_e32 v18, v10
	v_add_f32_e32 v10, 1.0, v19
	v_exp_f32_e32 v11, v11
	v_mul_f32_e32 v19, 0xbfb8aa3b, v13
	v_exp_f32_e32 v21, v19
	v_rcp_f32_e32 v19, v10
	v_add_f32_e32 v10, 1.0, v11
	v_rcp_f32_e32 v20, v10
	v_add_f32_e32 v10, 1.0, v21
	v_mul_f32_e32 v11, 0xbfb8aa3b, v14
	v_mul_f32_e32 v21, 0xbfb8aa3b, v15
	v_exp_f32_e32 v11, v11
	v_exp_f32_e32 v22, v21
	v_rcp_f32_e32 v21, v10
	v_pk_fma_f32 v[130:131], v[0:1], v[130:131], v[160:161]
	v_add_f32_e32 v10, 1.0, v11
	v_add_f32_e32 v11, 1.0, v22
	v_rcp_f32_e32 v10, v10
	v_rcp_f32_e32 v11, v11
	v_pk_fma_f32 v[162:163], v[30:31], v[122:123], v[162:163]
	v_pk_fma_f32 v[164:165], v[24:25], v[124:125], v[164:165]
	v_pk_fma_f32 v[134:135], v[2:3], v[134:135], v[162:163]
	v_pk_mul_f32 v[10:11], v[14:15], v[10:11]
	v_pk_mul_f32 v[14:15], v[16:17], v[18:19]
	v_mul_f32_e32 v16, 0xbfb8aa3b, v130
	v_exp_f32_e32 v18, v16
	v_mul_f32_e32 v16, 0xbfb8aa3b, v131
	v_exp_f32_e32 v19, v16
	v_pk_fma_f32 v[138:139], v[4:5], v[138:139], v[164:165]
	v_add_f32_e32 v18, 1.0, v18
	v_rcp_f32_e32 v28, v18
	v_add_f32_e32 v18, 1.0, v19
	v_rcp_f32_e32 v29, v18
	v_mul_f32_e32 v18, 0xbfb8aa3b, v134
	v_pk_mul_f32 v[12:13], v[12:13], v[20:21]
	v_exp_f32_e32 v18, v18
	v_mul_f32_e32 v20, 0xbfb8aa3b, v138
	v_exp_f32_e32 v21, v20
	v_pk_fma_f32 v[166:167], v[26:27], v[118:119], v[166:167]
	v_mul_f32_e32 v19, 0xbfb8aa3b, v135
	v_pk_fma_f32 v[140:141], v[6:7], v[140:141], v[166:167]
	v_exp_f32_e32 v19, v19
	v_add_f32_e32 v18, 1.0, v18
	v_rcp_f32_e32 v20, v18
	v_add_f32_e32 v18, 1.0, v21
	v_mul_f32_e32 v21, 0xbfb8aa3b, v140
	v_exp_f32_e32 v21, v21
	v_mul_f32_e32 v30, 0xbfb8aa3b, v141
	v_exp_f32_e32 v31, v30
	v_add_f32_e32 v60, 1.0, v19
	v_mul_f32_e32 v19, 0xbfb8aa3b, v139
	v_exp_f32_e32 v19, v19
	v_mul_f32_e32 v22, 0xbfb8aa3b, v8
	v_mul_f32_e32 v23, 0xbfb8aa3b, v9
	v_add_f32_e32 v21, 1.0, v21
	v_exp_f32_e32 v22, v22
	v_exp_f32_e32 v23, v23
	v_rcp_f32_e32 v30, v21
	v_add_f32_e32 v21, 1.0, v31
	v_rcp_f32_e32 v31, v21
	v_rcp_f32_e32 v21, v60
	v_add_f32_e32 v19, 1.0, v19
	v_rcp_f32_e32 v18, v18
	v_rcp_f32_e32 v19, v19
	v_add_f32_e32 v22, 1.0, v22
	v_add_f32_e32 v23, 1.0, v23
	v_pk_mul_f32 v[62:63], v[130:131], v[28:29]
	v_rcp_f32_e32 v22, v22
	v_rcp_f32_e32 v23, v23
	v_xor_b32_e32 v24, 1, v202
	v_add_u32_e32 v64, 64, v203
	v_pk_mul_f32 v[16:17], v[14:15], v[14:15]
	v_pk_mul_f32 v[20:21], v[134:135], v[20:21]
	v_pk_mul_f32 v[28:29], v[62:63], v[62:63]
	v_cmp_lt_i32_e32 vcc, v24, v64
	v_pk_mul_f32 v[26:27], v[12:13], v[12:13]
	v_pk_mul_f32 v[92:93], v[20:21], v[20:21]
	v_mov_b32_e32 v94, v28
	v_mov_b32_e32 v95, v16
	v_mov_b32_e32 v16, v29
	v_cndmask_b32_e32 v24, v202, v24, vcc
	v_pk_mul_f32 v[18:19], v[138:139], v[18:19]
	v_pk_add_f32 v[16:17], v[94:95], v[16:17]
	v_mov_b32_e32 v28, v92
	v_mov_b32_e32 v29, v26
	v_pk_fma_f32 v[56:57], v[4:5], v[56:57], v[174:175]
	v_lshlrev_b32_e32 v174, 2, v24
	v_pk_mul_f32 v[24:25], v[10:11], v[10:11]
	v_pk_mul_f32 v[90:91], v[18:19], v[18:19]
	v_pk_add_f32 v[16:17], v[28:29], v[16:17]
	v_mov_b32_e32 v26, v93
	v_pk_mul_f32 v[8:9], v[8:9], v[22:23]
	v_pk_mul_f32 v[60:61], v[140:141], v[30:31]
	v_pk_add_f32 v[16:17], v[26:27], v[16:17]
	v_mov_b32_e32 v26, v90
	v_mov_b32_e32 v27, v24
	v_pk_mul_f32 v[22:23], v[8:9], v[8:9]
	v_pk_mul_f32 v[30:31], v[60:61], v[60:61]
	v_pk_add_f32 v[16:17], v[26:27], v[16:17]
	v_mov_b32_e32 v24, v91
	v_pk_add_f32 v[16:17], v[24:25], v[16:17]
	v_mov_b32_e32 v24, v30
	v_mov_b32_e32 v25, v22
	v_pk_add_f32 v[16:17], v[24:25], v[16:17]
	v_mov_b32_e32 v22, v31
	v_pk_add_f32 v[16:17], v[22:23], v[16:17]
	ds_bpermute_b32 v23, v174, v17
	ds_bpermute_b32 v22, v174, v16
	v_xor_b32_e32 v24, 2, v202
	v_cmp_lt_i32_e32 vcc, v24, v64
	v_pk_fma_f32 v[58:59], v[6:7], v[58:59], v[176:177]
	v_mul_f32_e32 v71, 0xbfb8aa3b, v154
	v_cndmask_b32_e32 v24, v202, v24, vcc
	v_lshlrev_b32_e32 v175, 2, v24
	s_waitcnt lgkmcnt(0)
; __device__ __forceinline__ float silu_f(float x) { return x * __builtin_amdgcn_rcpf(1.f + __builtin_amdgcn_exp2f(-1.4426950408889634f * x)); }
; __device__ __forceinline__ void prep_seg(const bf16_t* QK, const float* cw, const size_t rowbase, const int t0, const int h, const int seg, const int lane, float (&o)[8][8]) {
;     ...
;     for (int r = 0; r < 8; ++r) { float ss = 0.f;
; #pragma unroll
;         for (int e = 0; e < 8; ++e) { o[r][e] = silu_f(o[r][e]); ss += o[r][e] * o[r][e]; }
;         if (seg < 2) { ss += __shfl_xor(ss, 1); ss += __shfl_xor(ss, 2); ss += __shfl_xor(ss, 4); const float sc = rsqrtf(ss + 1e-6f) * (seg == 0 ? 0.125f : 1.f);
; #pragma unroll
;             for (int e = 0; e < 8; ++e) o[r][e] *= sc; } }
	v_pk_add_f32 v[16:17], v[16:17], v[22:23]
	ds_bpermute_b32 v23, v175, v17
	ds_bpermute_b32 v22, v175, v16
	v_xor_b32_e32 v24, 4, v202
	v_cmp_lt_i32_e32 vcc, v24, v64
	v_exp_f32_e32 v71, v71
	v_mul_f32_e32 v25, 0xbfb8aa3b, v145
	v_cndmask_b32_e32 v24, v202, v24, vcc
	v_lshlrev_b32_e32 v176, 2, v24
	s_waitcnt lgkmcnt(0)
	v_pk_add_f32 v[16:17], v[16:17], v[22:23]
	ds_bpermute_b32 v23, v176, v17
	ds_bpermute_b32 v22, v176, v16
	v_mul_f32_e32 v24, 0xbfb8aa3b, v144
	v_exp_f32_e32 v24, v24
	v_exp_f32_e32 v25, v25
	v_mul_f32_e32 v26, 0xbfb8aa3b, v146
	s_waitcnt lgkmcnt(0)
	v_pk_add_f32 v[16:17], v[16:17], v[22:23]
	v_mul_f32_e32 v23, 0xbfb8aa3b, v143
	v_pk_add_f32 v[16:17], v[16:17], s[68:69] op_sel_hi:[1,0]
	v_exp_f32_e32 v23, v23
	v_mul_f32_e32 v22, 0x4b800000, v17
	v_cmp_gt_f32_e32 vcc, s73, v17
	v_mul_f32_e32 v27, 0xbfb8aa3b, v147
	v_add_f32_e32 v23, 1.0, v23
	v_cndmask_b32_e32 v17, v17, v22, vcc
	v_mul_f32_e32 v22, 0xbfb8aa3b, v142
	v_exp_f32_e32 v22, v22
	v_rcp_f32_e32 v23, v23
	v_exp_f32_e32 v26, v26
	v_exp_f32_e32 v27, v27
	v_add_f32_e32 v22, 1.0, v22
	v_rcp_f32_e32 v22, v22
	v_mul_f32_e32 v28, 0xbfb8aa3b, v148
	v_mul_f32_e32 v29, 0xbfb8aa3b, v149
	v_mul_f32_e32 v73, 0xbfb8aa3b, v157
	v_pk_mul_f32 v[94:95], v[142:143], v[22:23]
	v_mul_f32_e32 v22, 0xbfb8aa3b, v150
	v_exp_f32_e32 v67, v22
	v_mul_f32_e32 v22, 0xbfb8aa3b, v151
	v_exp_f32_e32 v69, v22
	v_add_f32_e32 v24, 1.0, v24
	v_add_f32_e32 v67, 1.0, v67
	v_rcp_f32_e32 v96, v67
	v_add_f32_e32 v67, 1.0, v69
	v_rcp_f32_e32 v97, v67
	v_mul_f32_e32 v67, 0xbfb8aa3b, v152
	v_exp_f32_e32 v67, v67
	v_mul_f32_e32 v69, 0xbfb8aa3b, v153
	v_exp_f32_e32 v69, v69
	v_add_f32_e32 v25, 1.0, v25
	v_add_f32_e32 v67, 1.0, v67
	v_rcp_f32_e32 v98, v67
	v_add_f32_e32 v67, 1.0, v69
	v_add_f32_e32 v69, 1.0, v71
	v_rcp_f32_e32 v100, v69
	v_mul_f32_e32 v69, 0xbfb8aa3b, v155
	v_mul_f32_e32 v71, 0xbfb8aa3b, v156
	v_exp_f32_e32 v69, v69
	v_exp_f32_e32 v71, v71
	v_exp_f32_e32 v28, v28
	v_exp_f32_e32 v29, v29
	v_exp_f32_e32 v73, v73
	v_rcp_f32_e32 v24, v24
	v_rcp_f32_e32 v25, v25
	v_rcp_f32_e32 v99, v67
	v_add_f32_e32 v26, 1.0, v26
	v_add_f32_e32 v27, 1.0, v27
	v_add_f32_e32 v69, 1.0, v69
	v_rcp_f32_e32 v26, v26
	v_rcp_f32_e32 v27, v27
	v_add_f32_e32 v71, 1.0, v71
	v_rcp_f32_e32 v101, v69
	v_add_f32_e32 v28, 1.0, v28
	v_add_f32_e32 v29, 1.0, v29
	v_rcp_f32_e32 v102, v71
	v_add_f32_e32 v71, 1.0, v73
	v_pk_mul_f32 v[124:125], v[150:151], v[96:97]
	v_rcp_f32_e32 v28, v28
	v_rcp_f32_e32 v29, v29
	v_pk_mul_f32 v[92:93], v[144:145], v[24:25]
	v_pk_mul_f32 v[22:23], v[94:95], v[94:95]
	v_rcp_f32_e32 v103, v71
	v_pk_mul_f32 v[122:123], v[152:153], v[98:99]
	v_pk_mul_f32 v[96:97], v[124:125], v[124:125]
	v_pk_mul_f32 v[24:25], v[92:93], v[92:93]
	v_pk_mul_f32 v[98:99], v[122:123], v[122:123]
	v_mov_b32_e32 v104, v96
	v_mov_b32_e32 v105, v22
	v_mov_b32_e32 v22, v97
	v_pk_mul_f32 v[30:31], v[146:147], v[26:27]
	v_pk_mul_f32 v[118:119], v[154:155], v[100:101]
	v_pk_add_f32 v[22:23], v[104:105], v[22:23]
	v_mov_b32_e32 v96, v98
	v_mov_b32_e32 v97, v24
	v_pk_mul_f32 v[26:27], v[30:31], v[30:31]
	v_pk_mul_f32 v[100:101], v[118:119], v[118:119]
	v_pk_add_f32 v[22:23], v[96:97], v[22:23]
	v_mov_b32_e32 v24, v99
	v_pk_mul_f32 v[28:29], v[148:149], v[28:29]
	v_pk_mul_f32 v[110:111], v[156:157], v[102:103]
	v_pk_add_f32 v[22:23], v[24:25], v[22:23]
	v_mov_b32_e32 v24, v100
	v_mov_b32_e32 v25, v26
	v_pk_mul_f32 v[90:91], v[28:29], v[28:29]
	v_pk_mul_f32 v[102:103], v[110:111], v[110:111]
	v_pk_add_f32 v[22:23], v[24:25], v[22:23]
	v_mov_b32_e32 v26, v101
	v_pk_add_f32 v[22:23], v[26:27], v[22:23]
	v_mov_b32_e32 v24, v102
	v_mov_b32_e32 v25, v90
	v_pk_add_f32 v[22:23], v[24:25], v[22:23]
	v_mov_b32_e32 v90, v103
	v_rsq_f32_e32 v17, v17
	v_pk_add_f32 v[90:91], v[90:91], v[22:23]
	ds_bpermute_b32 v97, v174, v91
	ds_bpermute_b32 v96, v174, v90
	v_mul_f32_e32 v64, 0x45800000, v17
	v_cndmask_b32_e32 v64, v17, v64, vcc
	v_pk_mul_f32 v[22:23], v[10:11], v[64:65] op_sel_hi:[1,0]
	v_pk_mul_f32 v[24:25], v[12:13], v[64:65] op_sel_hi:[1,0]
	s_waitcnt lgkmcnt(0)
	v_pk_add_f32 v[10:11], v[90:91], v[96:97]
	ds_bpermute_b32 v13, v175, v11
	ds_bpermute_b32 v12, v175, v10
	v_pk_mul_f32 v[26:27], v[14:15], v[64:65] op_sel_hi:[1,0]
	v_mul_f32_e32 v14, 0x4b800000, v16
	v_cmp_gt_f32_e32 vcc, s73, v16
	v_mul_f32_e32 v67, 0xbfb8aa3b, v137
	s_waitcnt lgkmcnt(0)
	v_pk_add_f32 v[10:11], v[10:11], v[12:13]
	v_cndmask_b32_e32 v14, v16, v14, vcc
	v_rsq_f32_e32 v14, v14
	ds_bpermute_b32 v13, v176, v11
	ds_bpermute_b32 v12, v176, v10
	v_pk_mul_f32 v[16:17], v[8:9], v[64:65] op_sel_hi:[1,0]
	v_mul_f32_e32 v8, 0x45800000, v14
	v_cndmask_b32_e32 v8, v14, v8, vcc
	v_pk_mul_f32 v[14:15], v[62:63], v[8:9] op_sel_hi:[1,0]
	s_waitcnt lgkmcnt(0)
; __device__ __forceinline__ float silu_f(float x) { return x * __builtin_amdgcn_rcpf(1.f + __builtin_amdgcn_exp2f(-1.4426950408889634f * x)); }
; __device__ __forceinline__ void prep_seg(const bf16_t* QK, const float* cw, const size_t rowbase, const int t0, const int h, const int seg, const int lane, float (&o)[8][8]) {
;     ...
;     for (int r = 0; r < 8; ++r) { float ss = 0.f;
; #pragma unroll
;         for (int e = 0; e < 8; ++e) { o[r][e] = silu_f(o[r][e]); ss += o[r][e] * o[r][e]; }
;         if (seg < 2) { ss += __shfl_xor(ss, 1); ss += __shfl_xor(ss, 2); ss += __shfl_xor(ss, 4); const float sc = rsqrtf(ss + 1e-6f) * (seg == 0 ? 0.125f : 1.f);
; #pragma unroll
;             for (int e = 0; e < 8; ++e) o[r][e] *= sc; } }
	v_pk_add_f32 v[10:11], v[10:11], v[12:13]
	v_mul_f32_e32 v12, 0xbfb8aa3b, v126
	v_pk_add_f32 v[62:63], v[10:11], s[68:69] op_sel_hi:[1,0]
	v_mul_f32_e32 v64, 0xbfb8aa3b, v132
	v_mul_f32_e32 v9, 0x4b800000, v63
	v_cmp_gt_f32_e32 vcc, s73, v63
	v_exp_f32_e32 v64, v64
	v_exp_f32_e32 v67, v67
	v_cndmask_b32_e32 v9, v63, v9, vcc
	v_rsq_f32_e32 v9, v9
	v_pk_fma_f32 v[50:51], v[0:1], v[50:51], v[168:169]
	v_pk_fma_f32 v[52:53], v[2:3], v[52:53], v[170:171]
	v_mul_f32_e32 v69, 0xbfb8aa3b, v51
	v_pk_mul_f32 v[20:21], v[20:21], v[8:9] op_sel_hi:[1,0]
	v_pk_mul_f32 v[18:19], v[18:19], v[8:9] op_sel_hi:[1,0]
	v_pk_mul_f32 v[10:11], v[60:61], v[8:9] op_sel_hi:[1,0]
	v_mul_f32_e32 v8, 0x45800000, v9
	v_cndmask_b32_e32 v60, v9, v8, vcc
	v_pk_mul_f32 v[8:9], v[94:95], v[60:61] op_sel_hi:[1,0]
	v_exp_f32_e32 v61, v12
	v_mul_f32_e32 v12, 0xbfb8aa3b, v127
	v_exp_f32_e32 v63, v12
	v_cmp_gt_f32_e32 vcc, s73, v62
	v_pk_mul_f32 v[12:13], v[92:93], v[60:61] op_sel_hi:[1,0]
	v_add_f32_e32 v61, 1.0, v61
	v_rcp_f32_e32 v90, v61
	v_add_f32_e32 v61, 1.0, v63
	v_rcp_f32_e32 v91, v61
	v_mul_f32_e32 v61, 0xbfb8aa3b, v128
	v_exp_f32_e32 v61, v61
	v_mul_f32_e32 v63, 0xbfb8aa3b, v129
	v_exp_f32_e32 v63, v63
	v_pk_mul_f32 v[100:101], v[126:127], v[90:91]
	v_add_f32_e32 v61, 1.0, v61
	v_rcp_f32_e32 v92, v61
	v_add_f32_e32 v61, 1.0, v63
	v_add_f32_e32 v63, 1.0, v64
	v_rcp_f32_e32 v96, v63
	v_mul_f32_e32 v63, 0xbfb8aa3b, v133
	v_exp_f32_e32 v63, v63
	v_rcp_f32_e32 v93, v61
	v_mul_f32_e32 v61, 0xbfb8aa3b, v112
	v_mul_f32_e32 v64, 0xbfb8aa3b, v136
	v_add_f32_e32 v63, 1.0, v63
	v_rcp_f32_e32 v97, v63
	v_exp_f32_e32 v61, v61
	v_mul_f32_e32 v63, 0xbfb8aa3b, v113
	v_exp_f32_e32 v64, v64
	v_exp_f32_e32 v63, v63
	v_add_f32_e32 v61, 1.0, v61
	v_rcp_f32_e32 v108, v61
	v_add_f32_e32 v64, 1.0, v64
	v_add_f32_e32 v61, 1.0, v63
	v_rcp_f32_e32 v94, v64
	v_add_f32_e32 v64, 1.0, v67
	v_rcp_f32_e32 v109, v61
	v_mul_f32_e32 v61, 0xbfb8aa3b, v114
	v_rcp_f32_e32 v95, v64
	v_exp_f32_e32 v61, v61
	v_mul_f32_e32 v63, 0xbfb8aa3b, v115
	v_mul_f32_e32 v64, 0xbfb8aa3b, v116
	v_exp_f32_e32 v63, v63
	v_exp_f32_e32 v64, v64
	v_add_f32_e32 v61, 1.0, v61
	v_rcp_f32_e32 v106, v61
	v_add_f32_e32 v61, 1.0, v63
	v_add_f32_e32 v63, 1.0, v64
	v_rcp_f32_e32 v104, v63
	v_mul_f32_e32 v63, 0xbfb8aa3b, v117
	v_mul_f32_e32 v64, 0xbfb8aa3b, v120
	v_exp_f32_e32 v63, v63
	v_exp_f32_e32 v64, v64
	v_mul_f32_e32 v67, 0xbfb8aa3b, v121
	v_exp_f32_e32 v67, v67
	v_rcp_f32_e32 v107, v61
	v_add_f32_e32 v63, 1.0, v63
	v_add_f32_e32 v64, 1.0, v64
	v_rcp_f32_e32 v105, v63
	v_rcp_f32_e32 v102, v64
	v_add_f32_e32 v64, 1.0, v67
	v_pk_mul_f32 v[108:109], v[112:113], v[108:109]
	v_pk_mul_f32 v[98:99], v[128:129], v[92:93]
	v_pk_mul_f32 v[90:91], v[100:101], v[100:101]
	v_rcp_f32_e32 v103, v64
	v_pk_mul_f32 v[106:107], v[114:115], v[106:107]
	v_pk_mul_f32 v[112:113], v[108:109], v[108:109]
	v_pk_mul_f32 v[92:93], v[98:99], v[98:99]
	v_pk_mul_f32 v[114:115], v[106:107], v[106:107]
	v_mov_b32_e32 v126, v112
	v_mov_b32_e32 v127, v90
	v_mov_b32_e32 v90, v113
	v_pk_mul_f32 v[96:97], v[132:133], v[96:97]
	v_pk_mul_f32 v[104:105], v[116:117], v[104:105]
	v_pk_add_f32 v[90:91], v[126:127], v[90:91]
	v_mov_b32_e32 v112, v114
	v_mov_b32_e32 v113, v92
	v_pk_mul_f32 v[132:133], v[96:97], v[96:97]
	v_pk_mul_f32 v[116:117], v[104:105], v[104:105]
	v_pk_add_f32 v[90:91], v[112:113], v[90:91]
	v_mov_b32_e32 v92, v115
	v_pk_mul_f32 v[94:95], v[136:137], v[94:95]
	v_pk_mul_f32 v[102:103], v[120:121], v[102:103]
	v_pk_add_f32 v[90:91], v[92:93], v[90:91]
	v_mov_b32_e32 v92, v116
	v_mov_b32_e32 v93, v132
	v_pk_mul_f32 v[130:131], v[94:95], v[94:95]
	v_pk_mul_f32 v[120:121], v[102:103], v[102:103]
	v_pk_add_f32 v[90:91], v[92:93], v[90:91]
	v_mov_b32_e32 v132, v117
	v_pk_add_f32 v[90:91], v[132:133], v[90:91]
	v_mov_b32_e32 v92, v120
	v_mov_b32_e32 v93, v130
	v_pk_add_f32 v[90:91], v[92:93], v[90:91]
	v_mov_b32_e32 v130, v121
	v_pk_add_f32 v[90:91], v[130:131], v[90:91]
	ds_bpermute_b32 v93, v174, v91
	ds_bpermute_b32 v92, v174, v90
	v_mul_f32_e32 v61, 0x4b800000, v62
	v_cndmask_b32_e32 v61, v62, v61, vcc
	v_rsq_f32_e32 v61, v61
	v_mul_f32_e32 v67, 0xbfb8aa3b, v50
	s_waitcnt lgkmcnt(0)
	v_pk_add_f32 v[62:63], v[90:91], v[92:93]
	ds_bpermute_b32 v113, v175, v63
	ds_bpermute_b32 v112, v175, v62
	v_exp_f32_e32 v67, v67
	v_exp_f32_e32 v69, v69
	v_pk_mul_f32 v[90:91], v[28:29], v[60:61] op_sel_hi:[1,0]
	v_mul_f32_e32 v28, 0x45800000, v61
	s_waitcnt lgkmcnt(0)
	v_pk_add_f32 v[112:113], v[62:63], v[112:113]
	ds_bpermute_b32 v115, v176, v113
	ds_bpermute_b32 v114, v176, v112
	v_cndmask_b32_e32 v28, v61, v28, vcc
	v_add_f32_e32 v67, 1.0, v67
	v_pk_mul_f32 v[92:93], v[30:31], v[60:61] op_sel_hi:[1,0]
	v_pk_mul_f32 v[62:63], v[124:125], v[28:29] op_sel_hi:[1,0]
	v_pk_mul_f32 v[60:61], v[122:123], v[28:29] op_sel_hi:[1,0]
	v_pk_mul_f32 v[30:31], v[118:119], v[28:29] op_sel_hi:[1,0]
	v_pk_mul_f32 v[28:29], v[110:111], v[28:29] op_sel_hi:[1,0]
	s_waitcnt lgkmcnt(0)
; __device__ __forceinline__ float silu_f(float x) { return x * __builtin_amdgcn_rcpf(1.f + __builtin_amdgcn_exp2f(-1.4426950408889634f * x)); }
; #define GAS __attribute__((address_space(1)))
; #define LAS __attribute__((address_space(3)))
; __device__ __forceinline__ v4u pk8(const float (&a)[8], const float s) { return (v4u){pk2(a[0] * s, a[1] * s), pk2(a[2] * s, a[3] * s), pk2(a[4] * s, a[5] * s), pk2(a[6] * s, a[7] * s)}; }
; __device__ __forceinline__ void prep_seg(const bf16_t* QK, const float* cw, const size_t rowbase, const int t0, const int h, const int seg, const int lane, float (&o)[8][8]) {
;     ...
;     for (int r = 0; r < 8; ++r) { float ss = 0.f;
; #pragma unroll
;         for (int e = 0; e < 8; ++e) { o[r][e] = silu_f(o[r][e]); ss += o[r][e] * o[r][e]; }
;         if (seg < 2) { ss += __shfl_xor(ss, 1); ss += __shfl_xor(ss, 2); ss += __shfl_xor(ss, 4); const float sc = rsqrtf(ss + 1e-6f) * (seg == 0 ? 0.125f : 1.f);
; #pragma unroll
;             for (int e = 0; e < 8; ++e) o[r][e] *= sc; } }
; __device__ __forceinline__ void intra_item(Frame& F, const int item, LAS unsigned char* SA, LAS unsigned char* SB, LAS float* GC, LAS float* BT) {
;     ...
; #pragma unroll
;     for (int r = 0; r < 8; ++r) { const int c = 8 * rg + r; *(LAS v4u*)(SA + c * STRB + cg * 16) = pk8(o[r], 1.f); *(GAS v4u*)(gi + 3 * 8192 + c * 128 + cg * 16) = pk8(o[r], __expf(gl - GC[c])); }
	v_pk_add_f32 v[110:111], v[112:113], v[114:115]
	v_rcp_f32_e32 v112, v67
	v_add_f32_e32 v67, 1.0, v69
	v_rcp_f32_e32 v113, v67
	v_mul_f32_e32 v67, 0xbfb8aa3b, v52
	v_exp_f32_e32 v67, v67
	v_mul_f32_e32 v69, 0xbfb8aa3b, v53
	v_exp_f32_e32 v69, v69
	v_pk_fma_f32 v[6:7], v[6:7], v[42:43], v[54:55]
	v_add_f32_e32 v67, 1.0, v67
	v_mul_f32_e32 v42, 0xbfb8aa3b, v6
	v_rcp_f32_e32 v114, v67
	v_add_f32_e32 v67, 1.0, v69
	v_exp_f32_e32 v54, v42
	v_mul_f32_e32 v42, 0xbfb8aa3b, v7
	v_rcp_f32_e32 v115, v67
	v_exp_f32_e32 v55, v42
	v_pk_fma_f32 v[4:5], v[4:5], v[40:41], v[48:49]
	v_mul_f32_e32 v73, 0xbfb8aa3b, v56
	v_pk_mul_f32 v[42:43], v[52:53], v[114:115]
	v_add_f32_e32 v52, 1.0, v54
	v_add_f32_e32 v53, 1.0, v55
	v_rcp_f32_e32 v52, v52
	v_rcp_f32_e32 v53, v53
	v_exp_f32_e32 v73, v73
	v_pk_fma_f32 v[2:3], v[2:3], v[38:39], v[46:47]
	v_pk_fma_f32 v[0:1], v[0:1], v[36:37], v[44:45]
	v_pk_mul_f32 v[114:115], v[6:7], v[52:53]
	v_mul_f32_e32 v6, 0xbfb8aa3b, v4
	v_exp_f32_e32 v40, v6
	v_mul_f32_e32 v6, 0xbfb8aa3b, v5
	v_exp_f32_e32 v41, v6
	v_mul_f32_e32 v38, 0xbfb8aa3b, v2
	v_mul_f32_e32 v36, 0xbfb8aa3b, v0
	v_mul_f32_e32 v37, 0xbfb8aa3b, v1
	v_add_f32_e32 v40, 1.0, v40
	v_add_f32_e32 v41, 1.0, v41
	v_exp_f32_e32 v46, v38
	v_mul_f32_e32 v38, 0xbfb8aa3b, v3
	v_exp_f32_e32 v36, v36
	v_exp_f32_e32 v37, v37
	v_add_f32_e32 v69, 1.0, v73
	v_rcp_f32_e32 v40, v40
	v_rcp_f32_e32 v41, v41
	v_exp_f32_e32 v47, v38
	v_rcp_f32_e32 v116, v69
	v_mul_f32_e32 v69, 0xbfb8aa3b, v57
	v_mul_f32_e32 v73, 0xbfb8aa3b, v58
	v_exp_f32_e32 v69, v69
	v_exp_f32_e32 v73, v73
	v_mul_f32_e32 v75, 0xbfb8aa3b, v59
	v_add_f32_e32 v36, 1.0, v36
	v_add_f32_e32 v37, 1.0, v37
	v_exp_f32_e32 v75, v75
	v_pk_mul_f32 v[38:39], v[4:5], v[40:41]
	v_add_f32_e32 v4, 1.0, v46
	v_add_f32_e32 v5, 1.0, v47
	v_rcp_f32_e32 v36, v36
	v_rcp_f32_e32 v37, v37
	v_rcp_f32_e32 v4, v4
	v_rcp_f32_e32 v5, v5
	v_add_f32_e32 v69, 1.0, v69
	v_add_f32_e32 v73, 1.0, v73
	v_rcp_f32_e32 v117, v69
	v_rcp_f32_e32 v118, v73
	v_add_f32_e32 v73, 1.0, v75
	v_pk_mul_f32 v[50:51], v[50:51], v[112:113]
	v_pk_mul_f32 v[36:37], v[0:1], v[36:37]
	v_rcp_f32_e32 v119, v73
	v_pk_mul_f32 v[112:113], v[50:51], v[50:51]
	v_pk_mul_f32 v[44:45], v[2:3], v[4:5]
	v_pk_mul_f32 v[0:1], v[36:37], v[36:37]
	v_pk_mul_f32 v[54:55], v[42:43], v[42:43]
	v_pk_mul_f32 v[2:3], v[44:45], v[44:45]
	v_mov_b32_e32 v4, v0
	v_mov_b32_e32 v5, v112
	v_mov_b32_e32 v112, v1
	v_pk_mul_f32 v[56:57], v[56:57], v[116:117]
	v_pk_add_f32 v[0:1], v[4:5], v[112:113]
	v_mov_b32_e32 v4, v2
	v_mov_b32_e32 v5, v54
	v_pk_mul_f32 v[116:117], v[56:57], v[56:57]
	v_pk_mul_f32 v[40:41], v[38:39], v[38:39]
	v_pk_add_f32 v[0:1], v[4:5], v[0:1]
	v_mov_b32_e32 v54, v3
	v_pk_mul_f32 v[118:119], v[58:59], v[118:119]
	v_pk_add_f32 v[0:1], v[54:55], v[0:1]
	v_mov_b32_e32 v2, v40
	v_mov_b32_e32 v3, v116
	v_pk_mul_f32 v[58:59], v[118:119], v[118:119]
	v_pk_mul_f32 v[6:7], v[114:115], v[114:115]
	v_pk_add_f32 v[0:1], v[2:3], v[0:1]
	v_mov_b32_e32 v116, v41
	v_pk_add_f32 v[0:1], v[116:117], v[0:1]
	v_mov_b32_e32 v2, v6
	v_mov_b32_e32 v3, v58
	v_pk_add_f32 v[0:1], v[2:3], v[0:1]
	v_mov_b32_e32 v58, v7
	v_pk_add_f32 v[0:1], v[58:59], v[0:1]
	ds_bpermute_b32 v3, v174, v1
	ds_bpermute_b32 v2, v174, v0
	v_pk_add_f32 v[110:111], v[110:111], s[68:69] op_sel_hi:[1,0]
	v_mul_lo_u32 v40, v158, s74
	v_mul_f32_e32 v64, 0x4b800000, v111
	v_cmp_gt_f32_e32 vcc, s73, v111
	s_waitcnt lgkmcnt(0)
	v_pk_add_f32 v[0:1], v[0:1], v[2:3]
	ds_bpermute_b32 v3, v175, v1
	v_cndmask_b32_e32 v64, v111, v64, vcc
	v_rsq_f32_e32 v64, v64
	ds_bpermute_b32 v2, v175, v0
	v_lshl_add_u32 v177, v158, 2, s31
	s_mul_i32 s22, s80, 0xa000
	v_mul_f32_e32 v71, 0x45800000, v64
	v_cndmask_b32_e32 v4, v64, v71, vcc
	s_waitcnt lgkmcnt(0)
	v_pk_add_f32 v[0:1], v[0:1], v[2:3]
	v_pk_mul_f32 v[46:47], v[100:101], v[4:5] op_sel_hi:[1,0]
	v_pk_mul_f32 v[98:99], v[98:99], v[4:5] op_sel_hi:[1,0]
	v_pk_mul_f32 v[96:97], v[96:97], v[4:5] op_sel_hi:[1,0]
	v_mul_f32_e32 v5, 0x4b800000, v110
	v_cmp_gt_f32_e32 vcc, s73, v110
	ds_bpermute_b32 v3, v176, v1
	ds_bpermute_b32 v2, v176, v0
	v_cndmask_b32_e32 v5, v110, v5, vcc
	v_rsq_f32_e32 v5, v5
	s_mul_hi_i32 s23, s80, 0xa000
	s_add_u32 s22, s33, s22
	s_waitcnt lgkmcnt(0)
	v_pk_add_f32 v[0:1], v[0:1], v[2:3]
	v_pk_mul_f32 v[100:101], v[94:95], v[4:5] op_sel_hi:[1,0]
	v_mul_f32_e32 v4, 0x45800000, v5
	v_pk_add_f32 v[0:1], v[0:1], s[68:69] op_sel_hi:[1,0]
	v_cndmask_b32_e32 v4, v5, v4, vcc
	v_mul_f32_e32 v2, 0x4b800000, v1
	v_cmp_gt_f32_e32 vcc, s73, v1
	v_pk_mul_f32 v[94:95], v[108:109], v[4:5] op_sel_hi:[1,0]
	v_pk_mul_f32 v[106:107], v[106:107], v[4:5] op_sel_hi:[1,0]
	v_cndmask_b32_e32 v1, v1, v2, vcc
	v_rsq_f32_e32 v1, v1
	v_pk_mul_f32 v[104:105], v[104:105], v[4:5] op_sel_hi:[1,0]
	v_pk_mul_f32 v[48:49], v[102:103], v[4:5] op_sel_hi:[1,0]
	v_cvt_pk_bf16_f32 v4, v22, v23
	v_mul_f32_e32 v2, 0x45800000, v1
	v_cndmask_b32_e32 v2, v1, v2, vcc
	v_mul_f32_e32 v1, 0x4b800000, v0
	v_cmp_gt_f32_e32 vcc, s73, v0
	v_pk_mul_f32 v[50:51], v[50:51], v[2:3] op_sel_hi:[1,0]
	v_pk_mul_f32 v[58:59], v[42:43], v[2:3] op_sel_hi:[1,0]
	v_cndmask_b32_e32 v0, v0, v1, vcc
	v_rsq_f32_e32 v6, v0
	v_pk_mul_f32 v[56:57], v[56:57], v[2:3] op_sel_hi:[1,0]
	v_pk_mul_f32 v[0:1], v[118:119], v[2:3] op_sel_hi:[1,0]
	v_lshlrev_b32_e32 v2, 4, v88
	v_and_b32_e32 v64, 0x70, v2
	v_add_u32_e32 v67, s31, v64
	v_cvt_pk_bf16_f32 v2, v26, v27
	v_cvt_pk_bf16_f32 v3, v24, v25
	v_cvt_pk_bf16_f32 v5, v16, v17
	v_add_u32_e32 v211, v67, v40
	ds_write_b128 v211, v[2:5]
	ds_read_b32 v3, v177 offset:18432
	v_mul_f32_e32 v7, 0x45800000, v6
	v_cndmask_b32_e32 v2, v6, v7, vcc
	s_addc_u32 s23, s34, s23
	v_mov_b32_e32 v108, 0
	s_waitcnt lgkmcnt(0)
; #define GAS __attribute__((address_space(1)))
; #define LAS __attribute__((address_space(3)))
; __device__ __forceinline__ v4u pk8(const float (&a)[8], const float s) { return (v4u){pk2(a[0] * s, a[1] * s), pk2(a[2] * s, a[3] * s), pk2(a[4] * s, a[5] * s), pk2(a[6] * s, a[7] * s)}; }
; __device__ __forceinline__ void intra_item(Frame& F, const int item, LAS unsigned char* SA, LAS unsigned char* SB, LAS float* GC, LAS float* BT) {
;     ...
; #pragma unroll
;     for (int r = 0; r < 8; ++r) { const int c = 8 * rg + r; *(LAS v4u*)(SA + c * STRB + cg * 16) = pk8(o[r], 1.f); *(GAS v4u*)(gi + 3 * 8192 + c * 128 + cg * 16) = pk8(o[r], __expf(gl - GC[c])); }
	v_pk_mul_f32 v[52:53], v[36:37], v[2:3] op_sel_hi:[1,0]
	v_pk_mul_f32 v[6:7], v[44:45], v[2:3] op_sel_hi:[1,0]
	v_pk_mul_f32 v[4:5], v[38:39], v[2:3] op_sel_hi:[1,0]
	v_sub_f32_e32 v3, v33, v3
	v_mul_f32_e32 v3, 0x3fb8aa3b, v3
	v_exp_f32_e32 v38, v3
	v_lshl_add_u64 v[36:37], s[22:23], 0, v[64:65]
	s_mov_b64 s[22:23], 0x6000
	v_pk_mul_f32 v[54:55], v[114:115], v[2:3] op_sel_hi:[1,0]
	v_pk_mul_f32 v[26:27], v[26:27], v[38:39] op_sel_hi:[1,0]
	v_pk_mul_f32 v[24:25], v[24:25], v[38:39] op_sel_hi:[1,0]
	v_cvt_pk_bf16_f32 v40, v26, v27
	v_cvt_pk_bf16_f32 v41, v24, v25
	v_pk_mul_f32 v[26:27], v[22:23], v[38:39] op_sel_hi:[1,0]
	v_cvt_pk_bf16_f32 v22, v14, v15
	v_cvt_pk_bf16_f32 v23, v20, v21
	v_cvt_pk_bf16_f32 v24, v18, v19
	v_cvt_pk_bf16_f32 v25, v10, v11
	ds_write_b128 v211, v[22:25] offset:144
	ds_read_b32 v22, v177 offset:18436
	v_pk_mul_f32 v[16:17], v[16:17], v[38:39] op_sel_hi:[1,0]
	v_lshlrev_b32_e32 v38, 7, v158
	v_cvt_pk_bf16_f32 v43, v16, v17
	v_lshl_add_u64 v[2:3], v[36:37], 0, s[22:23]
	s_waitcnt lgkmcnt(0)
	v_sub_f32_e32 v16, v33, v22
	v_mul_f32_e32 v16, 0x3fb8aa3b, v16
	v_exp_f32_e32 v22, v16
	v_ashrrev_i32_e32 v39, 31, v38
	v_cvt_pk_bf16_f32 v42, v26, v27
	v_lshl_add_u64 v[16:17], v[2:3], 0, v[38:39]
	global_store_dwordx4 v[16:17], v[40:43], off
	v_pk_mul_f32 v[14:15], v[14:15], v[22:23] op_sel_hi:[1,0]
	v_pk_mul_f32 v[16:17], v[20:21], v[22:23] op_sel_hi:[1,0]
	v_cvt_pk_bf16_f32 v14, v14, v15
	v_cvt_pk_bf16_f32 v15, v16, v17
	v_pk_mul_f32 v[20:21], v[18:19], v[22:23] op_sel_hi:[1,0]
	v_cvt_pk_bf16_f32 v16, v8, v9
	v_cvt_pk_bf16_f32 v17, v12, v13
	v_cvt_pk_bf16_f32 v18, v92, v93
	v_cvt_pk_bf16_f32 v19, v90, v91
	ds_write_b128 v211, v[16:19] offset:288
	ds_read_b32 v18, v177 offset:18440
	v_pk_mul_f32 v[10:11], v[10:11], v[22:23] op_sel_hi:[1,0]
	v_or_b32_e32 v40, 0x80, v38
	v_cvt_pk_bf16_f32 v17, v10, v11
	v_ashrrev_i32_e32 v41, 31, v40
	s_waitcnt lgkmcnt(0)
	v_sub_f32_e32 v10, v33, v18
	v_mul_f32_e32 v10, 0x3fb8aa3b, v10
	v_exp_f32_e32 v18, v10
	v_cvt_pk_bf16_f32 v16, v20, v21
	v_lshl_add_u64 v[10:11], v[2:3], 0, v[40:41]
	global_store_dwordx4 v[10:11], v[14:17], off
	v_pk_mul_f32 v[8:9], v[8:9], v[18:19] op_sel_hi:[1,0]
	v_pk_mul_f32 v[10:11], v[12:13], v[18:19] op_sel_hi:[1,0]
	v_cvt_pk_bf16_f32 v8, v8, v9
	v_cvt_pk_bf16_f32 v9, v10, v11
	v_cvt_pk_bf16_f32 v10, v62, v63
	v_cvt_pk_bf16_f32 v11, v60, v61
	v_cvt_pk_bf16_f32 v12, v30, v31
	v_cvt_pk_bf16_f32 v13, v28, v29
	ds_write_b128 v211, v[10:13] offset:432
	ds_read_b32 v16, v177 offset:18444
	v_pk_mul_f32 v[12:13], v[90:91], v[18:19] op_sel_hi:[1,0]
	v_pk_mul_f32 v[14:15], v[92:93], v[18:19] op_sel_hi:[1,0]
	v_cvt_pk_bf16_f32 v11, v12, v13
	v_cvt_pk_bf16_f32 v10, v14, v15
	s_waitcnt lgkmcnt(0)
	v_sub_f32_e32 v12, v33, v16
	v_mul_f32_e32 v12, 0x3fb8aa3b, v12
	v_exp_f32_e32 v14, v12
	v_or_b32_e32 v42, 0x100, v38
	v_ashrrev_i32_e32 v43, 31, v42
	v_lshl_add_u64 v[12:13], v[2:3], 0, v[42:43]
	global_store_dwordx4 v[12:13], v[8:11], off
	v_cvt_pk_bf16_f32 v12, v96, v97
	v_cvt_pk_bf16_f32 v13, v100, v101
	v_pk_mul_f32 v[8:9], v[62:63], v[14:15] op_sel_hi:[1,0]
	v_pk_mul_f32 v[10:11], v[60:61], v[14:15] op_sel_hi:[1,0]
	v_cvt_pk_bf16_f32 v8, v8, v9
	v_cvt_pk_bf16_f32 v9, v10, v11
	v_cvt_pk_bf16_f32 v10, v46, v47
	v_cvt_pk_bf16_f32 v11, v98, v99
	ds_write_b128 v211, v[10:13] offset:576
	v_pk_mul_f32 v[16:17], v[30:31], v[14:15] op_sel_hi:[1,0]
	ds_read_b32 v15, v177 offset:18448
	v_or_b32_e32 v44, 0x180, v38
	v_ashrrev_i32_e32 v45, 31, v44
	v_cvt_pk_bf16_f32 v10, v16, v17
	s_movk_i32 s22, 0x1000
	s_waitcnt lgkmcnt(0)
	v_pk_mul_f32 v[12:13], v[28:29], v[14:15] op_sel_hi:[1,0]
	v_lshlrev_b32_e32 v64, 1, v89
	v_cvt_pk_bf16_f32 v11, v12, v13
	v_sub_f32_e32 v12, v33, v15
	v_mul_f32_e32 v12, 0x3fb8aa3b, v12
	v_exp_f32_e32 v14, v12
	v_lshl_add_u64 v[12:13], v[2:3], 0, v[44:45]
	global_store_dwordx4 v[12:13], v[8:11], off
	v_cvt_pk_bf16_f32 v12, v104, v105
	v_cvt_pk_bf16_f32 v13, v48, v49
	v_pk_mul_f32 v[8:9], v[46:47], v[14:15] op_sel_hi:[1,0]
	v_pk_mul_f32 v[10:11], v[98:99], v[14:15] op_sel_hi:[1,0]
	v_cvt_pk_bf16_f32 v8, v8, v9
	v_cvt_pk_bf16_f32 v9, v10, v11
	v_cvt_pk_bf16_f32 v10, v94, v95
	v_cvt_pk_bf16_f32 v11, v106, v107
	ds_write_b128 v211, v[10:13] offset:720
	v_pk_mul_f32 v[16:17], v[96:97], v[14:15] op_sel_hi:[1,0]
	ds_read_b32 v15, v177 offset:18452
	v_or_b32_e32 v46, 0x200, v38
	v_ashrrev_i32_e32 v47, 31, v46
	v_cvt_pk_bf16_f32 v10, v16, v17
	v_lshl_add_u64 v[60:61], s[46:47], 0, v[64:65]
	s_waitcnt lgkmcnt(0)
	v_pk_mul_f32 v[12:13], v[100:101], v[14:15] op_sel_hi:[1,0]
	v_mov_b32_e32 v109, 0
	v_cvt_pk_bf16_f32 v11, v12, v13
	v_sub_f32_e32 v12, v33, v15
	v_mul_f32_e32 v12, 0x3fb8aa3b, v12
	v_exp_f32_e32 v14, v12
	v_lshl_add_u64 v[12:13], v[2:3], 0, v[46:47]
	global_store_dwordx4 v[12:13], v[8:11], off
	v_cvt_pk_bf16_f32 v12, v56, v57
	v_cvt_pk_bf16_f32 v13, v0, v1
	v_pk_mul_f32 v[8:9], v[94:95], v[14:15] op_sel_hi:[1,0]
	v_pk_mul_f32 v[10:11], v[106:107], v[14:15] op_sel_hi:[1,0]
	v_cvt_pk_bf16_f32 v8, v8, v9
	v_cvt_pk_bf16_f32 v9, v10, v11
	v_cvt_pk_bf16_f32 v10, v50, v51
	v_cvt_pk_bf16_f32 v11, v58, v59
	ds_write_b128 v211, v[10:13] offset:864
	v_pk_mul_f32 v[16:17], v[104:105], v[14:15] op_sel_hi:[1,0]
	ds_read_b32 v15, v177 offset:18456
	v_cvt_pk_bf16_f32 v10, v16, v17
	v_mov_b32_e32 v104, 0
	v_mov_b32_e32 v105, 0
	v_mov_b32_e32 v106, 0
	s_waitcnt lgkmcnt(0)
; #define GAS __attribute__((address_space(1)))
; #define LAS __attribute__((address_space(3)))
; __device__ __forceinline__ v4u pk8(const float (&a)[8], const float s) { return (v4u){pk2(a[0] * s, a[1] * s), pk2(a[2] * s, a[3] * s), pk2(a[4] * s, a[5] * s), pk2(a[6] * s, a[7] * s)}; }
; __device__ __forceinline__ void prep_seg(const bf16_t* QK, const float* cw, const size_t rowbase, const int t0, const int h, const int seg, const int lane, float (&o)[8][8]) {
;     ...
; #pragma unroll
;     for (int j = 0; j < 4; ++j) { const f32x4 a = *(const GAS f32x4*)(cw + j * CONVD + col), b = *(const GAS f32x4*)(cw + j * CONVD + col + 4); wt[j][0] = a.x; wt[j][1] = a.y; wt[j][2] = a.z; wt[j][3] = a.w; wt[j][4] = b.x; wt[j][5] = b.y; wt[j][6] = b.z; wt[j][7] = b.w; }
; #pragma unroll
;     for (int r = 0; r < 8; ++r)
; #pragma unroll
;         for (int e = 0; e < 8; ++e) o[r][e] = 0.f;
; #pragma unroll
;     for (int rr = 0; rr < 11; ++rr) { const int t = t0 + 8 * rg + rr - 3; float x[8];
;         if (t >= 0) unpack8(*(const GAS v4u*)(QK + (rowbase + t) * CONVD + col), x); else {
; #pragma unroll
;             for (int e = 0; e < 8; ++e) x[e] = 0.f; }
; __device__ __forceinline__ void intra_item(Frame& F, const int item, LAS unsigned char* SA, LAS unsigned char* SB, LAS float* GC, LAS float* BT) {
;     ...
; #pragma unroll
;     for (int r = 0; r < 8; ++r) { const int c = 8 * rg + r; *(LAS v4u*)(SA + c * STRB + cg * 16) = pk8(o[r], 1.f); *(GAS v4u*)(gi + 3 * 8192 + c * 128 + cg * 16) = pk8(o[r], __expf(gl - GC[c])); }
;     prep_seg(QK, cw, rowbase, t0, h, 0, lane, o);
	v_pk_mul_f32 v[12:13], v[48:49], v[14:15] op_sel_hi:[1,0]
	v_or_b32_e32 v48, 0x280, v38
	v_cvt_pk_bf16_f32 v11, v12, v13
	v_sub_f32_e32 v12, v33, v15
	v_mul_f32_e32 v12, 0x3fb8aa3b, v12
	v_exp_f32_e32 v14, v12
	v_ashrrev_i32_e32 v49, 31, v48
	v_lshl_add_u64 v[12:13], v[2:3], 0, v[48:49]
	global_store_dwordx4 v[12:13], v[8:11], off
	v_pk_mul_f32 v[16:17], v[56:57], v[14:15] op_sel_hi:[1,0]
	v_cvt_pk_bf16_f32 v12, v4, v5
	v_pk_mul_f32 v[8:9], v[50:51], v[14:15] op_sel_hi:[1,0]
	v_pk_mul_f32 v[10:11], v[58:59], v[14:15] op_sel_hi:[1,0]
	v_or_b32_e32 v15, 7, v88
	v_mul_lo_u32 v18, v15, s74
	v_cvt_pk_bf16_f32 v8, v8, v9
	v_cvt_pk_bf16_f32 v9, v10, v11
	v_cvt_pk_bf16_f32 v10, v52, v53
	v_cvt_pk_bf16_f32 v11, v6, v7
	v_cvt_pk_bf16_f32 v13, v54, v55
	v_add_u32_e32 v212, v67, v18
	ds_write_b128 v212, v[10:13]
	v_lshl_add_u32 v178, v15, 2, s31
	ds_read_b32 v12, v178 offset:18432
	v_pk_mul_f32 v[0:1], v[0:1], v[14:15] op_sel_hi:[1,0]
	v_or_b32_e32 v50, 0x300, v38
	v_cvt_pk_bf16_f32 v11, v0, v1
	v_ashrrev_i32_e32 v51, 31, v50
	s_waitcnt lgkmcnt(0)
	v_sub_f32_e32 v0, v33, v12
	v_mul_f32_e32 v0, 0x3fb8aa3b, v0
	v_exp_f32_e32 v0, v0
	v_cvt_pk_bf16_f32 v10, v16, v17
	v_lshl_add_u64 v[12:13], v[2:3], 0, v[50:51]
	global_store_dwordx4 v[12:13], v[8:11], off
	v_pk_mul_f32 v[6:7], v[6:7], v[0:1] op_sel_hi:[1,0]
	v_pk_mul_f32 v[4:5], v[4:5], v[0:1] op_sel_hi:[1,0]
	v_pk_mul_f32 v[8:9], v[52:53], v[0:1] op_sel_hi:[1,0]
	v_lshlrev_b32_e32 v52, 7, v15
	v_pk_mul_f32 v[0:1], v[54:55], v[0:1] op_sel_hi:[1,0]
	v_ashrrev_i32_e32 v53, 31, v52
	v_cvt_pk_bf16_f32 v8, v8, v9
	v_cvt_pk_bf16_f32 v9, v6, v7
	v_cvt_pk_bf16_f32 v10, v4, v5
	v_cvt_pk_bf16_f32 v11, v0, v1
	v_lshl_add_u64 v[0:1], v[2:3], 0, v[52:53]
	v_add_co_u32_e32 v2, vcc, s22, v34
	global_store_dwordx4 v[0:1], v[8:11], off
	s_nop 0
	v_addc_co_u32_e32 v3, vcc, 0, v35, vcc
	s_movk_i32 s22, 0x3000
	global_load_dwordx4 v[16:19], v[34:35], off offset:16
	global_load_dwordx4 v[20:23], v[34:35], off
	v_lshl_add_u64 v[0:1], v[34:35], 0, s[44:45]
	global_load_dwordx4 v[28:31], v[2:3], off offset:2048
	global_load_dwordx4 v[24:27], v[0:1], off offset:16
	v_add_co_u32_e32 v2, vcc, s22, v34
	v_lshl_add_u64 v[0:1], v[34:35], 0, s[48:49]
	s_nop 0
	v_addc_co_u32_e32 v3, vcc, 0, v35, vcc
	global_load_dwordx4 v[12:15], v[2:3], off
	global_load_dwordx4 v[8:11], v[0:1], off offset:16
	v_add_co_u32_e32 v0, vcc, 0x4000, v34
	v_lshl_add_u64 v[4:5], v[34:35], 0, s[78:79]
	s_nop 0
	v_addc_co_u32_e32 v1, vcc, 0, v35, vcc
	global_load_dwordx4 v[0:3], v[0:1], off offset:2048
	s_nop 0
	global_load_dwordx4 v[4:7], v[4:5], off offset:16
	v_mov_b32_e32 v33, 0
	v_mov_b32_e32 v107, 0
	v_mov_b32_e32 v180, 0
	v_mov_b32_e32 v181, 0
	v_mov_b32_e32 v182, 0
	v_mov_b32_e32 v183, 0
	s_and_saveexec_b64 s[22:23], s[0:1]
	v_mov_b32_e32 v69, v65
	v_lshl_add_u64 v[32:33], s[82:83], 0, v[68:69]
	v_mad_u64_u32 v[34:35], s[24:25], v32, s72, v[60:61]
	v_mad_i32_i24 v35, v33, s72, v35
	global_load_dwordx4 v[180:183], v[34:35], off
.LBB0_932:
	s_or_b64 exec, exec, s[22:23]
	v_mov_b32_e32 v116, 0
	v_mov_b32_e32 v118, 0
	v_mov_b32_e32 v119, 0
	v_mov_b32_e32 v120, 0
	v_mov_b32_e32 v121, 0
	v_mov_b32_e32 v122, 0
	v_mov_b32_e32 v123, 0
	v_mov_b32_e32 v124, 0
	v_mov_b32_e32 v125, 0
	v_mov_b32_e32 v184, 0
	v_mov_b32_e32 v185, 0
	v_mov_b32_e32 v186, 0
	v_mov_b32_e32 v187, 0
	s_and_saveexec_b64 s[22:23], s[2:3]
	v_mov_b32_e32 v71, v65
	v_lshl_add_u64 v[34:35], s[82:83], 0, v[70:71]
	v_mad_u64_u32 v[54:55], s[24:25], v34, s72, v[60:61]
	v_mad_i32_i24 v55, v35, s72, v55
	global_load_dwordx4 v[184:187], v[54:55], off
.LBB0_934:
	s_or_b64 exec, exec, s[22:23]
	v_mov_b32_e32 v117, 0
	v_mov_b32_e32 v140, 0
	v_mov_b32_e32 v141, 0
	v_mov_b32_e32 v142, 0
	v_mov_b32_e32 v143, 0
	v_mov_b32_e32 v146, 0
	v_mov_b32_e32 v147, 0
	v_mov_b32_e32 v188, 0
	v_mov_b32_e32 v189, 0
	v_mov_b32_e32 v190, 0
	v_mov_b32_e32 v191, 0
	s_and_saveexec_b64 s[22:23], s[4:5]
	v_mov_b32_e32 v73, v65
	v_lshl_add_u64 v[34:35], s[82:83], 0, v[72:73]
	v_mad_u64_u32 v[54:55], s[24:25], v34, s72, v[60:61]
	v_mad_i32_i24 v55, v35, s72, v55
	global_load_dwordx4 v[188:191], v[54:55], off
.LBB0_936:
	s_or_b64 exec, exec, s[22:23]
	v_mov_b32_e32 v102, 0
	v_mov_b32_e32 v150, 0
	v_mov_b32_e32 v151, 0
	v_mov_b32_e32 v152, 0
	v_mov_b32_e32 v153, 0
	v_mov_b32_e32 v154, 0
	v_mov_b32_e32 v155, 0
	v_mov_b32_e32 v148, 0
	v_mov_b32_e32 v149, 0
	v_mov_b32_e32 v192, 0
	v_mov_b32_e32 v193, 0
	v_mov_b32_e32 v194, 0
	v_mov_b32_e32 v195, 0
	s_and_saveexec_b64 s[22:23], s[6:7]
	v_mov_b32_e32 v67, v65
	v_lshl_add_u64 v[34:35], s[82:83], 0, v[66:67]
	v_mad_u64_u32 v[54:55], s[24:25], v34, s72, v[60:61]
	v_mad_i32_i24 v55, v35, s72, v55
	global_load_dwordx4 v[192:195], v[54:55], off
.LBB0_938:
	s_or_b64 exec, exec, s[22:23]
	v_mov_b32_e32 v103, 0
	v_mov_b32_e32 v110, 0
	v_mov_b32_e32 v111, 0
	v_mov_b32_e32 v112, 0
	v_mov_b32_e32 v113, 0
	v_mov_b32_e32 v114, 0
	v_mov_b32_e32 v115, 0
	v_mov_b32_e32 v196, 0
	v_mov_b32_e32 v197, 0
	v_mov_b32_e32 v198, 0
	v_mov_b32_e32 v199, 0
	s_and_saveexec_b64 s[22:23], s[8:9]
	v_mov_b32_e32 v75, v65
	v_lshl_add_u64 v[34:35], s[82:83], 0, v[74:75]
	v_mad_u64_u32 v[54:55], s[24:25], v34, s72, v[60:61]
	v_mad_i32_i24 v55, v35, s72, v55
	global_load_dwordx4 v[196:199], v[54:55], off
.LBB0_940:
	s_or_b64 exec, exec, s[22:23]
	v_mov_b32_e32 v164, 0
	v_mov_b32_e32 v126, 0
	v_mov_b32_e32 v127, 0
	v_mov_b32_e32 v128, 0
	v_mov_b32_e32 v129, 0
	v_mov_b32_e32 v130, 0
	v_mov_b32_e32 v131, 0
	v_mov_b32_e32 v132, 0
	v_mov_b32_e32 v133, 0
	v_mov_b32_e32 v204, 0
	v_mov_b32_e32 v205, 0
	v_mov_b32_e32 v206, 0
	v_mov_b32_e32 v207, 0
	s_and_saveexec_b64 s[22:23], s[10:11]
	v_mov_b32_e32 v77, v65
	v_lshl_add_u64 v[34:35], s[82:83], 0, v[76:77]
	v_mad_u64_u32 v[54:55], s[24:25], v34, s72, v[60:61]
	v_mad_i32_i24 v55, v35, s72, v55
	global_load_dwordx4 v[204:207], v[54:55], off
; #define GAS __attribute__((address_space(1)))
; __device__ __forceinline__ void prep_seg(const bf16_t* QK, const float* cw, const size_t rowbase, const int t0, const int h, const int seg, const int lane, float (&o)[8][8]) {
;     ...
;     for (int rr = 0; rr < 11; ++rr) { const int t = t0 + 8 * rg + rr - 3; float x[8];
;         if (t >= 0) unpack8(*(const GAS v4u*)(QK + (rowbase + t) * CONVD + col), x); else {
; #pragma unroll
;             for (int e = 0; e < 8; ++e) x[e] = 0.f; }
.LBB0_942:
	s_or_b64 exec, exec, s[22:23]
	v_mov_b32_e32 v165, 0
	v_mov_b32_e32 v166, 0
	v_mov_b32_e32 v167, 0
	v_mov_b32_e32 v168, 0
	v_mov_b32_e32 v169, 0
	v_mov_b32_e32 v170, 0
	v_mov_b32_e32 v171, 0
	v_mov_b32_e32 v214, 0
	v_mov_b32_e32 v215, 0
	v_mov_b32_e32 v216, 0
	v_mov_b32_e32 v217, 0
	s_and_saveexec_b64 s[22:23], s[12:13]
	v_mov_b32_e32 v79, v65
	v_lshl_add_u64 v[34:35], s[82:83], 0, v[78:79]
	v_mad_u64_u32 v[54:55], s[24:25], v34, s72, v[60:61]
	v_mad_i32_i24 v55, v35, s72, v55
	global_load_dwordx4 v[214:217], v[54:55], off
.LBB0_944:
	s_or_b64 exec, exec, s[22:23]
	v_mov_b32_e32 v134, 0
	v_mov_b32_e32 v156, 0
	v_mov_b32_e32 v157, 0
	v_mov_b32_e32 v158, 0
	v_mov_b32_e32 v159, 0
	v_mov_b32_e32 v160, 0
	v_mov_b32_e32 v161, 0
	v_mov_b32_e32 v162, 0
	v_mov_b32_e32 v163, 0
	v_mov_b32_e32 v218, 0
	v_mov_b32_e32 v219, 0
	v_mov_b32_e32 v220, 0
	v_mov_b32_e32 v221, 0
	s_and_saveexec_b64 s[22:23], s[14:15]
	v_mov_b32_e32 v81, v65
	v_lshl_add_u64 v[34:35], s[82:83], 0, v[80:81]
	v_mad_u64_u32 v[54:55], s[24:25], v34, s72, v[60:61]
	v_mad_i32_i24 v55, v35, s72, v55
	global_load_dwordx4 v[218:221], v[54:55], off
.LBB0_946:
	s_or_b64 exec, exec, s[22:23]
	v_mov_b32_e32 v135, 0
	v_mov_b32_e32 v136, 0
	v_mov_b32_e32 v137, 0
	v_mov_b32_e32 v138, 0
	v_mov_b32_e32 v139, 0
	v_mov_b32_e32 v144, 0
	v_mov_b32_e32 v145, 0
	v_mov_b32_e32 v222, 0
	v_mov_b32_e32 v223, 0
	v_mov_b32_e32 v224, 0
	v_mov_b32_e32 v225, 0
	s_and_saveexec_b64 s[22:23], s[16:17]
	v_mov_b32_e32 v83, v65
	v_lshl_add_u64 v[34:35], s[82:83], 0, v[82:83]
	v_mad_u64_u32 v[54:55], s[24:25], v34, s72, v[60:61]
	v_mad_i32_i24 v55, v35, s72, v55
	global_load_dwordx4 v[222:225], v[54:55], off
.LBB0_948:
	s_or_b64 exec, exec, s[22:23]
	v_mov_b32_e32 v34, 0
	v_mov_b32_e32 v92, 0
	v_mov_b32_e32 v93, 0
	v_mov_b32_e32 v94, 0
	v_mov_b32_e32 v95, 0
	v_mov_b32_e32 v98, 0
	v_mov_b32_e32 v99, 0
	v_mov_b32_e32 v100, 0
	v_mov_b32_e32 v101, 0
	v_mov_b32_e32 v226, 0
	v_mov_b32_e32 v227, 0
	v_mov_b32_e32 v228, 0
	v_mov_b32_e32 v229, 0
	s_and_saveexec_b64 s[22:23], s[18:19]
	v_mov_b32_e32 v85, v65
	v_lshl_add_u64 v[54:55], s[82:83], 0, v[84:85]
	v_mad_u64_u32 v[56:57], s[24:25], v54, s72, v[60:61]
	v_mad_i32_i24 v57, v55, s72, v57
	global_load_dwordx4 v[226:229], v[56:57], off
.LBB0_950:
	s_or_b64 exec, exec, s[22:23]
	v_mov_b32_e32 v35, 0
	v_mov_b32_e32 v54, 0
	v_mov_b32_e32 v55, 0
	v_mov_b32_e32 v56, 0
	v_mov_b32_e32 v57, 0
	v_mov_b32_e32 v58, 0
	v_mov_b32_e32 v59, 0
	v_mov_b32_e32 v230, 0
	v_mov_b32_e32 v231, 0
	v_mov_b32_e32 v232, 0
	v_mov_b32_e32 v233, 0
	s_and_saveexec_b64 s[22:23], s[20:21]
	v_mov_b32_e32 v87, v65
	v_lshl_add_u64 v[34:35], s[82:83], 0, v[86:87]
	v_mad_u64_u32 v[54:55], s[24:25], v34, s72, v[60:61]
	v_mad_i32_i24 v55, v35, s72, v55
	global_load_dwordx4 v[230:233], v[54:55], off
.LBB0_952:
	s_or_b64 exec, exec, s[22:23]
	s_waitcnt vmcnt(10)
	v_lshlrev_b32_e32 v32, 16, v180
	v_and_b32_e32 v33, 0xffff0000, v180
	v_lshlrev_b32_e32 v104, 16, v181
	v_and_b32_e32 v105, 0xffff0000, v181
	v_lshlrev_b32_e32 v106, 16, v182
	v_and_b32_e32 v107, 0xffff0000, v182
	v_lshlrev_b32_e32 v108, 16, v183
	v_and_b32_e32 v109, 0xffff0000, v183
	s_waitcnt vmcnt(9)
	v_lshlrev_b32_e32 v118, 16, v184
	v_and_b32_e32 v119, 0xffff0000, v184
	v_lshlrev_b32_e32 v120, 16, v185
	v_and_b32_e32 v121, 0xffff0000, v185
	v_lshlrev_b32_e32 v122, 16, v186
	v_and_b32_e32 v123, 0xffff0000, v186
	v_lshlrev_b32_e32 v124, 16, v187
	v_and_b32_e32 v125, 0xffff0000, v187
	s_waitcnt vmcnt(8)
	v_lshlrev_b32_e32 v116, 16, v188
	v_and_b32_e32 v117, 0xffff0000, v188
	v_lshlrev_b32_e32 v140, 16, v189
	v_and_b32_e32 v141, 0xffff0000, v189
	v_lshlrev_b32_e32 v142, 16, v190
	v_and_b32_e32 v143, 0xffff0000, v190
	v_lshlrev_b32_e32 v146, 16, v191
	v_and_b32_e32 v147, 0xffff0000, v191
	s_waitcnt vmcnt(7)
	v_lshlrev_b32_e32 v150, 16, v192
	v_and_b32_e32 v151, 0xffff0000, v192
	v_lshlrev_b32_e32 v152, 16, v193
	v_and_b32_e32 v153, 0xffff0000, v193
	v_lshlrev_b32_e32 v154, 16, v194
	v_and_b32_e32 v155, 0xffff0000, v194
	v_lshlrev_b32_e32 v148, 16, v195
	v_and_b32_e32 v149, 0xffff0000, v195
	s_waitcnt vmcnt(6)
	v_lshlrev_b32_e32 v102, 16, v196
	v_and_b32_e32 v103, 0xffff0000, v196
	v_lshlrev_b32_e32 v110, 16, v197
	v_and_b32_e32 v111, 0xffff0000, v197
	v_lshlrev_b32_e32 v112, 16, v198
	v_and_b32_e32 v113, 0xffff0000, v198
	v_lshlrev_b32_e32 v114, 16, v199
	v_and_b32_e32 v115, 0xffff0000, v199
	s_waitcnt vmcnt(5)
	v_lshlrev_b32_e32 v126, 16, v204
	v_and_b32_e32 v127, 0xffff0000, v204
	v_lshlrev_b32_e32 v128, 16, v205
	v_and_b32_e32 v129, 0xffff0000, v205
	v_lshlrev_b32_e32 v130, 16, v206
	v_and_b32_e32 v131, 0xffff0000, v206
	v_lshlrev_b32_e32 v132, 16, v207
	v_and_b32_e32 v133, 0xffff0000, v207
	s_waitcnt vmcnt(4)
	v_lshlrev_b32_e32 v164, 16, v214
	v_and_b32_e32 v165, 0xffff0000, v214
	v_lshlrev_b32_e32 v166, 16, v215
	v_and_b32_e32 v167, 0xffff0000, v215
	v_lshlrev_b32_e32 v168, 16, v216
	v_and_b32_e32 v169, 0xffff0000, v216
	v_lshlrev_b32_e32 v170, 16, v217
	v_and_b32_e32 v171, 0xffff0000, v217
	s_waitcnt vmcnt(3)
	v_lshlrev_b32_e32 v156, 16, v218
	v_and_b32_e32 v157, 0xffff0000, v218
	v_lshlrev_b32_e32 v158, 16, v219
	v_and_b32_e32 v159, 0xffff0000, v219
	v_lshlrev_b32_e32 v160, 16, v220
	v_and_b32_e32 v161, 0xffff0000, v220
	v_lshlrev_b32_e32 v162, 16, v221
	v_and_b32_e32 v163, 0xffff0000, v221
	s_waitcnt vmcnt(2)
	v_lshlrev_b32_e32 v134, 16, v222
	v_and_b32_e32 v135, 0xffff0000, v222
	v_lshlrev_b32_e32 v136, 16, v223
	v_and_b32_e32 v137, 0xffff0000, v223
	v_lshlrev_b32_e32 v138, 16, v224
	v_and_b32_e32 v139, 0xffff0000, v224
	v_lshlrev_b32_e32 v144, 16, v225
	v_and_b32_e32 v145, 0xffff0000, v225
	s_waitcnt vmcnt(1)
; #define GAS __attribute__((address_space(1)))
; __device__ __forceinline__ void prep_seg(const bf16_t* QK, const float* cw, const size_t rowbase, const int t0, const int h, const int seg, const int lane, float (&o)[8][8]) {
;     ...
;     for (int rr = 0; rr < 11; ++rr) { const int t = t0 + 8 * rg + rr - 3; float x[8];
;         if (t >= 0) unpack8(*(const GAS v4u*)(QK + (rowbase + t) * CONVD + col), x); else {
; #pragma unroll
;             for (int e = 0; e < 8; ++e) x[e] = 0.f; }
; #pragma unroll
;         for (int j = 0; j < 4; ++j) { const int r = rr - j;
;             if (r >= 0 && r < 8) {
; #pragma unroll
;                 for (int e = 0; e < 8; ++e) o[r][e] += wt[j][e] * x[e]; } } }
	v_lshlrev_b32_e32 v92, 16, v226
	v_and_b32_e32 v93, 0xffff0000, v226
	v_lshlrev_b32_e32 v94, 16, v227
	v_and_b32_e32 v95, 0xffff0000, v227
	v_lshlrev_b32_e32 v98, 16, v228
	v_and_b32_e32 v99, 0xffff0000, v228
	v_lshlrev_b32_e32 v100, 16, v229
	v_and_b32_e32 v101, 0xffff0000, v229
	s_waitcnt vmcnt(0)
	v_lshlrev_b32_e32 v34, 16, v230
	v_and_b32_e32 v35, 0xffff0000, v230
	v_lshlrev_b32_e32 v54, 16, v231
	v_and_b32_e32 v55, 0xffff0000, v231
	v_lshlrev_b32_e32 v56, 16, v232
	v_and_b32_e32 v57, 0xffff0000, v232
	v_lshlrev_b32_e32 v58, 16, v233
	v_and_b32_e32 v59, 0xffff0000, v233
	s_waitcnt vmcnt(6)
	v_pk_fma_f32 v[60:61], v[20:21], v[164:165], 0 op_sel_hi:[1,1,0]
	v_pk_fma_f32 v[180:181], v[20:21], v[156:157], 0 op_sel_hi:[1,1,0]
	v_pk_fma_f32 v[62:63], v[22:23], v[166:167], 0 op_sel_hi:[1,1,0]
	v_pk_fma_f32 v[90:91], v[16:17], v[168:169], 0 op_sel_hi:[1,1,0]
	v_pk_fma_f32 v[182:183], v[22:23], v[158:159], 0 op_sel_hi:[1,1,0]
	v_pk_fma_f32 v[184:185], v[16:17], v[160:161], 0 op_sel_hi:[1,1,0]
	s_waitcnt vmcnt(5)
	v_pk_fma_f32 v[60:61], v[28:29], v[156:157], v[60:61]
	v_pk_fma_f32 v[180:181], v[28:29], v[134:135], v[180:181]
	v_pk_fma_f32 v[62:63], v[30:31], v[158:159], v[62:63]
	s_waitcnt vmcnt(4)
	v_pk_fma_f32 v[90:91], v[24:25], v[160:161], v[90:91]
	v_pk_fma_f32 v[182:183], v[30:31], v[136:137], v[182:183]
	v_pk_fma_f32 v[184:185], v[24:25], v[138:139], v[184:185]
	s_waitcnt vmcnt(3)
	v_pk_fma_f32 v[188:189], v[12:13], v[134:135], v[60:61]
	v_pk_fma_f32 v[60:61], v[12:13], v[92:93], v[180:181]
	v_pk_fma_f32 v[180:181], v[20:21], v[126:127], 0 op_sel_hi:[1,1,0]
	v_pk_fma_f32 v[190:191], v[14:15], v[136:137], v[62:63]
	s_waitcnt vmcnt(2)
	v_pk_fma_f32 v[192:193], v[8:9], v[138:139], v[90:91]
	v_pk_fma_f32 v[62:63], v[14:15], v[94:95], v[182:183]
	v_pk_fma_f32 v[90:91], v[8:9], v[98:99], v[184:185]
	v_pk_fma_f32 v[182:183], v[22:23], v[128:129], 0 op_sel_hi:[1,1,0]
	v_pk_fma_f32 v[184:185], v[16:17], v[130:131], 0 op_sel_hi:[1,1,0]
	v_pk_fma_f32 v[180:181], v[28:29], v[164:165], v[180:181]
	v_pk_fma_f32 v[96:97], v[18:19], v[170:171], 0 op_sel_hi:[1,1,0]
	v_pk_fma_f32 v[186:187], v[18:19], v[162:163], 0 op_sel_hi:[1,1,0]
	v_pk_fma_f32 v[182:183], v[30:31], v[166:167], v[182:183]
	v_pk_fma_f32 v[184:185], v[24:25], v[168:169], v[184:185]
	v_pk_fma_f32 v[180:181], v[12:13], v[156:157], v[180:181]
	v_pk_fma_f32 v[96:97], v[26:27], v[162:163], v[96:97]
	v_pk_fma_f32 v[186:187], v[26:27], v[144:145], v[186:187]
	v_pk_fma_f32 v[182:183], v[14:15], v[158:159], v[182:183]
	v_pk_fma_f32 v[184:185], v[8:9], v[160:161], v[184:185]
	s_waitcnt vmcnt(1)
	v_pk_fma_f32 v[134:135], v[0:1], v[134:135], v[180:181]
	v_pk_fma_f32 v[180:181], v[20:21], v[102:103], 0 op_sel_hi:[1,1,0]
	v_pk_fma_f32 v[194:195], v[10:11], v[144:145], v[96:97]
	v_pk_fma_f32 v[96:97], v[10:11], v[100:101], v[186:187]
	v_pk_fma_f32 v[186:187], v[18:19], v[132:133], 0 op_sel_hi:[1,1,0]
	v_pk_fma_f32 v[136:137], v[2:3], v[136:137], v[182:183]
	s_waitcnt vmcnt(0)
	v_pk_fma_f32 v[138:139], v[4:5], v[138:139], v[184:185]
	v_pk_fma_f32 v[182:183], v[22:23], v[110:111], 0 op_sel_hi:[1,1,0]
	v_pk_fma_f32 v[184:185], v[16:17], v[112:113], 0 op_sel_hi:[1,1,0]
	v_pk_fma_f32 v[180:181], v[28:29], v[126:127], v[180:181]
	v_pk_fma_f32 v[186:187], v[26:27], v[170:171], v[186:187]
	v_pk_fma_f32 v[182:183], v[30:31], v[128:129], v[182:183]
	v_pk_fma_f32 v[184:185], v[24:25], v[130:131], v[184:185]
	v_pk_fma_f32 v[180:181], v[12:13], v[164:165], v[180:181]
	v_pk_fma_f32 v[186:187], v[10:11], v[162:163], v[186:187]
	v_pk_fma_f32 v[182:183], v[14:15], v[166:167], v[182:183]
	v_pk_fma_f32 v[184:185], v[8:9], v[168:169], v[184:185]
	v_pk_fma_f32 v[156:157], v[0:1], v[156:157], v[180:181]
	v_pk_fma_f32 v[180:181], v[20:21], v[150:151], 0 op_sel_hi:[1,1,0]
	v_pk_fma_f32 v[144:145], v[6:7], v[144:145], v[186:187]
	v_pk_fma_f32 v[186:187], v[18:19], v[114:115], 0 op_sel_hi:[1,1,0]
	v_pk_fma_f32 v[158:159], v[2:3], v[158:159], v[182:183]
	v_pk_fma_f32 v[160:161], v[4:5], v[160:161], v[184:185]
	v_pk_fma_f32 v[182:183], v[22:23], v[152:153], 0 op_sel_hi:[1,1,0]
	v_pk_fma_f32 v[184:185], v[16:17], v[154:155], 0 op_sel_hi:[1,1,0]
	v_pk_fma_f32 v[180:181], v[28:29], v[102:103], v[180:181]
	v_pk_fma_f32 v[186:187], v[26:27], v[132:133], v[186:187]
	v_pk_fma_f32 v[182:183], v[30:31], v[110:111], v[182:183]
	v_pk_fma_f32 v[184:185], v[24:25], v[112:113], v[184:185]
	v_pk_fma_f32 v[180:181], v[12:13], v[126:127], v[180:181]
	v_pk_fma_f32 v[92:93], v[0:1], v[92:93], v[188:189]
	v_pk_fma_f32 v[186:187], v[10:11], v[170:171], v[186:187]
	v_pk_fma_f32 v[182:183], v[14:15], v[128:129], v[182:183]
	v_pk_fma_f32 v[184:185], v[8:9], v[130:131], v[184:185]
	v_pk_fma_f32 v[164:165], v[0:1], v[164:165], v[180:181]
	v_pk_fma_f32 v[180:181], v[20:21], v[116:117], 0 op_sel_hi:[1,1,0]
	v_pk_fma_f32 v[188:189], v[20:21], v[118:119], 0 op_sel_hi:[1,1,0]
	v_pk_fma_f32 v[20:21], v[20:21], v[32:33], 0 op_sel_hi:[1,1,0]
	v_pk_fma_f32 v[94:95], v[2:3], v[94:95], v[190:191]
	v_pk_fma_f32 v[98:99], v[4:5], v[98:99], v[192:193]
	v_pk_fma_f32 v[162:163], v[6:7], v[162:163], v[186:187]
	v_pk_fma_f32 v[186:187], v[18:19], v[148:149], 0 op_sel_hi:[1,1,0]
	v_pk_fma_f32 v[166:167], v[2:3], v[166:167], v[182:183]
	v_pk_fma_f32 v[168:169], v[4:5], v[168:169], v[184:185]
	v_pk_fma_f32 v[182:183], v[22:23], v[140:141], 0 op_sel_hi:[1,1,0]
	v_pk_fma_f32 v[184:185], v[16:17], v[142:143], 0 op_sel_hi:[1,1,0]
	v_pk_fma_f32 v[190:191], v[22:23], v[120:121], 0 op_sel_hi:[1,1,0]
	v_pk_fma_f32 v[192:193], v[16:17], v[122:123], 0 op_sel_hi:[1,1,0]
	v_pk_fma_f32 v[22:23], v[22:23], v[104:105], 0 op_sel_hi:[1,1,0]
	v_pk_fma_f32 v[16:17], v[16:17], v[106:107], 0 op_sel_hi:[1,1,0]
; __device__ __forceinline__ float silu_f(float x) { return x * __builtin_amdgcn_rcpf(1.f + __builtin_amdgcn_exp2f(-1.4426950408889634f * x)); }
; __device__ __forceinline__ void prep_seg(const bf16_t* QK, const float* cw, const size_t rowbase, const int t0, const int h, const int seg, const int lane, float (&o)[8][8]) {
;     ...
; #pragma unroll
;         for (int j = 0; j < 4; ++j) { const int r = rr - j;
;             if (r >= 0 && r < 8) {
; #pragma unroll
;                 for (int e = 0; e < 8; ++e) o[r][e] += wt[j][e] * x[e]; } } }
; #pragma unroll
;     for (int r = 0; r < 8; ++r) { float ss = 0.f;
; #pragma unroll
;         for (int e = 0; e < 8; ++e) { o[r][e] = silu_f(o[r][e]); ss += o[r][e] * o[r][e]; }
;         if (seg < 2) { ss += __shfl_xor(ss, 1); ss += __shfl_xor(ss, 2); ss += __shfl_xor(ss, 4); const float sc = rsqrtf(ss + 1e-6f) * (seg == 0 ? 0.125f : 1.f);
; #pragma unroll
;             for (int e = 0; e < 8; ++e) o[r][e] *= sc; } }
	v_pk_fma_f32 v[20:21], v[28:29], v[118:119], v[20:21]
	v_pk_fma_f32 v[186:187], v[26:27], v[114:115], v[186:187]
	v_pk_fma_f32 v[22:23], v[30:31], v[120:121], v[22:23]
	v_pk_fma_f32 v[16:17], v[24:25], v[122:123], v[16:17]
	v_pk_fma_f32 v[20:21], v[12:13], v[116:117], v[20:21]
	v_pk_fma_f32 v[186:187], v[10:11], v[132:133], v[186:187]
	v_pk_fma_f32 v[184:185], v[24:25], v[154:155], v[184:185]
	v_pk_fma_f32 v[192:193], v[24:25], v[142:143], v[192:193]
	v_pk_fma_f32 v[22:23], v[14:15], v[140:141], v[22:23]
	v_pk_fma_f32 v[16:17], v[8:9], v[142:143], v[16:17]
	v_pk_fma_f32 v[24:25], v[0:1], v[150:151], v[20:21]
	v_pk_fma_f32 v[100:101], v[6:7], v[100:101], v[194:195]
	v_pk_fma_f32 v[170:171], v[6:7], v[170:171], v[186:187]
	v_pk_fma_f32 v[186:187], v[18:19], v[146:147], 0 op_sel_hi:[1,1,0]
	v_pk_fma_f32 v[194:195], v[18:19], v[124:125], 0 op_sel_hi:[1,1,0]
	v_pk_fma_f32 v[18:19], v[18:19], v[108:109], 0 op_sel_hi:[1,1,0]
	v_pk_fma_f32 v[20:21], v[2:3], v[152:153], v[22:23]
	v_pk_fma_f32 v[22:23], v[4:5], v[154:155], v[16:17]
	v_mul_f32_e32 v16, 0xbfb8aa3b, v24
	v_pk_fma_f32 v[186:187], v[26:27], v[148:149], v[186:187]
	v_pk_fma_f32 v[194:195], v[26:27], v[146:147], v[194:195]
	v_pk_fma_f32 v[18:19], v[26:27], v[124:125], v[18:19]
	v_exp_f32_e32 v26, v16
	v_mul_f32_e32 v16, 0xbfb8aa3b, v25
	v_exp_f32_e32 v27, v16
	v_pk_fma_f32 v[18:19], v[10:11], v[146:147], v[18:19]
	v_pk_fma_f32 v[180:181], v[28:29], v[150:151], v[180:181]
	v_pk_fma_f32 v[16:17], v[6:7], v[148:149], v[18:19]
	v_add_f32_e32 v18, 1.0, v26
	v_rcp_f32_e32 v26, v18
	v_add_f32_e32 v18, 1.0, v27
	v_rcp_f32_e32 v27, v18
	v_mul_f32_e32 v18, 0xbfb8aa3b, v20
	v_pk_fma_f32 v[188:189], v[28:29], v[116:117], v[188:189]
	v_exp_f32_e32 v18, v18
	v_mul_f32_e32 v19, 0xbfb8aa3b, v21
	v_mul_f32_e32 v28, 0xbfb8aa3b, v22
	v_exp_f32_e32 v19, v19
	v_exp_f32_e32 v29, v28
	v_add_f32_e32 v18, 1.0, v18
	v_rcp_f32_e32 v28, v18
	v_add_f32_e32 v32, 1.0, v19
	v_add_f32_e32 v18, 1.0, v29
	v_mul_f32_e32 v19, 0xbfb8aa3b, v23
	v_mul_f32_e32 v29, 0xbfb8aa3b, v16
	v_pk_fma_f32 v[182:183], v[30:31], v[152:153], v[182:183]
	v_pk_fma_f32 v[190:191], v[30:31], v[140:141], v[190:191]
	v_exp_f32_e32 v29, v29
	v_mul_f32_e32 v30, 0xbfb8aa3b, v17
	v_exp_f32_e32 v19, v19
	v_exp_f32_e32 v31, v30
	v_pk_fma_f32 v[190:191], v[14:15], v[152:153], v[190:191]
	v_add_f32_e32 v29, 1.0, v29
	v_add_f32_e32 v19, 1.0, v19
	v_pk_fma_f32 v[192:193], v[8:9], v[154:155], v[192:193]
	v_pk_fma_f32 v[190:191], v[2:3], v[110:111], v[190:191]
	v_rcp_f32_e32 v18, v18
	v_rcp_f32_e32 v30, v29
	v_add_f32_e32 v29, 1.0, v31
	v_rcp_f32_e32 v19, v19
	v_pk_fma_f32 v[192:193], v[4:5], v[112:113], v[192:193]
	v_rcp_f32_e32 v31, v29
	v_rcp_f32_e32 v29, v32
	v_mul_f32_e32 v32, 0xbfb8aa3b, v190
	v_pk_fma_f32 v[188:189], v[12:13], v[150:151], v[188:189]
	v_exp_f32_e32 v32, v32
	v_mul_f32_e32 v64, 0xbfb8aa3b, v192
	v_pk_fma_f32 v[188:189], v[0:1], v[102:103], v[188:189]
	v_mul_f32_e32 v33, 0xbfb8aa3b, v191
	v_exp_f32_e32 v64, v64
	v_pk_mul_f32 v[18:19], v[22:23], v[18:19]
	v_pk_mul_f32 v[22:23], v[24:25], v[26:27]
	v_mul_f32_e32 v24, 0xbfb8aa3b, v188
	v_exp_f32_e32 v33, v33
	v_exp_f32_e32 v26, v24
	v_mul_f32_e32 v24, 0xbfb8aa3b, v189
	v_pk_fma_f32 v[194:195], v[10:11], v[148:149], v[194:195]
	v_exp_f32_e32 v27, v24
	v_add_f32_e32 v32, 1.0, v32
	v_pk_fma_f32 v[194:195], v[6:7], v[114:115], v[194:195]
	v_rcp_f32_e32 v106, v32
	v_add_f32_e32 v32, 1.0, v64
	v_add_f32_e32 v67, 1.0, v33
	v_rcp_f32_e32 v104, v32
	v_mul_f32_e32 v32, 0xbfb8aa3b, v193
	v_mul_f32_e32 v33, 0xbfb8aa3b, v194
	v_mul_f32_e32 v64, 0xbfb8aa3b, v195
	v_exp_f32_e32 v33, v33
	v_exp_f32_e32 v64, v64
	v_exp_f32_e32 v69, v32
	v_add_f32_e32 v26, 1.0, v26
	v_add_f32_e32 v27, 1.0, v27
	v_rcp_f32_e32 v26, v26
	v_rcp_f32_e32 v27, v27
	v_rcp_f32_e32 v107, v67
	v_add_f32_e32 v32, 1.0, v33
	v_add_f32_e32 v33, 1.0, v64
	v_add_f32_e32 v64, 1.0, v69
	v_rcp_f32_e32 v105, v64
	v_pk_mul_f32 v[108:109], v[188:189], v[26:27]
	v_pk_mul_f32 v[20:21], v[20:21], v[28:29]
	v_pk_mul_f32 v[24:25], v[22:23], v[22:23]
	v_rcp_f32_e32 v32, v32
	v_rcp_f32_e32 v33, v33
	v_pk_mul_f32 v[106:107], v[190:191], v[106:107]
	v_pk_mul_f32 v[26:27], v[108:109], v[108:109]
	v_pk_mul_f32 v[28:29], v[20:21], v[20:21]
	v_pk_mul_f32 v[122:123], v[106:107], v[106:107]
	v_mov_b32_e32 v124, v26
	v_mov_b32_e32 v125, v24
	v_mov_b32_e32 v24, v27
	v_pk_mul_f32 v[104:105], v[192:193], v[104:105]
	v_pk_add_f32 v[24:25], v[124:125], v[24:25]
	v_mov_b32_e32 v26, v122
	v_mov_b32_e32 v27, v28
	v_pk_mul_f32 v[116:117], v[18:19], v[18:19]
	v_pk_mul_f32 v[120:121], v[104:105], v[104:105]
	v_pk_add_f32 v[24:25], v[26:27], v[24:25]
	v_mov_b32_e32 v28, v123
	v_pk_mul_f32 v[16:17], v[16:17], v[30:31]
	v_pk_mul_f32 v[32:33], v[194:195], v[32:33]
	v_pk_add_f32 v[24:25], v[28:29], v[24:25]
	v_mov_b32_e32 v26, v120
	v_mov_b32_e32 v27, v116
	v_pk_mul_f32 v[30:31], v[16:17], v[16:17]
	v_pk_mul_f32 v[118:119], v[32:33], v[32:33]
	v_pk_add_f32 v[24:25], v[26:27], v[24:25]
	v_mov_b32_e32 v116, v121
	v_pk_add_f32 v[24:25], v[116:117], v[24:25]
	v_mov_b32_e32 v26, v118
	v_mov_b32_e32 v27, v30
	v_pk_add_f32 v[24:25], v[26:27], v[24:25]
	v_mov_b32_e32 v30, v119
	v_pk_add_f32 v[24:25], v[30:31], v[24:25]
	ds_bpermute_b32 v27, v174, v25
	ds_bpermute_b32 v26, v174, v24
	v_pk_fma_f32 v[14:15], v[14:15], v[110:111], v[182:183]
	v_pk_fma_f32 v[12:13], v[12:13], v[102:103], v[180:181]
	v_pk_fma_f32 v[8:9], v[8:9], v[112:113], v[184:185]
	v_pk_fma_f32 v[12:13], v[0:1], v[126:127], v[12:13]
	s_waitcnt lgkmcnt(0)
	v_pk_add_f32 v[24:25], v[24:25], v[26:27]
	ds_bpermute_b32 v27, v175, v25
	ds_bpermute_b32 v26, v175, v24
	v_pk_fma_f32 v[14:15], v[2:3], v[128:129], v[14:15]
	v_pk_fma_f32 v[8:9], v[4:5], v[130:131], v[8:9]
	v_pk_fma_f32 v[10:11], v[10:11], v[114:115], v[186:187]
	v_and_b32_e32 v28, 16, v88
	s_waitcnt lgkmcnt(0)
; __device__ __forceinline__ float silu_f(float x) { return x * __builtin_amdgcn_rcpf(1.f + __builtin_amdgcn_exp2f(-1.4426950408889634f * x)); }
; __device__ __forceinline__ void prep_seg(const bf16_t* QK, const float* cw, const size_t rowbase, const int t0, const int h, const int seg, const int lane, float (&o)[8][8]) {
;     ...
;     for (int r = 0; r < 8; ++r) { float ss = 0.f;
; #pragma unroll
;         for (int e = 0; e < 8; ++e) { o[r][e] = silu_f(o[r][e]); ss += o[r][e] * o[r][e]; }
;         if (seg < 2) { ss += __shfl_xor(ss, 1); ss += __shfl_xor(ss, 2); ss += __shfl_xor(ss, 4); const float sc = rsqrtf(ss + 1e-6f) * (seg == 0 ? 0.125f : 1.f);
; #pragma unroll
;             for (int e = 0; e < 8; ++e) o[r][e] *= sc; } }
	v_pk_add_f32 v[24:25], v[24:25], v[26:27]
	ds_bpermute_b32 v27, v176, v25
	ds_bpermute_b32 v26, v176, v24
	v_pk_fma_f32 v[10:11], v[6:7], v[132:133], v[10:11]
	v_xor_b32_e32 v29, v173, v88
	v_cmp_eq_u32_e64 s[22:23], 0, v28
	v_cmp_eq_u32_e64 s[24:25], 16, v29
	s_waitcnt lgkmcnt(0)
	v_pk_add_f32 v[24:25], v[24:25], v[26:27]
	v_mul_f32_e32 v26, 0xbfb8aa3b, v13
	v_pk_add_f32 v[110:111], v[24:25], s[68:69] op_sel_hi:[1,0]
	v_exp_f32_e32 v26, v26
	v_mul_f32_e32 v24, 0x4b800000, v111
	v_cmp_gt_f32_e32 vcc, s73, v111
	v_mul_f32_e32 v27, 0xbfb8aa3b, v11
	v_exp_f32_e32 v27, v27
	v_cndmask_b32_e32 v24, v111, v24, vcc
	v_rsq_f32_e32 v24, v24
	v_mul_f32_e32 v75, 0xbfb8aa3b, v168
	v_exp_f32_e32 v75, v75
	v_mul_f32_e32 v77, 0xbfb8aa3b, v171
	v_mul_f32_e32 v25, 0x45800000, v24
	v_cndmask_b32_e32 v24, v24, v25, vcc
	v_mul_f32_e32 v25, 0xbfb8aa3b, v12
	v_exp_f32_e32 v25, v25
	v_mul_f32_e32 v64, 0x3e000000, v24
	v_exp_f32_e32 v77, v77
	v_cmp_gt_f32_e32 vcc, s73, v110
	v_add_f32_e32 v24, 1.0, v25
	v_rcp_f32_e32 v30, v24
	v_add_f32_e32 v24, 1.0, v26
	v_rcp_f32_e32 v31, v24
	v_mul_f32_e32 v24, 0xbfb8aa3b, v14
	v_exp_f32_e32 v24, v24
	v_mul_f32_e32 v26, 0xbfb8aa3b, v8
	v_mul_f32_e32 v25, 0xbfb8aa3b, v15
	v_exp_f32_e32 v26, v26
	v_exp_f32_e32 v25, v25
	v_add_f32_e32 v24, 1.0, v24
	v_rcp_f32_e32 v28, v24
	v_add_f32_e32 v24, 1.0, v26
	v_add_f32_e32 v29, 1.0, v25
	v_rcp_f32_e32 v26, v24
	v_mul_f32_e32 v24, 0xbfb8aa3b, v9
	v_mul_f32_e32 v25, 0xbfb8aa3b, v10
	v_exp_f32_e32 v25, v25
	v_exp_f32_e32 v71, v24
	v_pk_mul_f32 v[30:31], v[12:13], v[30:31]
	v_mul_f32_e32 v12, 0xbfb8aa3b, v164
	v_add_f32_e32 v24, 1.0, v25
	v_add_f32_e32 v25, 1.0, v27
	v_add_f32_e32 v27, 1.0, v71
	v_exp_f32_e32 v71, v12
	v_mul_f32_e32 v12, 0xbfb8aa3b, v165
	v_exp_f32_e32 v73, v12
	v_rcp_f32_e32 v29, v29
	v_add_f32_e32 v71, 1.0, v71
	v_rcp_f32_e32 v112, v71
	v_add_f32_e32 v71, 1.0, v73
	v_rcp_f32_e32 v113, v71
	v_mul_f32_e32 v71, 0xbfb8aa3b, v166
	v_exp_f32_e32 v71, v71
	v_mul_f32_e32 v73, 0xbfb8aa3b, v167
	v_exp_f32_e32 v73, v73
	v_rcp_f32_e32 v27, v27
	v_add_f32_e32 v71, 1.0, v71
	v_rcp_f32_e32 v102, v71
	v_add_f32_e32 v71, 1.0, v73
	v_add_f32_e32 v73, 1.0, v75
	v_rcp_f32_e32 v114, v73
	v_mul_f32_e32 v73, 0xbfb8aa3b, v169
	v_mul_f32_e32 v75, 0xbfb8aa3b, v170
	v_exp_f32_e32 v73, v73
	v_exp_f32_e32 v75, v75
	v_rcp_f32_e32 v103, v71
	v_pk_mul_f32 v[128:129], v[164:165], v[112:113]
	v_add_f32_e32 v73, 1.0, v73
	v_add_f32_e32 v75, 1.0, v75
	v_rcp_f32_e32 v115, v73
	v_rcp_f32_e32 v116, v75
	v_add_f32_e32 v75, 1.0, v77
	v_rcp_f32_e32 v24, v24
	v_rcp_f32_e32 v25, v25
	v_pk_mul_f32 v[28:29], v[14:15], v[28:29]
	v_pk_mul_f32 v[12:13], v[30:31], v[30:31]
	v_rcp_f32_e32 v117, v75
	v_pk_mul_f32 v[102:103], v[166:167], v[102:103]
	v_pk_mul_f32 v[112:113], v[128:129], v[128:129]
	v_pk_mul_f32 v[14:15], v[28:29], v[28:29]
	v_pk_mul_f32 v[118:119], v[102:103], v[102:103]
	v_mov_b32_e32 v120, v112
	v_mov_b32_e32 v121, v12
	v_mov_b32_e32 v12, v113
	v_pk_mul_f32 v[26:27], v[8:9], v[26:27]
	v_pk_mul_f32 v[124:125], v[168:169], v[114:115]
	v_pk_add_f32 v[12:13], v[120:121], v[12:13]
	v_mov_b32_e32 v112, v118
	v_mov_b32_e32 v113, v14
	v_pk_mul_f32 v[8:9], v[26:27], v[26:27]
	v_pk_mul_f32 v[114:115], v[124:125], v[124:125]
	v_pk_add_f32 v[12:13], v[112:113], v[12:13]
	v_mov_b32_e32 v14, v119
	v_pk_mul_f32 v[24:25], v[10:11], v[24:25]
	v_pk_mul_f32 v[122:123], v[170:171], v[116:117]
	v_pk_add_f32 v[12:13], v[14:15], v[12:13]
	v_mov_b32_e32 v14, v114
	v_mov_b32_e32 v15, v8
	v_pk_mul_f32 v[10:11], v[24:25], v[24:25]
	v_pk_mul_f32 v[116:117], v[122:123], v[122:123]
	v_pk_add_f32 v[12:13], v[14:15], v[12:13]
	v_mov_b32_e32 v8, v115
	v_pk_add_f32 v[8:9], v[8:9], v[12:13]
	v_mov_b32_e32 v12, v116
	v_mov_b32_e32 v13, v10
	v_pk_add_f32 v[8:9], v[12:13], v[8:9]
	v_mov_b32_e32 v10, v117
	v_pk_add_f32 v[8:9], v[10:11], v[8:9]
	ds_bpermute_b32 v11, v174, v9
	ds_bpermute_b32 v10, v174, v8
	v_pk_mul_f32 v[12:13], v[16:17], v[64:65] op_sel_hi:[1,0]
	v_mul_f32_e32 v16, 0x4b800000, v110
	v_cndmask_b32_e32 v16, v110, v16, vcc
	v_rsq_f32_e32 v16, v16
	s_waitcnt lgkmcnt(0)
	v_pk_add_f32 v[8:9], v[8:9], v[10:11]
	ds_bpermute_b32 v11, v175, v9
	ds_bpermute_b32 v10, v175, v8
	v_mul_f32_e32 v17, 0x45800000, v16
	v_cndmask_b32_e32 v16, v16, v17, vcc
	v_pk_mul_f32 v[22:23], v[22:23], v[64:65] op_sel_hi:[1,0]
	v_pk_mul_f32 v[20:21], v[20:21], v[64:65] op_sel_hi:[1,0]
	s_waitcnt lgkmcnt(0)
	v_pk_add_f32 v[8:9], v[8:9], v[10:11]
	ds_bpermute_b32 v11, v176, v9
	ds_bpermute_b32 v10, v176, v8
	v_pk_mul_f32 v[14:15], v[18:19], v[64:65] op_sel_hi:[1,0]
	v_mul_f32_e32 v64, 0x3e000000, v16
	v_pk_mul_f32 v[16:17], v[108:109], v[64:65] op_sel_hi:[1,0]
	v_pk_mul_f32 v[18:19], v[106:107], v[64:65] op_sel_hi:[1,0]
	s_waitcnt lgkmcnt(0)
; __device__ __forceinline__ float silu_f(float x) { return x * __builtin_amdgcn_rcpf(1.f + __builtin_amdgcn_exp2f(-1.4426950408889634f * x)); }
; __device__ __forceinline__ void prep_seg(const bf16_t* QK, const float* cw, const size_t rowbase, const int t0, const int h, const int seg, const int lane, float (&o)[8][8]) {
;     ...
;     for (int r = 0; r < 8; ++r) { float ss = 0.f;
; #pragma unroll
;         for (int e = 0; e < 8; ++e) { o[r][e] = silu_f(o[r][e]); ss += o[r][e] * o[r][e]; }
;         if (seg < 2) { ss += __shfl_xor(ss, 1); ss += __shfl_xor(ss, 2); ss += __shfl_xor(ss, 4); const float sc = rsqrtf(ss + 1e-6f) * (seg == 0 ? 0.125f : 1.f);
; #pragma unroll
;             for (int e = 0; e < 8; ++e) o[r][e] *= sc; } }
	v_pk_add_f32 v[8:9], v[8:9], v[10:11]
	v_pk_mul_f32 v[10:11], v[104:105], v[64:65] op_sel_hi:[1,0]
	v_pk_add_f32 v[130:131], v[8:9], s[68:69] op_sel_hi:[1,0]
	v_mul_f32_e32 v73, 0xbfb8aa3b, v163
	v_mul_f32_e32 v8, 0x4b800000, v131
	v_cmp_gt_f32_e32 vcc, s73, v131
	v_exp_f32_e32 v73, v73
	v_mul_f32_e32 v75, 0xbfb8aa3b, v98
	v_cndmask_b32_e32 v8, v131, v8, vcc
	v_rsq_f32_e32 v71, v8
	v_pk_mul_f32 v[8:9], v[32:33], v[64:65] op_sel_hi:[1,0]
	v_mul_f32_e32 v33, 0xbfb8aa3b, v156
	v_exp_f32_e32 v33, v33
	v_mul_f32_e32 v64, 0xbfb8aa3b, v157
	v_exp_f32_e32 v64, v64
	v_mul_f32_e32 v32, 0x45800000, v71
	v_add_f32_e32 v33, 1.0, v33
	v_rcp_f32_e32 v104, v33
	v_add_f32_e32 v33, 1.0, v64
	v_rcp_f32_e32 v105, v33
	v_mul_f32_e32 v33, 0xbfb8aa3b, v158
	v_cndmask_b32_e32 v32, v71, v32, vcc
	v_exp_f32_e32 v33, v33
	v_mul_f32_e32 v64, 0xbfb8aa3b, v159
	v_mul_f32_e32 v71, 0xbfb8aa3b, v160
	v_exp_f32_e32 v64, v64
	v_exp_f32_e32 v71, v71
	v_add_f32_e32 v33, 1.0, v33
	v_rcp_f32_e32 v106, v33
	v_add_f32_e32 v33, 1.0, v64
	v_add_f32_e32 v64, 1.0, v71
	v_rcp_f32_e32 v110, v64
	v_mul_f32_e32 v64, 0xbfb8aa3b, v161
	v_exp_f32_e32 v64, v64
	v_rcp_f32_e32 v107, v33
	v_mul_f32_e32 v33, 0xbfb8aa3b, v134
	v_mul_f32_e32 v71, 0xbfb8aa3b, v162
	v_add_f32_e32 v64, 1.0, v64
	v_rcp_f32_e32 v111, v64
	v_exp_f32_e32 v33, v33
	v_mul_f32_e32 v64, 0xbfb8aa3b, v135
	v_exp_f32_e32 v71, v71
	v_exp_f32_e32 v64, v64
	v_add_f32_e32 v33, 1.0, v33
	v_rcp_f32_e32 v126, v33
	v_add_f32_e32 v71, 1.0, v71
	v_add_f32_e32 v33, 1.0, v64
	v_rcp_f32_e32 v108, v71
	v_add_f32_e32 v71, 1.0, v73
	v_rcp_f32_e32 v127, v33
	v_mul_f32_e32 v33, 0xbfb8aa3b, v136
	v_rcp_f32_e32 v109, v71
	v_exp_f32_e32 v33, v33
	v_mul_f32_e32 v64, 0xbfb8aa3b, v137
	v_mul_f32_e32 v71, 0xbfb8aa3b, v138
	v_exp_f32_e32 v64, v64
	v_exp_f32_e32 v71, v71
	v_add_f32_e32 v33, 1.0, v33
	v_rcp_f32_e32 v120, v33
	v_add_f32_e32 v33, 1.0, v64
	v_add_f32_e32 v64, 1.0, v71
	v_mul_f32_e32 v71, 0xbfb8aa3b, v144
	v_exp_f32_e32 v71, v71
	v_mul_f32_e32 v73, 0xbfb8aa3b, v145
	v_rcp_f32_e32 v118, v64
	v_mul_f32_e32 v64, 0xbfb8aa3b, v139
	v_exp_f32_e32 v73, v73
	v_exp_f32_e32 v64, v64
	v_add_f32_e32 v71, 1.0, v71
	v_rcp_f32_e32 v116, v71
	v_add_f32_e32 v71, 1.0, v73
	v_rcp_f32_e32 v121, v33
	v_rcp_f32_e32 v117, v71
	v_add_f32_e32 v64, 1.0, v64
	v_rcp_f32_e32 v119, v64
	v_pk_mul_f32 v[114:115], v[156:157], v[104:105]
	v_pk_mul_f32 v[126:127], v[134:135], v[126:127]
	v_pk_mul_f32 v[112:113], v[158:159], v[106:107]
	v_pk_mul_f32 v[104:105], v[114:115], v[114:115]
	v_pk_mul_f32 v[120:121], v[136:137], v[120:121]
	v_pk_mul_f32 v[134:135], v[126:127], v[126:127]
	v_pk_mul_f32 v[106:107], v[112:113], v[112:113]
	v_pk_mul_f32 v[116:117], v[144:145], v[116:117]
	v_pk_mul_f32 v[136:137], v[120:121], v[120:121]
	v_mov_b32_e32 v144, v134
	v_mov_b32_e32 v145, v104
	v_mov_b32_e32 v104, v135
	v_pk_mul_f32 v[110:111], v[160:161], v[110:111]
	v_pk_mul_f32 v[118:119], v[138:139], v[118:119]
	v_pk_add_f32 v[104:105], v[144:145], v[104:105]
	v_mov_b32_e32 v134, v136
	v_mov_b32_e32 v135, v106
	v_pk_mul_f32 v[140:141], v[110:111], v[110:111]
	v_pk_mul_f32 v[138:139], v[118:119], v[118:119]
	v_pk_add_f32 v[104:105], v[134:135], v[104:105]
	v_mov_b32_e32 v106, v137
	v_pk_mul_f32 v[108:109], v[162:163], v[108:109]
	v_pk_add_f32 v[104:105], v[106:107], v[104:105]
	v_mov_b32_e32 v106, v138
	v_mov_b32_e32 v107, v140
	v_pk_mul_f32 v[132:133], v[108:109], v[108:109]
	v_pk_mul_f32 v[142:143], v[116:117], v[116:117]
	v_pk_add_f32 v[104:105], v[106:107], v[104:105]
	v_mov_b32_e32 v140, v139
	v_pk_add_f32 v[104:105], v[140:141], v[104:105]
	v_mov_b32_e32 v106, v142
	v_mov_b32_e32 v107, v132
	v_pk_add_f32 v[104:105], v[106:107], v[104:105]
	v_mov_b32_e32 v132, v143
	v_pk_add_f32 v[132:133], v[132:133], v[104:105]
	ds_bpermute_b32 v135, v174, v133
	ds_bpermute_b32 v134, v174, v132
	v_mul_f32_e32 v32, 0x3e000000, v32
	v_pk_mul_f32 v[104:105], v[28:29], v[32:33] op_sel_hi:[1,0]
	v_pk_mul_f32 v[28:29], v[24:25], v[32:33] op_sel_hi:[1,0]
	v_pk_mul_f32 v[106:107], v[30:31], v[32:33] op_sel_hi:[1,0]
	s_waitcnt lgkmcnt(0)
	v_pk_add_f32 v[24:25], v[132:133], v[134:135]
	v_pk_mul_f32 v[30:31], v[26:27], v[32:33] op_sel_hi:[1,0]
	ds_bpermute_b32 v27, v175, v25
	ds_bpermute_b32 v26, v175, v24
	v_mul_f32_e32 v32, 0x4b800000, v130
	v_cmp_gt_f32_e32 vcc, s73, v130
	v_mul_f32_e32 v73, 0xbfb8aa3b, v93
	v_exp_f32_e32 v73, v73
	v_cndmask_b32_e32 v32, v130, v32, vcc
	v_rsq_f32_e32 v32, v32
	s_waitcnt lgkmcnt(0)
	v_pk_add_f32 v[24:25], v[24:25], v[26:27]
	ds_bpermute_b32 v27, v176, v25
	ds_bpermute_b32 v26, v176, v24
	v_mul_f32_e32 v33, 0x45800000, v32
	v_cndmask_b32_e32 v32, v32, v33, vcc
	v_mul_f32_e32 v64, 0x3e000000, v32
	v_pk_mul_f32 v[32:33], v[128:129], v[64:65] op_sel_hi:[1,0]
	s_waitcnt lgkmcnt(0)
; __device__ __forceinline__ float silu_f(float x) { return x * __builtin_amdgcn_rcpf(1.f + __builtin_amdgcn_exp2f(-1.4426950408889634f * x)); }
; #define GAS __attribute__((address_space(1)))
; #define LAS __attribute__((address_space(3)))
; __device__ __forceinline__ v4u pk8(const float (&a)[8], const float s) { return (v4u){pk2(a[0] * s, a[1] * s), pk2(a[2] * s, a[3] * s), pk2(a[4] * s, a[5] * s), pk2(a[6] * s, a[7] * s)}; }
; __device__ __forceinline__ void prep_seg(const bf16_t* QK, const float* cw, const size_t rowbase, const int t0, const int h, const int seg, const int lane, float (&o)[8][8]) {
;     ...
;     for (int r = 0; r < 8; ++r) { float ss = 0.f;
; #pragma unroll
;         for (int e = 0; e < 8; ++e) { o[r][e] = silu_f(o[r][e]); ss += o[r][e] * o[r][e]; }
;         if (seg < 2) { ss += __shfl_xor(ss, 1); ss += __shfl_xor(ss, 2); ss += __shfl_xor(ss, 4); const float sc = rsqrtf(ss + 1e-6f) * (seg == 0 ? 0.125f : 1.f);
; #pragma unroll
;             for (int e = 0; e < 8; ++e) o[r][e] *= sc; } }
; __device__ __forceinline__ void intra_item(Frame& F, const int item, LAS unsigned char* SA, LAS unsigned char* SB, LAS float* GC, LAS float* BT) {
;     ...
; #pragma unroll
;     for (int r = 0; r < 8; ++r) { const int c = 8 * rg + r; *(LAS v4u*)(SB + c * STRB + cg * 16) = pk8(o[r], 1.f); *(GAS v4u*)(gi + 2 * 8192 + c * 128 + cg * 16) = pk8(o[r], __expf(GC[c])); }
	v_pk_add_f32 v[24:25], v[24:25], v[26:27]
	v_pk_mul_f32 v[102:103], v[102:103], v[64:65] op_sel_hi:[1,0]
	v_pk_add_f32 v[128:129], v[24:25], s[68:69] op_sel_hi:[1,0]
	v_pk_mul_f32 v[26:27], v[124:125], v[64:65] op_sel_hi:[1,0]
	v_mul_f32_e32 v24, 0x4b800000, v129
	v_cmp_gt_f32_e32 vcc, s73, v129
	v_exp_f32_e32 v75, v75
	v_pk_fma_f32 v[6:7], v[6:7], v[58:59], v[96:97]
	v_cndmask_b32_e32 v24, v129, v24, vcc
	v_rsq_f32_e32 v71, v24
	v_pk_mul_f32 v[24:25], v[122:123], v[64:65] op_sel_hi:[1,0]
	v_mul_f32_e32 v58, 0xbfb8aa3b, v6
	v_pk_fma_f32 v[4:5], v[4:5], v[56:57], v[90:91]
	v_mul_f32_e32 v64, 0x45800000, v71
	v_cndmask_b32_e32 v64, v71, v64, vcc
	v_mul_f32_e32 v71, 0xbfb8aa3b, v92
	v_exp_f32_e32 v71, v71
	v_pk_fma_f32 v[2:3], v[2:3], v[54:55], v[62:63]
	v_pk_fma_f32 v[0:1], v[0:1], v[34:35], v[60:61]
	v_mul_f32_e32 v54, 0xbfb8aa3b, v2
	v_add_f32_e32 v71, 1.0, v71
	v_rcp_f32_e32 v122, v71
	v_add_f32_e32 v71, 1.0, v73
	v_rcp_f32_e32 v123, v71
	v_mul_f32_e32 v71, 0xbfb8aa3b, v94
	v_exp_f32_e32 v71, v71
	v_mul_f32_e32 v73, 0xbfb8aa3b, v95
	v_exp_f32_e32 v73, v73
	v_mul_f32_e32 v34, 0xbfb8aa3b, v0
	v_add_f32_e32 v71, 1.0, v71
	v_rcp_f32_e32 v124, v71
	v_add_f32_e32 v71, 1.0, v73
	v_add_f32_e32 v73, 1.0, v75
	v_rcp_f32_e32 v130, v73
	v_mul_f32_e32 v73, 0xbfb8aa3b, v99
	v_exp_f32_e32 v73, v73
	v_rcp_f32_e32 v125, v71
	v_exp_f32_e32 v71, v58
	v_mul_f32_e32 v58, 0xbfb8aa3b, v7
	v_add_f32_e32 v73, 1.0, v73
	v_rcp_f32_e32 v131, v73
	v_exp_f32_e32 v73, v58
	v_add_f32_e32 v71, 1.0, v71
	v_pk_mul_f32 v[58:59], v[94:95], v[124:125]
	v_rcp_f32_e32 v94, v71
	v_add_f32_e32 v71, 1.0, v73
	v_rcp_f32_e32 v95, v71
	v_mul_f32_e32 v35, 0xbfb8aa3b, v1
	v_exp_f32_e32 v62, v54
	v_mul_f32_e32 v54, 0xbfb8aa3b, v3
	v_pk_mul_f32 v[94:95], v[6:7], v[94:95]
	v_mul_f32_e32 v6, 0xbfb8aa3b, v4
	v_exp_f32_e32 v56, v6
	v_mul_f32_e32 v6, 0xbfb8aa3b, v5
	v_exp_f32_e32 v57, v6
	v_exp_f32_e32 v34, v34
	v_add_f32_e32 v56, 1.0, v56
	v_exp_f32_e32 v35, v35
	v_add_f32_e32 v57, 1.0, v57
	v_rcp_f32_e32 v56, v56
	v_rcp_f32_e32 v57, v57
	v_exp_f32_e32 v63, v54
	v_mul_f32_e32 v75, 0xbfb8aa3b, v100
	v_exp_f32_e32 v75, v75
	v_mul_f32_e32 v77, 0xbfb8aa3b, v101
	v_add_f32_e32 v34, 1.0, v34
	v_add_f32_e32 v35, 1.0, v35
	v_exp_f32_e32 v77, v77
	v_pk_mul_f32 v[54:55], v[4:5], v[56:57]
	v_add_f32_e32 v4, 1.0, v62
	v_add_f32_e32 v5, 1.0, v63
	v_rcp_f32_e32 v34, v34
	v_rcp_f32_e32 v35, v35
	v_rcp_f32_e32 v4, v4
	v_rcp_f32_e32 v5, v5
	v_add_f32_e32 v75, 1.0, v75
	v_rcp_f32_e32 v132, v75
	v_add_f32_e32 v75, 1.0, v77
	v_pk_mul_f32 v[92:93], v[92:93], v[122:123]
	v_pk_mul_f32 v[34:35], v[0:1], v[34:35]
	v_rcp_f32_e32 v133, v75
	v_pk_mul_f32 v[122:123], v[92:93], v[92:93]
	v_pk_mul_f32 v[60:61], v[2:3], v[4:5]
	v_pk_mul_f32 v[0:1], v[34:35], v[34:35]
	v_pk_mul_f32 v[96:97], v[58:59], v[58:59]
	v_pk_mul_f32 v[2:3], v[60:61], v[60:61]
	v_mov_b32_e32 v4, v0
	v_mov_b32_e32 v5, v122
	v_mov_b32_e32 v122, v1
	v_pk_mul_f32 v[98:99], v[98:99], v[130:131]
	v_pk_add_f32 v[0:1], v[4:5], v[122:123]
	v_mov_b32_e32 v4, v2
	v_mov_b32_e32 v5, v96
	v_pk_mul_f32 v[130:131], v[98:99], v[98:99]
	v_pk_mul_f32 v[56:57], v[54:55], v[54:55]
	v_pk_add_f32 v[0:1], v[4:5], v[0:1]
	v_mov_b32_e32 v96, v3
	v_pk_mul_f32 v[100:101], v[100:101], v[132:133]
	v_pk_add_f32 v[0:1], v[96:97], v[0:1]
	v_mov_b32_e32 v2, v56
	v_mov_b32_e32 v3, v130
	v_pk_mul_f32 v[132:133], v[100:101], v[100:101]
	v_pk_mul_f32 v[6:7], v[94:95], v[94:95]
	v_pk_add_f32 v[0:1], v[2:3], v[0:1]
	v_mov_b32_e32 v130, v57
	v_pk_add_f32 v[0:1], v[130:131], v[0:1]
	v_mov_b32_e32 v2, v6
	v_mov_b32_e32 v3, v132
	v_pk_add_f32 v[0:1], v[2:3], v[0:1]
	v_mov_b32_e32 v132, v7
	v_pk_add_f32 v[0:1], v[132:133], v[0:1]
	ds_bpermute_b32 v3, v174, v1
	ds_bpermute_b32 v2, v174, v0
	v_mul_f32_e32 v4, 0x4b800000, v128
	v_cmp_gt_f32_e32 vcc, s73, v128
	v_mul_f32_e32 v64, 0x3e000000, v64
	v_pk_mul_f32 v[56:57], v[114:115], v[64:65] op_sel_hi:[1,0]
	s_waitcnt lgkmcnt(0)
	v_pk_add_f32 v[0:1], v[0:1], v[2:3]
	ds_bpermute_b32 v3, v175, v1
	ds_bpermute_b32 v2, v175, v0
	v_cndmask_b32_e32 v4, v128, v4, vcc
	v_rsq_f32_e32 v4, v4
	v_pk_mul_f32 v[62:63], v[112:113], v[64:65] op_sel_hi:[1,0]
	v_pk_mul_f32 v[90:91], v[110:111], v[64:65] op_sel_hi:[1,0]
	s_waitcnt lgkmcnt(0)
	v_pk_add_f32 v[0:1], v[0:1], v[2:3]
	ds_bpermute_b32 v3, v176, v1
	ds_bpermute_b32 v2, v176, v0
	v_mul_f32_e32 v5, 0x45800000, v4
	v_cndmask_b32_e32 v4, v4, v5, vcc
	v_mul_f32_e32 v4, 0x3e000000, v4
	v_pk_mul_f32 v[96:97], v[108:109], v[64:65] op_sel_hi:[1,0]
	s_waitcnt lgkmcnt(0)
	v_pk_add_f32 v[0:1], v[0:1], v[2:3]
	v_pk_mul_f32 v[108:109], v[126:127], v[4:5] op_sel_hi:[1,0]
	v_pk_add_f32 v[0:1], v[0:1], s[68:69] op_sel_hi:[1,0]
	v_pk_mul_f32 v[110:111], v[120:121], v[4:5] op_sel_hi:[1,0]
	v_mul_f32_e32 v2, 0x4b800000, v1
	v_cmp_gt_f32_e32 vcc, s73, v1
	v_pk_mul_f32 v[112:113], v[118:119], v[4:5] op_sel_hi:[1,0]
	v_pk_mul_f32 v[114:115], v[116:117], v[4:5] op_sel_hi:[1,0]
	v_cndmask_b32_e32 v1, v1, v2, vcc
	v_rsq_f32_e32 v1, v1
	v_cvt_pk_bf16_f32 v6, v14, v15
	v_cvt_pk_bf16_f32 v7, v12, v13
	s_mov_b64 s[28:29], 0x4000
	v_mul_f32_e32 v2, 0x45800000, v1
	v_cndmask_b32_e32 v1, v1, v2, vcc
	v_mul_f32_e32 v4, 0x3e000000, v1
	v_mul_f32_e32 v1, 0x4b800000, v0
	v_cmp_gt_f32_e32 vcc, s73, v0
	v_pk_mul_f32 v[92:93], v[92:93], v[4:5] op_sel_hi:[1,0]
	v_pk_mul_f32 v[58:59], v[58:59], v[4:5] op_sel_hi:[1,0]
	v_cndmask_b32_e32 v0, v0, v1, vcc
	v_rsq_f32_e32 v64, v0
	v_pk_mul_f32 v[2:3], v[98:99], v[4:5] op_sel_hi:[1,0]
	v_pk_mul_f32 v[0:1], v[100:101], v[4:5] op_sel_hi:[1,0]
	v_cvt_pk_bf16_f32 v4, v22, v23
	v_cvt_pk_bf16_f32 v5, v20, v21
	ds_write_b128 v211, v[4:7] offset:9216
	ds_read_b32 v5, v177 offset:18432
	v_mul_f32_e32 v71, 0x45800000, v64
	v_cndmask_b32_e32 v4, v64, v71, vcc
	v_mul_f32_e32 v4, 0x3e000000, v4
	v_lshl_add_u64 v[36:37], v[36:37], 0, s[28:29]
	s_waitcnt lgkmcnt(0)
; #define GAS __attribute__((address_space(1)))
; #define LAS __attribute__((address_space(3)))
; __device__ __forceinline__ v4u pk8(const float (&a)[8], const float s) { return (v4u){pk2(a[0] * s, a[1] * s), pk2(a[2] * s, a[3] * s), pk2(a[4] * s, a[5] * s), pk2(a[6] * s, a[7] * s)}; }
; __device__ __forceinline__ void strip_mm(f32x4 (&acc)[4], const LAS unsigned char* A, const LAS unsigned char* Bt, const int r0, const int lane) {
;     const int c16 = lane & 15, q4 = lane >> 4; bf16x8 a[2], b[2][4];
; #pragma unroll
;     for (int ks = 0; ks < 2; ++ks) { a[ks] = *(const LAS bf16x8*)(A + (r0 + c16) * STRB + (32 * ks + 8 * q4) * 2);
; #pragma unroll
;         for (int tn = 0; tn < 4; ++tn) b[ks][tn] = *(const LAS bf16x8*)(Bt + (16 * tn + c16) * STRB + (32 * ks + 8 * q4) * 2); }
; __device__ __forceinline__ void intra_item(Frame& F, const int item, LAS unsigned char* SA, LAS unsigned char* SB, LAS float* GC, LAS float* BT) {
;     ...
; #pragma unroll
;     for (int r = 0; r < 8; ++r) { const int c = 8 * rg + r; *(LAS v4u*)(SB + c * STRB + cg * 16) = pk8(o[r], 1.f); *(GAS v4u*)(gi + 2 * 8192 + c * 128 + cg * 16) = pk8(o[r], __expf(GC[c])); }
; #pragma unroll 1
;     for (int st = 0; st < 4; ++st) { f32x4 acc[4]; zero4(acc); strip_mm(acc, SA, SB, 16 * st, lane);
	v_pk_mul_f32 v[34:35], v[34:35], v[4:5] op_sel_hi:[1,0]
	v_pk_mul_f32 v[60:61], v[60:61], v[4:5] op_sel_hi:[1,0]
	v_mul_f32_e32 v5, 0x3fb8aa3b, v5
	v_exp_f32_e32 v64, v5
	v_pk_mul_f32 v[54:55], v[54:55], v[4:5] op_sel_hi:[1,0]
	v_pk_mul_f32 v[94:95], v[94:95], v[4:5] op_sel_hi:[1,0]
	v_ashrrev_i32_e32 v69, 4, v88
	v_pk_mul_f32 v[4:5], v[22:23], v[64:65] op_sel_hi:[1,0]
	v_pk_mul_f32 v[6:7], v[20:21], v[64:65] op_sel_hi:[1,0]
	v_cvt_pk_bf16_f32 v20, v16, v17
	v_cvt_pk_bf16_f32 v21, v18, v19
	v_cvt_pk_bf16_f32 v22, v10, v11
	v_cvt_pk_bf16_f32 v23, v8, v9
	ds_write_b128 v211, v[20:23] offset:9360
	ds_read_b32 v20, v177 offset:18436
	v_cvt_pk_bf16_f32 v4, v4, v5
	v_cvt_pk_bf16_f32 v5, v6, v7
	v_pk_mul_f32 v[6:7], v[14:15], v[64:65] op_sel_hi:[1,0]
	v_pk_mul_f32 v[12:13], v[12:13], v[64:65] op_sel_hi:[1,0]
	v_cvt_pk_bf16_f32 v6, v6, v7
	s_waitcnt lgkmcnt(0)
	v_mul_f32_e32 v7, 0x3fb8aa3b, v20
	v_exp_f32_e32 v20, v7
	v_cvt_pk_bf16_f32 v7, v12, v13
	v_lshl_add_u64 v[12:13], v[36:37], 0, v[38:39]
	global_store_dwordx4 v[12:13], v[4:7], off
	v_cvt_pk_bf16_f32 v12, v106, v107
	v_cvt_pk_bf16_f32 v13, v104, v105
	v_cvt_pk_bf16_f32 v14, v30, v31
	v_cvt_pk_bf16_f32 v15, v28, v29
	ds_write_b128 v211, v[12:15] offset:9504
	ds_read_b32 v12, v177 offset:18440
	v_pk_mul_f32 v[4:5], v[16:17], v[20:21] op_sel_hi:[1,0]
	v_pk_mul_f32 v[6:7], v[18:19], v[20:21] op_sel_hi:[1,0]
	v_cvt_pk_bf16_f32 v4, v4, v5
	v_cvt_pk_bf16_f32 v5, v6, v7
	v_pk_mul_f32 v[6:7], v[10:11], v[20:21] op_sel_hi:[1,0]
	v_pk_mul_f32 v[8:9], v[8:9], v[20:21] op_sel_hi:[1,0]
	v_cvt_pk_bf16_f32 v6, v6, v7
	s_waitcnt lgkmcnt(0)
	v_mul_f32_e32 v7, 0x3fb8aa3b, v12
	v_exp_f32_e32 v10, v7
	v_cvt_pk_bf16_f32 v7, v8, v9
	v_lshl_add_u64 v[8:9], v[36:37], 0, v[40:41]
	global_store_dwordx4 v[8:9], v[4:7], off
	v_cvt_pk_bf16_f32 v8, v26, v27
	v_cvt_pk_bf16_f32 v9, v24, v25
	v_cvt_pk_bf16_f32 v6, v32, v33
	v_cvt_pk_bf16_f32 v7, v102, v103
	ds_write_b128 v211, v[6:9] offset:9648
	v_pk_mul_f32 v[4:5], v[106:107], v[10:11] op_sel_hi:[1,0]
	v_pk_mul_f32 v[12:13], v[104:105], v[10:11] op_sel_hi:[1,0]
	ds_read_b32 v11, v177 offset:18444
	v_cvt_pk_bf16_f32 v4, v4, v5
	v_cvt_pk_bf16_f32 v5, v12, v13
	v_and_b32_e32 v67, 15, v88
	v_mul_u32_u24_e32 v213, 0x90, v67
	s_waitcnt lgkmcnt(0)
	v_pk_mul_f32 v[6:7], v[30:31], v[10:11] op_sel_hi:[1,0]
	v_pk_mul_f32 v[8:9], v[28:29], v[10:11] op_sel_hi:[1,0]
	v_cvt_pk_bf16_f32 v6, v6, v7
	v_mul_f32_e32 v7, 0x3fb8aa3b, v11
	v_exp_f32_e32 v10, v7
	v_cvt_pk_bf16_f32 v7, v8, v9
	v_lshl_add_u64 v[8:9], v[36:37], 0, v[42:43]
	global_store_dwordx4 v[8:9], v[4:7], off
	v_cvt_pk_bf16_f32 v8, v90, v91
	v_cvt_pk_bf16_f32 v9, v96, v97
	v_cvt_pk_bf16_f32 v6, v56, v57
	v_cvt_pk_bf16_f32 v7, v62, v63
	ds_write_b128 v211, v[6:9] offset:9792
	v_pk_mul_f32 v[4:5], v[32:33], v[10:11] op_sel_hi:[1,0]
	v_pk_mul_f32 v[12:13], v[102:103], v[10:11] op_sel_hi:[1,0]
	ds_read_b32 v11, v177 offset:18448
	v_cvt_pk_bf16_f32 v4, v4, v5
	v_cvt_pk_bf16_f32 v5, v12, v13
	v_and_b32_e32 v32, -16, v88
	v_lshlrev_b32_e32 v64, 7, v67
	s_waitcnt lgkmcnt(0)
	v_pk_mul_f32 v[6:7], v[26:27], v[10:11] op_sel_hi:[1,0]
	v_pk_mul_f32 v[8:9], v[24:25], v[10:11] op_sel_hi:[1,0]
	v_cvt_pk_bf16_f32 v6, v6, v7
	v_mul_f32_e32 v7, 0x3fb8aa3b, v11
	v_exp_f32_e32 v10, v7
	v_cvt_pk_bf16_f32 v7, v8, v9
	v_lshl_add_u64 v[8:9], v[36:37], 0, v[44:45]
	global_store_dwordx4 v[8:9], v[4:7], off
	v_cvt_pk_bf16_f32 v8, v112, v113
	v_cvt_pk_bf16_f32 v9, v114, v115
	v_cvt_pk_bf16_f32 v6, v108, v109
	v_cvt_pk_bf16_f32 v7, v110, v111
	ds_write_b128 v211, v[6:9] offset:9936
	v_pk_mul_f32 v[4:5], v[56:57], v[10:11] op_sel_hi:[1,0]
	v_pk_mul_f32 v[12:13], v[62:63], v[10:11] op_sel_hi:[1,0]
	ds_read_b32 v11, v177 offset:18452
	v_cvt_pk_bf16_f32 v4, v4, v5
	v_cvt_pk_bf16_f32 v5, v12, v13
	v_mad_u32_u24 v30, v67, s74, v32
	s_mov_b32 s36, 0
	s_waitcnt lgkmcnt(0)
	v_pk_mul_f32 v[6:7], v[90:91], v[10:11] op_sel_hi:[1,0]
	v_pk_mul_f32 v[8:9], v[96:97], v[10:11] op_sel_hi:[1,0]
	v_cvt_pk_bf16_f32 v6, v6, v7
	v_mul_f32_e32 v7, 0x3fb8aa3b, v11
	v_exp_f32_e32 v10, v7
	v_cvt_pk_bf16_f32 v7, v8, v9
	v_lshl_add_u64 v[8:9], v[36:37], 0, v[46:47]
	global_store_dwordx4 v[8:9], v[4:7], off
	v_cvt_pk_bf16_f32 v8, v2, v3
	v_cvt_pk_bf16_f32 v9, v0, v1
	v_cvt_pk_bf16_f32 v6, v92, v93
	v_cvt_pk_bf16_f32 v7, v58, v59
	ds_write_b128 v211, v[6:9] offset:10080
	v_pk_mul_f32 v[4:5], v[108:109], v[10:11] op_sel_hi:[1,0]
	v_pk_mul_f32 v[12:13], v[110:111], v[10:11] op_sel_hi:[1,0]
	ds_read_b32 v11, v177 offset:18456
	v_cvt_pk_bf16_f32 v4, v4, v5
	v_cvt_pk_bf16_f32 v5, v12, v13
	v_lshlrev_b32_e32 v90, 3, v69
	v_lshlrev_b32_e32 v22, 2, v69
	s_waitcnt lgkmcnt(0)
	v_pk_mul_f32 v[6:7], v[112:113], v[10:11] op_sel_hi:[1,0]
	v_pk_mul_f32 v[8:9], v[114:115], v[10:11] op_sel_hi:[1,0]
	v_cvt_pk_bf16_f32 v6, v6, v7
	v_mul_f32_e32 v7, 0x3fb8aa3b, v11
	v_exp_f32_e32 v10, v7
	v_cvt_pk_bf16_f32 v7, v8, v9
	v_lshl_add_u64 v[8:9], v[36:37], 0, v[48:49]
	global_store_dwordx4 v[8:9], v[4:7], off
	v_cvt_pk_bf16_f32 v8, v54, v55
	v_cvt_pk_bf16_f32 v9, v94, v95
	v_cvt_pk_bf16_f32 v6, v34, v35
	v_cvt_pk_bf16_f32 v7, v60, v61
	ds_write_b128 v212, v[6:9] offset:9216
	ds_read_b32 v7, v178 offset:18432
	v_pk_mul_f32 v[2:3], v[2:3], v[10:11] op_sel_hi:[1,0]
	v_pk_mul_f32 v[4:5], v[92:93], v[10:11] op_sel_hi:[1,0]
	v_cvt_pk_bf16_f32 v6, v2, v3
	v_pk_mul_f32 v[12:13], v[58:59], v[10:11] op_sel_hi:[1,0]
	s_waitcnt lgkmcnt(0)
	v_mul_f32_e32 v2, 0x3fb8aa3b, v7
	v_exp_f32_e32 v8, v2
	v_pk_mul_f32 v[0:1], v[0:1], v[10:11] op_sel_hi:[1,0]
	v_cvt_pk_bf16_f32 v4, v4, v5
	v_cvt_pk_bf16_f32 v5, v12, v13
	v_cvt_pk_bf16_f32 v7, v0, v1
	v_lshl_add_u64 v[0:1], v[36:37], 0, v[50:51]
	global_store_dwordx4 v[0:1], v[4:7], off
	v_pk_mul_f32 v[0:1], v[34:35], v[8:9] op_sel_hi:[1,0]
	v_pk_mul_f32 v[2:3], v[60:61], v[8:9] op_sel_hi:[1,0]
	v_cvt_pk_bf16_f32 v0, v0, v1
	v_cvt_pk_bf16_f32 v1, v2, v3
	v_pk_mul_f32 v[2:3], v[54:55], v[8:9] op_sel_hi:[1,0]
	v_pk_mul_f32 v[4:5], v[94:95], v[8:9] op_sel_hi:[1,0]
	v_cvt_pk_bf16_f32 v2, v2, v3
	v_cvt_pk_bf16_f32 v3, v4, v5
	v_lshl_add_u64 v[4:5], v[36:37], 0, v[52:53]
	global_store_dwordx4 v[4:5], v[0:3], off
	v_lshl_add_u32 v23, v67, 2, s31
	v_or_b32_e32 v24, 16, v67
	v_add_u32_e32 v0, s31, v32
	v_or_b32_e32 v25, 32, v67
	v_or_b32_e32 v26, 48, v67
	v_add_u32_e32 v28, s31, v30
	v_add_u32_e32 v29, s96, v32
	v_ashrrev_i32_e32 v91, 31, v90
	v_lshl_add_u64 v[16:17], s[52:53], 0, v[64:65]
	v_lshl_add_u64 v[18:19], s[56:57], 0, v[64:65]
	v_lshl_add_u64 v[20:21], s[58:59], 0, v[64:65]
	v_add_u32_e32 v27, v0, v213
	s_branch .LBB0_954

; #define GAS __attribute__((address_space(1)))
; __device__ __forceinline__ void prep_seg(const bf16_t* QK, const float* cw, const size_t rowbase, const int t0, const int h, const int seg, const int lane, float (&o)[8][8]) {
;     const int rg = lane >> 3, cg = lane & 7, col = seg * 512 + h * 64 + cg * 8;
;     float wt[4][8];
; #pragma unroll
;     for (int j = 0; j < 4; ++j) { const f32x4 a = *(const GAS f32x4*)(cw + j * CONVD + col), b = *(const GAS f32x4*)(cw + j * CONVD + col + 4); wt[j][0] = a.x; wt[j][1] = a.y; wt[j][2] = a.z; wt[j][3] = a.w; wt[j][4] = b.x; wt[j][5] = b.y; wt[j][6] = b.z; wt[j][7] = b.w; }
; #pragma unroll
;     for (int r = 0; r < 8; ++r)
; #pragma unroll
;         for (int e = 0; e < 8; ++e) o[r][e] = 0.f;
; #pragma unroll
;     for (int rr = 0; rr < 11; ++rr) { const int t = t0 + 8 * rg + rr - 3; float x[8];
;         if (t >= 0) unpack8(*(const GAS v4u*)(QK + (rowbase + t) * CONVD + col), x); else {
; #pragma unroll
;             for (int e = 0; e < 8; ++e) x[e] = 0.f; }
; __device__ __forceinline__ void intra_item(Frame& F, const int item, LAS unsigned char* SA, LAS unsigned char* SB, LAS float* GC, LAS float* BT) {
;     ...
;     prep_seg(QK, cw, rowbase, t0, h, 2, lane, o);
.LBB0_1046:
	v_or_b32_e32 v67, 0x400, v89
	v_lshlrev_b32_e32 v0, 2, v67
	v_mov_b32_e32 v1, v65
	v_lshl_add_u64 v[2:3], s[70:71], 0, v[0:1]
	v_add_co_u32_e32 v4, vcc, 0x1000, v2
	global_load_dwordx4 v[8:11], v0, s[70:71] offset:16
	global_load_dwordx4 v[20:23], v0, s[70:71]
	v_addc_co_u32_e32 v5, vcc, 0, v3, vcc
	v_lshl_add_u64 v[0:1], v[2:3], 0, s[44:45]
	global_load_dwordx4 v[16:19], v[4:5], off offset:2048
	global_load_dwordx4 v[12:15], v[0:1], off offset:16
	v_add_co_u32_e32 v4, vcc, 0x3000, v2
	v_lshl_add_u64 v[0:1], v[2:3], 0, s[48:49]
	s_nop 0
	v_addc_co_u32_e32 v5, vcc, 0, v3, vcc
	global_load_dwordx4 v[28:31], v[4:5], off
	global_load_dwordx4 v[24:27], v[0:1], off offset:16
	v_lshl_add_u64 v[0:1], v[2:3], 0, s[78:79]
	v_add_co_u32_e32 v2, vcc, 0x4000, v2
	v_mov_b32_e32 v88, 0
	s_nop 0
	v_addc_co_u32_e32 v3, vcc, 0, v3, vcc
	global_load_dwordx4 v[4:7], v[2:3], off offset:2048
	s_nop 0
	global_load_dwordx4 v[0:3], v[0:1], off offset:16
	v_lshlrev_b32_e32 v160, 1, v67
	v_mov_b32_e32 v124, 0
	v_mov_b32_e32 v125, 0
	v_mov_b32_e32 v126, 0
	v_mov_b32_e32 v127, 0
	v_mov_b32_e32 v128, 0
	v_mov_b32_e32 v129, 0
	v_mov_b32_e32 v130, 0
	v_mov_b32_e32 v131, 0
	v_mov_b32_e32 v204, 0
	v_mov_b32_e32 v205, 0
	v_mov_b32_e32 v206, 0
	v_mov_b32_e32 v207, 0
	s_and_saveexec_b64 s[26:27], s[0:1]
	v_mov_b32_e32 v69, v65
	v_lshl_add_u64 v[68:69], s[82:83], 0, v[68:69]
	v_mov_b64_e32 v[124:125], s[46:47]
	v_mad_u64_u32 v[124:125], s[0:1], v68, s72, v[124:125]
	v_mad_i32_i24 v125, v69, s72, v125
	v_mov_b32_e32 v161, v65
	v_lshl_add_u64 v[68:69], v[124:125], 0, v[160:161]
	global_load_dwordx4 v[204:207], v[68:69], off
.LBB0_1048:
	s_or_b64 exec, exec, s[26:27]
	v_mov_b32_e32 v89, 0
	v_mov_b32_e32 v68, 0
	v_mov_b32_e32 v69, 0
	v_mov_b32_e32 v132, 0
	v_mov_b32_e32 v133, 0
	v_mov_b32_e32 v134, 0
	v_mov_b32_e32 v135, 0
	v_mov_b32_e32 v220, 0
	v_mov_b32_e32 v221, 0
	v_mov_b32_e32 v222, 0
	v_mov_b32_e32 v223, 0
	s_and_saveexec_b64 s[0:1], s[2:3]
	v_mov_b32_e32 v71, v65
	v_lshl_add_u64 v[68:69], s[82:83], 0, v[70:71]
	v_mov_b64_e32 v[70:71], s[46:47]
	v_mad_u64_u32 v[70:71], s[2:3], v68, s72, v[70:71]
	v_mad_i32_i24 v71, v69, s72, v71
	v_mov_b32_e32 v161, v65
	v_lshl_add_u64 v[68:69], v[70:71], 0, v[160:161]
	global_load_dwordx4 v[220:223], v[68:69], off
.LBB0_1050:
	s_or_b64 exec, exec, s[0:1]
	v_mov_b32_e32 v136, 0
	v_mov_b32_e32 v138, 0
	v_mov_b32_e32 v139, 0
	v_mov_b32_e32 v140, 0
	v_mov_b32_e32 v141, 0
	v_mov_b32_e32 v142, 0
	v_mov_b32_e32 v143, 0
	v_mov_b32_e32 v144, 0
	v_mov_b32_e32 v145, 0
	v_mov_b32_e32 v224, 0
	v_mov_b32_e32 v225, 0
	v_mov_b32_e32 v226, 0
	v_mov_b32_e32 v227, 0
	s_and_saveexec_b64 s[0:1], s[4:5]
	v_mov_b32_e32 v73, v65
	v_lshl_add_u64 v[70:71], s[82:83], 0, v[72:73]
	v_mov_b64_e32 v[72:73], s[46:47]
	v_mad_u64_u32 v[72:73], s[2:3], v70, s72, v[72:73]
	v_mad_i32_i24 v73, v71, s72, v73
	v_mov_b32_e32 v161, v65
	v_lshl_add_u64 v[70:71], v[72:73], 0, v[160:161]
	global_load_dwordx4 v[224:227], v[70:71], off
.LBB0_1052:
	s_or_b64 exec, exec, s[0:1]
	v_mov_b32_e32 v137, 0
	v_mov_b32_e32 v146, 0
	v_mov_b32_e32 v147, 0
	v_mov_b32_e32 v148, 0
	v_mov_b32_e32 v149, 0
	v_mov_b32_e32 v150, 0
	v_mov_b32_e32 v151, 0
	v_mov_b32_e32 v228, 0
	v_mov_b32_e32 v229, 0
	v_mov_b32_e32 v230, 0
	v_mov_b32_e32 v231, 0
	s_and_saveexec_b64 s[0:1], s[6:7]
	v_mov_b32_e32 v67, v65
	v_lshl_add_u64 v[66:67], s[82:83], 0, v[66:67]
	v_mov_b64_e32 v[70:71], s[46:47]
	v_mad_u64_u32 v[70:71], s[2:3], v66, s72, v[70:71]
	v_mad_i32_i24 v71, v67, s72, v71
	v_mov_b32_e32 v161, v65
	v_lshl_add_u64 v[66:67], v[70:71], 0, v[160:161]
	global_load_dwordx4 v[228:231], v[66:67], off
.LBB0_1054:
	s_or_b64 exec, exec, s[0:1]
	v_mov_b32_e32 v162, 0
	v_mov_b32_e32 v152, 0
	v_mov_b32_e32 v153, 0
	v_mov_b32_e32 v154, 0
	v_mov_b32_e32 v155, 0
	v_mov_b32_e32 v156, 0
	v_mov_b32_e32 v157, 0
	v_mov_b32_e32 v158, 0
	v_mov_b32_e32 v159, 0
	v_mov_b32_e32 v232, 0
	v_mov_b32_e32 v233, 0
	v_mov_b32_e32 v234, 0
	v_mov_b32_e32 v235, 0
	s_and_saveexec_b64 s[0:1], s[8:9]
	v_mov_b32_e32 v75, v65
	v_lshl_add_u64 v[66:67], s[82:83], 0, v[74:75]
	v_mov_b64_e32 v[70:71], s[46:47]
	v_mad_u64_u32 v[70:71], s[2:3], v66, s72, v[70:71]
	v_mad_i32_i24 v71, v67, s72, v71
	v_mov_b32_e32 v161, v65
	v_lshl_add_u64 v[66:67], v[70:71], 0, v[160:161]
	global_load_dwordx4 v[232:235], v[66:67], off
.LBB0_1056:
	s_or_b64 exec, exec, s[0:1]
	v_mov_b32_e32 v163, 0
	v_mov_b32_e32 v166, 0
	v_mov_b32_e32 v167, 0
	v_mov_b32_e32 v168, 0
	v_mov_b32_e32 v169, 0
	v_mov_b32_e32 v170, 0
	v_mov_b32_e32 v171, 0
	v_mov_b32_e32 v236, 0
	v_mov_b32_e32 v237, 0
	v_mov_b32_e32 v238, 0
	v_mov_b32_e32 v239, 0
	s_and_saveexec_b64 s[0:1], s[10:11]
	v_mov_b32_e32 v77, v65
	v_lshl_add_u64 v[66:67], s[82:83], 0, v[76:77]
	v_mov_b64_e32 v[70:71], s[46:47]
	v_mad_u64_u32 v[70:71], s[2:3], v66, s72, v[70:71]
	v_mad_i32_i24 v71, v67, s72, v71
	v_mov_b32_e32 v161, v65
	v_lshl_add_u64 v[66:67], v[70:71], 0, v[160:161]
	global_load_dwordx4 v[236:239], v[66:67], off
; #define GAS __attribute__((address_space(1)))
; __device__ __forceinline__ void prep_seg(const bf16_t* QK, const float* cw, const size_t rowbase, const int t0, const int h, const int seg, const int lane, float (&o)[8][8]) {
;     ...
;     for (int rr = 0; rr < 11; ++rr) { const int t = t0 + 8 * rg + rr - 3; float x[8];
;         if (t >= 0) unpack8(*(const GAS v4u*)(QK + (rowbase + t) * CONVD + col), x); else {
; #pragma unroll
;             for (int e = 0; e < 8; ++e) x[e] = 0.f; }
.LBB0_1058:
	s_or_b64 exec, exec, s[0:1]
	s_waitcnt vmcnt(5)
	v_lshlrev_b32_e32 v124, 16, v204
	v_and_b32_e32 v125, 0xffff0000, v204
	v_lshlrev_b32_e32 v126, 16, v205
	v_and_b32_e32 v127, 0xffff0000, v205
	v_lshlrev_b32_e32 v128, 16, v206
	v_and_b32_e32 v129, 0xffff0000, v206
	v_lshlrev_b32_e32 v130, 16, v207
	v_and_b32_e32 v131, 0xffff0000, v207
	s_waitcnt vmcnt(4)
	v_lshlrev_b32_e32 v88, 16, v220
	v_and_b32_e32 v89, 0xffff0000, v220
	v_lshlrev_b32_e32 v68, 16, v221
	v_and_b32_e32 v69, 0xffff0000, v221
	v_lshlrev_b32_e32 v132, 16, v222
	v_and_b32_e32 v133, 0xffff0000, v222
	v_lshlrev_b32_e32 v134, 16, v223
	v_and_b32_e32 v135, 0xffff0000, v223
	s_waitcnt vmcnt(3)
	v_lshlrev_b32_e32 v138, 16, v224
	v_and_b32_e32 v139, 0xffff0000, v224
	v_lshlrev_b32_e32 v140, 16, v225
	v_and_b32_e32 v141, 0xffff0000, v225
	v_lshlrev_b32_e32 v142, 16, v226
	v_and_b32_e32 v143, 0xffff0000, v226
	v_lshlrev_b32_e32 v144, 16, v227
	v_and_b32_e32 v145, 0xffff0000, v227
	s_waitcnt vmcnt(2)
	v_lshlrev_b32_e32 v136, 16, v228
	v_and_b32_e32 v137, 0xffff0000, v228
	v_lshlrev_b32_e32 v146, 16, v229
	v_and_b32_e32 v147, 0xffff0000, v229
	v_lshlrev_b32_e32 v148, 16, v230
	v_and_b32_e32 v149, 0xffff0000, v230
	v_lshlrev_b32_e32 v150, 16, v231
	v_and_b32_e32 v151, 0xffff0000, v231
	s_waitcnt vmcnt(1)
	v_lshlrev_b32_e32 v152, 16, v232
	v_and_b32_e32 v153, 0xffff0000, v232
	v_lshlrev_b32_e32 v154, 16, v233
	v_and_b32_e32 v155, 0xffff0000, v233
	v_lshlrev_b32_e32 v156, 16, v234
	v_and_b32_e32 v157, 0xffff0000, v234
	v_lshlrev_b32_e32 v158, 16, v235
	v_and_b32_e32 v159, 0xffff0000, v235
	s_waitcnt vmcnt(0)
	v_lshlrev_b32_e32 v162, 16, v236
	v_and_b32_e32 v163, 0xffff0000, v236
	v_lshlrev_b32_e32 v166, 16, v237
	v_and_b32_e32 v167, 0xffff0000, v237
	v_lshlrev_b32_e32 v168, 16, v238
	v_and_b32_e32 v169, 0xffff0000, v238
	v_lshlrev_b32_e32 v170, 16, v239
	v_and_b32_e32 v171, 0xffff0000, v239
	v_mov_b32_e32 v188, 0
	v_mov_b32_e32 v180, 0
	v_mov_b32_e32 v181, 0
	v_mov_b32_e32 v182, 0
	v_mov_b32_e32 v183, 0
	v_mov_b32_e32 v184, 0
	v_mov_b32_e32 v185, 0
	v_mov_b32_e32 v186, 0
	v_mov_b32_e32 v187, 0
	v_mov_b32_e32 v204, 0
	v_mov_b32_e32 v205, 0
	v_mov_b32_e32 v206, 0
	v_mov_b32_e32 v207, 0
	s_and_saveexec_b64 s[0:1], s[12:13]
	v_mov_b32_e32 v79, v65
	v_lshl_add_u64 v[66:67], s[82:83], 0, v[78:79]
	v_mov_b64_e32 v[70:71], s[46:47]
	v_mad_u64_u32 v[70:71], s[2:3], v66, s72, v[70:71]
	v_mad_i32_i24 v71, v67, s72, v71
	v_mov_b32_e32 v161, v65
	v_lshl_add_u64 v[66:67], v[70:71], 0, v[160:161]
	global_load_dwordx4 v[204:207], v[66:67], off
.LBB0_1060:
	s_or_b64 exec, exec, s[0:1]
	v_mov_b32_e32 v189, 0
	v_mov_b32_e32 v190, 0
	v_mov_b32_e32 v191, 0
	v_mov_b32_e32 v196, 0
	v_mov_b32_e32 v197, 0
	v_mov_b32_e32 v198, 0
	v_mov_b32_e32 v199, 0
	v_mov_b32_e32 v220, 0
	v_mov_b32_e32 v221, 0
	v_mov_b32_e32 v222, 0
	v_mov_b32_e32 v223, 0
	s_and_saveexec_b64 s[0:1], s[14:15]
	v_mov_b32_e32 v81, v65
	v_lshl_add_u64 v[66:67], s[82:83], 0, v[80:81]
	v_mov_b64_e32 v[70:71], s[46:47]
	v_mad_u64_u32 v[70:71], s[2:3], v66, s72, v[70:71]
	v_mad_i32_i24 v71, v67, s72, v71
	v_mov_b32_e32 v161, v65
	v_lshl_add_u64 v[66:67], v[70:71], 0, v[160:161]
	global_load_dwordx4 v[220:223], v[66:67], off
.LBB0_1062:
	s_or_b64 exec, exec, s[0:1]
	v_mov_b32_e32 v164, 0
	v_mov_b32_e32 v172, 0
	v_mov_b32_e32 v173, 0
	v_mov_b32_e32 v174, 0
	v_mov_b32_e32 v175, 0
	v_mov_b32_e32 v192, 0
	v_mov_b32_e32 v193, 0
	v_mov_b32_e32 v194, 0
	v_mov_b32_e32 v195, 0
	v_mov_b32_e32 v224, 0
	v_mov_b32_e32 v225, 0
	v_mov_b32_e32 v226, 0
	v_mov_b32_e32 v227, 0
	s_and_saveexec_b64 s[0:1], s[16:17]
	v_mov_b32_e32 v83, v65
	v_lshl_add_u64 v[66:67], s[82:83], 0, v[82:83]
	v_mov_b64_e32 v[70:71], s[46:47]
	v_mad_u64_u32 v[70:71], s[2:3], v66, s72, v[70:71]
	v_mad_i32_i24 v71, v67, s72, v71
	v_mov_b32_e32 v161, v65
	v_lshl_add_u64 v[66:67], v[70:71], 0, v[160:161]
	global_load_dwordx4 v[224:227], v[66:67], off
.LBB0_1064:
	s_or_b64 exec, exec, s[0:1]
	v_mov_b32_e32 v165, 0
	v_mov_b32_e32 v176, 0
	v_mov_b32_e32 v177, 0
	v_mov_b32_e32 v178, 0
	v_mov_b32_e32 v179, 0
	v_mov_b32_e32 v200, 0
	v_mov_b32_e32 v201, 0
	v_mov_b32_e32 v228, 0
	v_mov_b32_e32 v229, 0
	v_mov_b32_e32 v230, 0
	v_mov_b32_e32 v231, 0
	s_and_saveexec_b64 s[0:1], s[18:19]
	v_mov_b32_e32 v85, v65
	v_lshl_add_u64 v[66:67], s[82:83], 0, v[84:85]
	v_mov_b64_e32 v[70:71], s[46:47]
	v_mad_u64_u32 v[70:71], s[2:3], v66, s72, v[70:71]
	v_mad_i32_i24 v71, v67, s72, v71
	v_mov_b32_e32 v161, v65
	v_lshl_add_u64 v[66:67], v[70:71], 0, v[160:161]
	global_load_dwordx4 v[228:231], v[66:67], off
.LBB0_1066:
	s_or_b64 exec, exec, s[0:1]
	v_mov_b32_e32 v74, 0
	v_mov_b32_e32 v75, 0
	v_mov_b32_e32 v72, 0
	v_mov_b32_e32 v73, 0
	v_mov_b32_e32 v70, 0
	v_mov_b32_e32 v71, 0
	v_mov_b32_e32 v66, 0
	v_mov_b32_e32 v67, 0
	v_mov_b32_e32 v232, 0
	v_mov_b32_e32 v233, 0
	v_mov_b32_e32 v234, 0
	v_mov_b32_e32 v235, 0
	s_and_saveexec_b64 s[0:1], s[20:21]
	v_mov_b32_e32 v87, v65
	v_lshl_add_u64 v[66:67], s[82:83], 0, v[86:87]
	v_mov_b64_e32 v[70:71], s[46:47]
	v_mad_u64_u32 v[70:71], s[2:3], v66, s72, v[70:71]
	v_mad_i32_i24 v71, v67, s72, v71
	v_mov_b32_e32 v161, v65
	v_lshl_add_u64 v[66:67], v[70:71], 0, v[160:161]
	global_load_dwordx4 v[232:235], v[66:67], off
; #define GAS __attribute__((address_space(1)))
; __device__ __forceinline__ void prep_seg(const bf16_t* QK, const float* cw, const size_t rowbase, const int t0, const int h, const int seg, const int lane, float (&o)[8][8]) {
;     ...
;     for (int rr = 0; rr < 11; ++rr) { const int t = t0 + 8 * rg + rr - 3; float x[8];
;         if (t >= 0) unpack8(*(const GAS v4u*)(QK + (rowbase + t) * CONVD + col), x); else {
; #pragma unroll
;             for (int e = 0; e < 8; ++e) x[e] = 0.f; }
; #pragma unroll
;         for (int j = 0; j < 4; ++j) { const int r = rr - j;
;             if (r >= 0 && r < 8) {
; #pragma unroll
;                 for (int e = 0; e < 8; ++e) o[r][e] += wt[j][e] * x[e]; } } }
.LBB0_1068:
	s_or_b64 exec, exec, s[0:1]
	s_waitcnt vmcnt(4)
	v_lshlrev_b32_e32 v180, 16, v204
	v_and_b32_e32 v181, 0xffff0000, v204
	v_lshlrev_b32_e32 v182, 16, v205
	v_and_b32_e32 v183, 0xffff0000, v205
	v_lshlrev_b32_e32 v184, 16, v206
	v_and_b32_e32 v185, 0xffff0000, v206
	v_lshlrev_b32_e32 v186, 16, v207
	v_and_b32_e32 v187, 0xffff0000, v207
	s_waitcnt vmcnt(3)
	v_lshlrev_b32_e32 v188, 16, v220
	v_and_b32_e32 v189, 0xffff0000, v220
	v_lshlrev_b32_e32 v190, 16, v221
	v_and_b32_e32 v191, 0xffff0000, v221
	v_lshlrev_b32_e32 v196, 16, v222
	v_and_b32_e32 v197, 0xffff0000, v222
	v_lshlrev_b32_e32 v198, 16, v223
	v_and_b32_e32 v199, 0xffff0000, v223
	s_waitcnt vmcnt(2)
	v_lshlrev_b32_e32 v172, 16, v224
	v_and_b32_e32 v173, 0xffff0000, v224
	v_lshlrev_b32_e32 v174, 16, v225
	v_and_b32_e32 v175, 0xffff0000, v225
	v_lshlrev_b32_e32 v192, 16, v226
	v_and_b32_e32 v193, 0xffff0000, v226
	v_lshlrev_b32_e32 v194, 16, v227
	v_and_b32_e32 v195, 0xffff0000, v227
	s_waitcnt vmcnt(1)
	v_lshlrev_b32_e32 v164, 16, v228
	v_and_b32_e32 v165, 0xffff0000, v228
	v_lshlrev_b32_e32 v176, 16, v229
	v_and_b32_e32 v177, 0xffff0000, v229
	v_lshlrev_b32_e32 v178, 16, v230
	v_and_b32_e32 v179, 0xffff0000, v230
	v_lshlrev_b32_e32 v200, 16, v231
	v_and_b32_e32 v201, 0xffff0000, v231
	s_waitcnt vmcnt(0)
	v_lshlrev_b32_e32 v74, 16, v232
	v_and_b32_e32 v75, 0xffff0000, v232
	v_lshlrev_b32_e32 v72, 16, v233
	v_and_b32_e32 v73, 0xffff0000, v233
	v_lshlrev_b32_e32 v70, 16, v234
	v_and_b32_e32 v71, 0xffff0000, v234
	v_lshlrev_b32_e32 v66, 16, v235
	v_and_b32_e32 v67, 0xffff0000, v235
	s_waitcnt vmcnt(6)
	v_pk_fma_f32 v[78:79], v[22:23], v[182:183], 0 op_sel_hi:[1,1,0]
	v_pk_fma_f32 v[80:81], v[8:9], v[184:185], 0 op_sel_hi:[1,1,0]
	v_pk_fma_f32 v[82:83], v[10:11], v[186:187], 0 op_sel_hi:[1,1,0]
	v_pk_fma_f32 v[76:77], v[20:21], v[180:181], 0 op_sel_hi:[1,1,0]
	v_pk_fma_f32 v[84:85], v[20:21], v[188:189], 0 op_sel_hi:[1,1,0]
	v_pk_fma_f32 v[86:87], v[22:23], v[190:191], 0 op_sel_hi:[1,1,0]
	v_pk_fma_f32 v[160:161], v[8:9], v[196:197], 0 op_sel_hi:[1,1,0]
	v_pk_fma_f32 v[204:205], v[10:11], v[198:199], 0 op_sel_hi:[1,1,0]
	s_waitcnt vmcnt(5)
	v_pk_fma_f32 v[78:79], v[18:19], v[190:191], v[78:79]
	s_waitcnt vmcnt(4)
	v_pk_fma_f32 v[80:81], v[12:13], v[196:197], v[80:81]
	v_pk_fma_f32 v[82:83], v[14:15], v[198:199], v[82:83]
	v_pk_fma_f32 v[76:77], v[16:17], v[188:189], v[76:77]
	v_pk_fma_f32 v[84:85], v[16:17], v[172:173], v[84:85]
	v_pk_fma_f32 v[86:87], v[18:19], v[174:175], v[86:87]
	v_pk_fma_f32 v[160:161], v[12:13], v[192:193], v[160:161]
	v_pk_fma_f32 v[204:205], v[14:15], v[194:195], v[204:205]
	s_waitcnt vmcnt(3)
	v_pk_fma_f32 v[220:221], v[30:31], v[174:175], v[78:79]
	s_waitcnt vmcnt(2)
	v_pk_fma_f32 v[222:223], v[24:25], v[192:193], v[80:81]
	v_pk_fma_f32 v[224:225], v[26:27], v[194:195], v[82:83]
	v_pk_fma_f32 v[206:207], v[28:29], v[172:173], v[76:77]
	v_pk_fma_f32 v[82:83], v[28:29], v[164:165], v[84:85]
	v_pk_fma_f32 v[80:81], v[30:31], v[176:177], v[86:87]
	v_pk_fma_f32 v[78:79], v[24:25], v[178:179], v[160:161]
	v_pk_fma_f32 v[76:77], v[26:27], v[200:201], v[204:205]
	s_waitcnt vmcnt(1)
	v_pk_fma_f32 v[160:161], v[6:7], v[176:177], v[220:221]
	s_waitcnt vmcnt(0)
	v_pk_fma_f32 v[86:87], v[0:1], v[178:179], v[222:223]
	v_pk_fma_f32 v[84:85], v[2:3], v[200:201], v[224:225]
	v_pk_fma_f32 v[176:177], v[20:21], v[162:163], 0 op_sel_hi:[1,1,0]
	v_pk_fma_f32 v[178:179], v[22:23], v[166:167], 0 op_sel_hi:[1,1,0]
	v_pk_fma_f32 v[200:201], v[8:9], v[168:169], 0 op_sel_hi:[1,1,0]
	v_pk_fma_f32 v[204:205], v[10:11], v[170:171], 0 op_sel_hi:[1,1,0]
	v_pk_fma_f32 v[176:177], v[16:17], v[180:181], v[176:177]
	v_pk_fma_f32 v[178:179], v[18:19], v[182:183], v[178:179]
	v_pk_fma_f32 v[200:201], v[12:13], v[184:185], v[200:201]
	v_pk_fma_f32 v[204:205], v[14:15], v[186:187], v[204:205]
	v_pk_fma_f32 v[164:165], v[4:5], v[164:165], v[206:207]
	v_pk_fma_f32 v[176:177], v[28:29], v[188:189], v[176:177]
	v_pk_fma_f32 v[206:207], v[30:31], v[190:191], v[178:179]
	v_pk_fma_f32 v[200:201], v[24:25], v[196:197], v[200:201]
	v_pk_fma_f32 v[204:205], v[26:27], v[198:199], v[204:205]
	v_pk_fma_f32 v[178:179], v[4:5], v[172:173], v[176:177]
	v_pk_fma_f32 v[176:177], v[6:7], v[174:175], v[206:207]
	v_pk_fma_f32 v[174:175], v[0:1], v[192:193], v[200:201]
	v_pk_fma_f32 v[172:173], v[2:3], v[194:195], v[204:205]
	v_pk_fma_f32 v[192:193], v[20:21], v[152:153], 0 op_sel_hi:[1,1,0]
	v_pk_fma_f32 v[194:195], v[22:23], v[154:155], 0 op_sel_hi:[1,1,0]
	v_pk_fma_f32 v[200:201], v[8:9], v[156:157], 0 op_sel_hi:[1,1,0]
	v_pk_fma_f32 v[204:205], v[10:11], v[158:159], 0 op_sel_hi:[1,1,0]
	v_pk_fma_f32 v[192:193], v[16:17], v[162:163], v[192:193]
	v_pk_fma_f32 v[194:195], v[18:19], v[166:167], v[194:195]
	v_pk_fma_f32 v[200:201], v[12:13], v[168:169], v[200:201]
	v_pk_fma_f32 v[204:205], v[14:15], v[170:171], v[204:205]
	v_pk_fma_f32 v[192:193], v[28:29], v[180:181], v[192:193]
	v_pk_fma_f32 v[206:207], v[30:31], v[182:183], v[194:195]
	v_pk_fma_f32 v[200:201], v[24:25], v[184:185], v[200:201]
	v_pk_fma_f32 v[204:205], v[26:27], v[186:187], v[204:205]
	v_pk_fma_f32 v[194:195], v[4:5], v[188:189], v[192:193]
	v_pk_fma_f32 v[192:193], v[6:7], v[190:191], v[206:207]
	v_pk_fma_f32 v[190:191], v[0:1], v[196:197], v[200:201]
	v_pk_fma_f32 v[188:189], v[2:3], v[198:199], v[204:205]
	v_pk_fma_f32 v[196:197], v[20:21], v[136:137], 0 op_sel_hi:[1,1,0]
	v_pk_fma_f32 v[198:199], v[22:23], v[146:147], 0 op_sel_hi:[1,1,0]
	v_pk_fma_f32 v[200:201], v[8:9], v[148:149], 0 op_sel_hi:[1,1,0]
	v_pk_fma_f32 v[204:205], v[10:11], v[150:151], 0 op_sel_hi:[1,1,0]
	v_pk_fma_f32 v[196:197], v[16:17], v[152:153], v[196:197]
; __device__ __forceinline__ float silu_f(float x) { return x * __builtin_amdgcn_rcpf(1.f + __builtin_amdgcn_exp2f(-1.4426950408889634f * x)); }
; #define GAS __attribute__((address_space(1)))
; __device__ __forceinline__ void prep_seg(const bf16_t* QK, const float* cw, const size_t rowbase, const int t0, const int h, const int seg, const int lane, float (&o)[8][8]) {
;     ...
;     for (int rr = 0; rr < 11; ++rr) { const int t = t0 + 8 * rg + rr - 3; float x[8];
;         if (t >= 0) unpack8(*(const GAS v4u*)(QK + (rowbase + t) * CONVD + col), x); else {
; #pragma unroll
;             for (int e = 0; e < 8; ++e) x[e] = 0.f; }
; #pragma unroll
;         for (int j = 0; j < 4; ++j) { const int r = rr - j;
;             if (r >= 0 && r < 8) {
; #pragma unroll
;                 for (int e = 0; e < 8; ++e) o[r][e] += wt[j][e] * x[e]; } } }
; #pragma unroll
;     for (int r = 0; r < 8; ++r) { float ss = 0.f;
; #pragma unroll
;         for (int e = 0; e < 8; ++e) { o[r][e] = silu_f(o[r][e]); ss += o[r][e] * o[r][e]; }
	v_pk_fma_f32 v[198:199], v[18:19], v[154:155], v[198:199]
	v_pk_fma_f32 v[200:201], v[12:13], v[156:157], v[200:201]
	v_pk_fma_f32 v[204:205], v[14:15], v[158:159], v[204:205]
	v_pk_fma_f32 v[196:197], v[28:29], v[162:163], v[196:197]
	v_pk_fma_f32 v[206:207], v[30:31], v[166:167], v[198:199]
	v_pk_fma_f32 v[200:201], v[24:25], v[168:169], v[200:201]
	v_pk_fma_f32 v[204:205], v[26:27], v[170:171], v[204:205]
	v_pk_fma_f32 v[198:199], v[4:5], v[180:181], v[196:197]
	v_pk_fma_f32 v[196:197], v[6:7], v[182:183], v[206:207]
	v_pk_fma_f32 v[182:183], v[0:1], v[184:185], v[200:201]
	v_pk_fma_f32 v[184:185], v[20:21], v[138:139], 0 op_sel_hi:[1,1,0]
	v_pk_fma_f32 v[180:181], v[2:3], v[186:187], v[204:205]
	v_pk_fma_f32 v[200:201], v[8:9], v[142:143], 0 op_sel_hi:[1,1,0]
	v_pk_fma_f32 v[204:205], v[10:11], v[144:145], 0 op_sel_hi:[1,1,0]
	v_pk_fma_f32 v[184:185], v[16:17], v[136:137], v[184:185]
	v_pk_fma_f32 v[186:187], v[22:23], v[140:141], 0 op_sel_hi:[1,1,0]
	v_pk_fma_f32 v[200:201], v[12:13], v[148:149], v[200:201]
	v_pk_fma_f32 v[204:205], v[14:15], v[150:151], v[204:205]
	v_pk_fma_f32 v[184:185], v[28:29], v[152:153], v[184:185]
	v_pk_fma_f32 v[186:187], v[18:19], v[146:147], v[186:187]
	v_pk_fma_f32 v[200:201], v[24:25], v[156:157], v[200:201]
	v_pk_fma_f32 v[204:205], v[26:27], v[158:159], v[204:205]
	v_pk_fma_f32 v[162:163], v[4:5], v[162:163], v[184:185]
	v_pk_fma_f32 v[184:185], v[20:21], v[88:89], 0 op_sel_hi:[1,1,0]
	v_pk_fma_f32 v[20:21], v[20:21], v[124:125], 0 op_sel_hi:[1,1,0]
	v_pk_fma_f32 v[186:187], v[30:31], v[154:155], v[186:187]
	v_pk_fma_f32 v[168:169], v[0:1], v[168:169], v[200:201]
	v_pk_fma_f32 v[170:171], v[2:3], v[170:171], v[204:205]
	v_pk_fma_f32 v[200:201], v[8:9], v[132:133], 0 op_sel_hi:[1,1,0]
	v_pk_fma_f32 v[204:205], v[10:11], v[134:135], 0 op_sel_hi:[1,1,0]
	v_pk_fma_f32 v[184:185], v[16:17], v[138:139], v[184:185]
	v_pk_fma_f32 v[8:9], v[8:9], v[128:129], 0 op_sel_hi:[1,1,0]
	v_pk_fma_f32 v[10:11], v[10:11], v[130:131], 0 op_sel_hi:[1,1,0]
	v_pk_fma_f32 v[16:17], v[16:17], v[88:89], v[20:21]
	v_pk_fma_f32 v[166:167], v[6:7], v[166:167], v[186:187]
	v_pk_fma_f32 v[186:187], v[22:23], v[68:69], 0 op_sel_hi:[1,1,0]
	v_pk_fma_f32 v[200:201], v[12:13], v[142:143], v[200:201]
	v_pk_fma_f32 v[22:23], v[22:23], v[126:127], 0 op_sel_hi:[1,1,0]
	v_pk_fma_f32 v[8:9], v[12:13], v[132:133], v[8:9]
	v_pk_fma_f32 v[10:11], v[14:15], v[134:135], v[10:11]
	v_pk_fma_f32 v[12:13], v[28:29], v[138:139], v[16:17]
	v_pk_fma_f32 v[186:187], v[18:19], v[140:141], v[186:187]
	v_pk_fma_f32 v[18:19], v[18:19], v[68:69], v[22:23]
	v_pk_fma_f32 v[8:9], v[24:25], v[142:143], v[8:9]
	v_pk_fma_f32 v[10:11], v[26:27], v[144:145], v[10:11]
	v_pk_fma_f32 v[12:13], v[4:5], v[136:137], v[12:13]
	v_pk_fma_f32 v[204:205], v[14:15], v[144:145], v[204:205]
	v_pk_fma_f32 v[14:15], v[30:31], v[140:141], v[18:19]
	v_pk_fma_f32 v[16:17], v[0:1], v[148:149], v[8:9]
	v_pk_fma_f32 v[18:19], v[2:3], v[150:151], v[10:11]
	v_mul_f32_e32 v9, 0xbfb8aa3b, v12
	v_mul_f32_e32 v10, 0xbfb8aa3b, v13
	v_exp_f32_e32 v9, v9
	v_exp_f32_e32 v10, v10
	v_or_b32_e32 v8, v217, v218
	v_pk_fma_f32 v[14:15], v[6:7], v[146:147], v[14:15]
	v_mul_lo_u32 v8, v8, s74
	v_add_u32_e32 v91, s31, v8
	v_add_f32_e32 v8, 1.0, v9
	v_add_f32_e32 v9, 1.0, v10
	v_mul_f32_e32 v10, 0xbfb8aa3b, v14
	v_mul_f32_e32 v11, 0xbfb8aa3b, v15
	v_exp_f32_e32 v10, v10
	v_exp_f32_e32 v11, v11
	v_rcp_f32_e32 v8, v8
	v_rcp_f32_e32 v9, v9
	v_add_f32_e32 v10, 1.0, v10
	v_add_f32_e32 v11, 1.0, v11
	v_rcp_f32_e32 v10, v10
	v_rcp_f32_e32 v11, v11
	v_pk_mul_f32 v[8:9], v[12:13], v[8:9]
	v_mul_f32_e32 v12, 0xbfb8aa3b, v16
	v_mul_f32_e32 v13, 0xbfb8aa3b, v17
	v_pk_mul_f32 v[10:11], v[14:15], v[10:11]
	v_mul_f32_e32 v14, 0xbfb8aa3b, v18
	v_mul_f32_e32 v15, 0xbfb8aa3b, v19
	v_exp_f32_e32 v12, v12
	v_exp_f32_e32 v13, v13
	v_exp_f32_e32 v14, v14
	v_exp_f32_e32 v15, v15
	v_add_f32_e32 v12, 1.0, v12
	v_add_f32_e32 v13, 1.0, v13
	v_add_f32_e32 v14, 1.0, v14
	v_add_f32_e32 v15, 1.0, v15
	v_rcp_f32_e32 v12, v12
	v_rcp_f32_e32 v13, v13
	v_rcp_f32_e32 v14, v14
	v_rcp_f32_e32 v15, v15
	v_pk_fma_f32 v[184:185], v[28:29], v[136:137], v[184:185]
	v_pk_fma_f32 v[186:187], v[30:31], v[146:147], v[186:187]
	v_pk_fma_f32 v[200:201], v[24:25], v[148:149], v[200:201]
	v_pk_fma_f32 v[204:205], v[26:27], v[150:151], v[204:205]
	v_pk_fma_f32 v[152:153], v[4:5], v[152:153], v[184:185]
	v_pk_fma_f32 v[154:155], v[6:7], v[154:155], v[186:187]
	v_pk_fma_f32 v[156:157], v[0:1], v[156:157], v[200:201]
	v_pk_fma_f32 v[158:159], v[2:3], v[158:159], v[204:205]
	v_pk_fma_f32 v[0:1], v[0:1], v[70:71], v[78:79]
	v_pk_fma_f32 v[2:3], v[2:3], v[66:67], v[76:77]
	v_pk_mul_f32 v[12:13], v[16:17], v[12:13]
	v_mul_f32_e32 v16, 0xbfb8aa3b, v152
	v_mul_f32_e32 v17, 0xbfb8aa3b, v153
	v_pk_mul_f32 v[14:15], v[18:19], v[14:15]
	v_mul_f32_e32 v18, 0xbfb8aa3b, v154
	v_mul_f32_e32 v19, 0xbfb8aa3b, v155
	v_mul_f32_e32 v20, 0xbfb8aa3b, v156
	v_mul_f32_e32 v21, 0xbfb8aa3b, v157
	v_mul_f32_e32 v22, 0xbfb8aa3b, v158
	v_mul_f32_e32 v23, 0xbfb8aa3b, v159
	v_mul_f32_e32 v148, 0xbfb8aa3b, v86
	v_mul_f32_e32 v149, 0xbfb8aa3b, v87
	v_mul_f32_e32 v70, 0xbfb8aa3b, v0
	v_mul_f32_e32 v71, 0xbfb8aa3b, v1
	v_mul_f32_e32 v66, 0xbfb8aa3b, v2
	v_mul_f32_e32 v67, 0xbfb8aa3b, v3
	v_exp_f32_e32 v16, v16
	v_exp_f32_e32 v17, v17
	v_exp_f32_e32 v18, v18
	v_exp_f32_e32 v19, v19
	v_exp_f32_e32 v20, v20
	v_exp_f32_e32 v21, v21
	v_exp_f32_e32 v22, v22
	v_exp_f32_e32 v23, v23
	v_mul_f32_e32 v24, 0xbfb8aa3b, v162
	v_mul_f32_e32 v25, 0xbfb8aa3b, v163
	v_mul_f32_e32 v26, 0xbfb8aa3b, v166
	v_mul_f32_e32 v27, 0xbfb8aa3b, v167
	v_mul_f32_e32 v28, 0xbfb8aa3b, v168
	v_mul_f32_e32 v29, 0xbfb8aa3b, v169
; __device__ __forceinline__ float silu_f(float x) { return x * __builtin_amdgcn_rcpf(1.f + __builtin_amdgcn_exp2f(-1.4426950408889634f * x)); }
; __device__ __forceinline__ void prep_seg(const bf16_t* QK, const float* cw, const size_t rowbase, const int t0, const int h, const int seg, const int lane, float (&o)[8][8]) {
;     ...
;     for (int r = 0; r < 8; ++r) { float ss = 0.f;
; #pragma unroll
;         for (int e = 0; e < 8; ++e) { o[r][e] = silu_f(o[r][e]); ss += o[r][e] * o[r][e]; }
	v_mul_f32_e32 v30, 0xbfb8aa3b, v170
	v_mul_f32_e32 v31, 0xbfb8aa3b, v171
	v_exp_f32_e32 v148, v148
	v_exp_f32_e32 v149, v149
	v_exp_f32_e32 v70, v70
	v_exp_f32_e32 v71, v71
	v_exp_f32_e32 v66, v66
	v_exp_f32_e32 v67, v67
	v_exp_f32_e32 v24, v24
	v_exp_f32_e32 v25, v25
	v_exp_f32_e32 v26, v26
	v_exp_f32_e32 v27, v27
	v_exp_f32_e32 v28, v28
	v_exp_f32_e32 v29, v29
	v_exp_f32_e32 v30, v30
	v_exp_f32_e32 v31, v31
	v_mul_f32_e32 v68, 0xbfb8aa3b, v198
	v_mul_f32_e32 v69, 0xbfb8aa3b, v199
	v_mul_f32_e32 v88, 0xbfb8aa3b, v196
	v_mul_f32_e32 v89, 0xbfb8aa3b, v197
	v_mul_f32_e32 v124, 0xbfb8aa3b, v182
	v_mul_f32_e32 v125, 0xbfb8aa3b, v183
	v_mul_f32_e32 v126, 0xbfb8aa3b, v180
	v_mul_f32_e32 v127, 0xbfb8aa3b, v181
	v_exp_f32_e32 v68, v68
	v_exp_f32_e32 v69, v69
	v_exp_f32_e32 v88, v88
	v_exp_f32_e32 v89, v89
	v_exp_f32_e32 v124, v124
	v_exp_f32_e32 v125, v125
	v_exp_f32_e32 v126, v126
	v_exp_f32_e32 v127, v127
	v_mul_f32_e32 v128, 0xbfb8aa3b, v194
	v_mul_f32_e32 v129, 0xbfb8aa3b, v195
	v_mul_f32_e32 v130, 0xbfb8aa3b, v192
	v_mul_f32_e32 v131, 0xbfb8aa3b, v193
	v_mul_f32_e32 v132, 0xbfb8aa3b, v190
	v_mul_f32_e32 v133, 0xbfb8aa3b, v191
	v_mul_f32_e32 v134, 0xbfb8aa3b, v188
	v_mul_f32_e32 v135, 0xbfb8aa3b, v189
	v_exp_f32_e32 v128, v128
	v_exp_f32_e32 v129, v129
	v_exp_f32_e32 v130, v130
	v_exp_f32_e32 v131, v131
	v_exp_f32_e32 v132, v132
	v_exp_f32_e32 v133, v133
	v_exp_f32_e32 v134, v134
	v_exp_f32_e32 v135, v135
	v_mul_f32_e32 v136, 0xbfb8aa3b, v178
	v_mul_f32_e32 v137, 0xbfb8aa3b, v179
	v_mul_f32_e32 v138, 0xbfb8aa3b, v176
	v_mul_f32_e32 v139, 0xbfb8aa3b, v177
	v_mul_f32_e32 v140, 0xbfb8aa3b, v174
	v_mul_f32_e32 v141, 0xbfb8aa3b, v175
	v_mul_f32_e32 v142, 0xbfb8aa3b, v172
	v_mul_f32_e32 v143, 0xbfb8aa3b, v173
	v_pk_fma_f32 v[4:5], v[4:5], v[74:75], v[82:83]
	v_add_f32_e32 v16, 1.0, v16
	v_add_f32_e32 v17, 1.0, v17
	v_add_f32_e32 v18, 1.0, v18
	v_add_f32_e32 v19, 1.0, v19
	v_add_f32_e32 v20, 1.0, v20
	v_add_f32_e32 v21, 1.0, v21
	v_add_f32_e32 v22, 1.0, v22
	v_add_f32_e32 v23, 1.0, v23
	v_exp_f32_e32 v136, v136
	v_exp_f32_e32 v137, v137
	v_exp_f32_e32 v138, v138
	v_exp_f32_e32 v139, v139
	v_exp_f32_e32 v140, v140
	v_exp_f32_e32 v141, v141
	v_exp_f32_e32 v142, v142
	v_exp_f32_e32 v143, v143
	v_mul_f32_e32 v144, 0xbfb8aa3b, v164
	v_mul_f32_e32 v145, 0xbfb8aa3b, v165
	v_mul_f32_e32 v146, 0xbfb8aa3b, v160
	v_mul_f32_e32 v147, 0xbfb8aa3b, v161
	v_add_f32_e32 v148, 1.0, v148
	v_add_f32_e32 v149, 1.0, v149
	v_mul_f32_e32 v150, 0xbfb8aa3b, v84
	v_mul_f32_e32 v151, 0xbfb8aa3b, v85
	v_mul_f32_e32 v74, 0xbfb8aa3b, v4
	v_pk_fma_f32 v[6:7], v[6:7], v[72:73], v[80:81]
	v_add_f32_e32 v70, 1.0, v70
	v_add_f32_e32 v71, 1.0, v71
	v_add_f32_e32 v66, 1.0, v66
	v_add_f32_e32 v67, 1.0, v67
	v_rcp_f32_e32 v16, v16
	v_rcp_f32_e32 v17, v17
	v_rcp_f32_e32 v18, v18
	v_rcp_f32_e32 v19, v19
	v_rcp_f32_e32 v20, v20
	v_rcp_f32_e32 v21, v21
	v_rcp_f32_e32 v22, v22
	v_rcp_f32_e32 v23, v23
	v_add_f32_e32 v24, 1.0, v24
	v_add_f32_e32 v25, 1.0, v25
	v_add_f32_e32 v26, 1.0, v26
	v_add_f32_e32 v27, 1.0, v27
	v_add_f32_e32 v28, 1.0, v28
	v_add_f32_e32 v29, 1.0, v29
	v_add_f32_e32 v30, 1.0, v30
	v_add_f32_e32 v31, 1.0, v31
	v_exp_f32_e32 v144, v144
	v_exp_f32_e32 v145, v145
	v_exp_f32_e32 v146, v146
	v_exp_f32_e32 v147, v147
	v_rcp_f32_e32 v148, v148
	v_rcp_f32_e32 v149, v149
	v_exp_f32_e32 v150, v150
	v_exp_f32_e32 v151, v151
	v_exp_f32_e32 v82, v74
	v_mul_f32_e32 v74, 0xbfb8aa3b, v5
	v_mul_f32_e32 v72, 0xbfb8aa3b, v6
	v_mul_f32_e32 v73, 0xbfb8aa3b, v7
	v_rcp_f32_e32 v70, v70
	v_rcp_f32_e32 v71, v71
	v_rcp_f32_e32 v66, v66
	v_rcp_f32_e32 v67, v67
	v_rcp_f32_e32 v24, v24
	v_rcp_f32_e32 v25, v25
	v_rcp_f32_e32 v26, v26
	v_rcp_f32_e32 v27, v27
	v_rcp_f32_e32 v28, v28
	v_rcp_f32_e32 v29, v29
	v_rcp_f32_e32 v30, v30
	v_rcp_f32_e32 v31, v31
	v_add_f32_e32 v68, 1.0, v68
	v_add_f32_e32 v69, 1.0, v69
	v_add_f32_e32 v88, 1.0, v88
	v_add_f32_e32 v89, 1.0, v89
	v_add_f32_e32 v124, 1.0, v124
	v_add_f32_e32 v125, 1.0, v125
	v_add_f32_e32 v126, 1.0, v126
	v_add_f32_e32 v127, 1.0, v127
	v_exp_f32_e32 v83, v74
	v_exp_f32_e32 v72, v72
	v_exp_f32_e32 v73, v73
	v_rcp_f32_e32 v68, v68
	v_rcp_f32_e32 v69, v69
	v_rcp_f32_e32 v88, v88
	v_rcp_f32_e32 v89, v89
	v_rcp_f32_e32 v124, v124
	v_rcp_f32_e32 v125, v125
	v_rcp_f32_e32 v126, v126
	v_rcp_f32_e32 v127, v127
	v_add_f32_e32 v128, 1.0, v128
	v_add_f32_e32 v129, 1.0, v129
	v_add_f32_e32 v130, 1.0, v130
	v_add_f32_e32 v131, 1.0, v131
	v_add_f32_e32 v132, 1.0, v132
	v_add_f32_e32 v133, 1.0, v133
	v_add_f32_e32 v134, 1.0, v134
	v_add_f32_e32 v135, 1.0, v135
	v_rcp_f32_e32 v128, v128
	v_rcp_f32_e32 v129, v129
	v_rcp_f32_e32 v130, v130
	v_rcp_f32_e32 v131, v131
	v_rcp_f32_e32 v132, v132
	v_rcp_f32_e32 v133, v133
	v_rcp_f32_e32 v134, v134
	v_rcp_f32_e32 v135, v135
	v_add_f32_e32 v136, 1.0, v136
	v_add_f32_e32 v137, 1.0, v137
	v_add_f32_e32 v138, 1.0, v138
	v_add_f32_e32 v139, 1.0, v139
	v_add_f32_e32 v140, 1.0, v140
	v_add_f32_e32 v141, 1.0, v141
	v_add_f32_e32 v142, 1.0, v142
	v_add_f32_e32 v143, 1.0, v143
	v_pk_mul_f32 v[16:17], v[152:153], v[16:17]
	v_pk_mul_f32 v[18:19], v[154:155], v[18:19]
	v_pk_mul_f32 v[20:21], v[156:157], v[20:21]
	v_pk_mul_f32 v[22:23], v[158:159], v[22:23]
	v_rcp_f32_e32 v136, v136
	v_rcp_f32_e32 v137, v137
	v_rcp_f32_e32 v138, v138
	v_rcp_f32_e32 v139, v139
	v_rcp_f32_e32 v140, v140
	v_rcp_f32_e32 v141, v141
	v_rcp_f32_e32 v142, v142
	v_rcp_f32_e32 v143, v143
	v_add_f32_e32 v144, 1.0, v144
	v_add_f32_e32 v145, 1.0, v145
	v_add_f32_e32 v146, 1.0, v146
	v_add_f32_e32 v147, 1.0, v147
	v_pk_mul_f32 v[86:87], v[86:87], v[148:149]
	v_add_f32_e32 v148, 1.0, v150
	v_add_f32_e32 v149, 1.0, v151
	v_pk_mul_f32 v[70:71], v[0:1], v[70:71]
; #define LAS __attribute__((address_space(3)))
; __device__ __forceinline__ v4u pk8(const float (&a)[8], const float s) { return (v4u){pk2(a[0] * s, a[1] * s), pk2(a[2] * s, a[3] * s), pk2(a[4] * s, a[5] * s), pk2(a[6] * s, a[7] * s)}; }
; __device__ __forceinline__ void intra_item(Frame& F, const int item, LAS unsigned char* SA, LAS unsigned char* SB, LAS float* GC, LAS float* BT) {
;     ...
;     prep_seg(QK, cw, rowbase, t0, h, 2, lane, o);
; #pragma unroll
;     for (int r = 0; r < 8; ++r) *(LAS v4u*)(SA + (8 * rg + r) * STRB + cg * 16) = pk8(o[r], 1.f);
; #pragma unroll
;     for (int c8 = 0; c8 < 8; ++c8) { float uu[8]; __builtin_amdgcn_sched_barrier(0);
; #pragma unroll
;         for (int e = 0; e < 8; ++e) { const int s = c8 * 8 + e; uu[e] = X[s] * BT[s]; }
;         *(LAS v4u*)(SB + lane * STRB + c8 * 16) = pk8(uu, 1.f); }
	v_pk_mul_f32 v[66:67], v[2:3], v[66:67]
	v_cvt_pk_bf16_f32 v0, v8, v9
	v_cvt_pk_bf16_f32 v1, v10, v11
	v_cvt_pk_bf16_f32 v2, v12, v13
	v_cvt_pk_bf16_f32 v3, v14, v15
	v_pk_mul_f32 v[24:25], v[162:163], v[24:25]
	v_pk_mul_f32 v[26:27], v[166:167], v[26:27]
	v_pk_mul_f32 v[28:29], v[168:169], v[28:29]
	v_pk_mul_f32 v[30:31], v[170:171], v[30:31]
	v_rcp_f32_e32 v144, v144
	v_rcp_f32_e32 v145, v145
	v_rcp_f32_e32 v146, v146
	v_rcp_f32_e32 v147, v147
	v_rcp_f32_e32 v148, v148
	v_rcp_f32_e32 v149, v149
	v_add_f32_e32 v82, 1.0, v82
	v_add_f32_e32 v83, 1.0, v83
	v_add_f32_e32 v72, 1.0, v72
	v_add_f32_e32 v73, 1.0, v73
	ds_write_b128 v211, v[0:3]
	v_cvt_pk_bf16_f32 v0, v16, v17
	v_cvt_pk_bf16_f32 v1, v18, v19
	v_cvt_pk_bf16_f32 v2, v20, v21
	v_cvt_pk_bf16_f32 v3, v22, v23
	v_pk_mul_f32 v[68:69], v[198:199], v[68:69]
	v_pk_mul_f32 v[88:89], v[196:197], v[88:89]
	v_pk_mul_f32 v[124:125], v[182:183], v[124:125]
	v_pk_mul_f32 v[126:127], v[180:181], v[126:127]
	v_rcp_f32_e32 v82, v82
	v_rcp_f32_e32 v83, v83
	v_rcp_f32_e32 v72, v72
	v_rcp_f32_e32 v73, v73
	ds_write_b128 v211, v[0:3] offset:144
	v_cvt_pk_bf16_f32 v0, v24, v25
	v_cvt_pk_bf16_f32 v1, v26, v27
	v_cvt_pk_bf16_f32 v2, v28, v29
	v_cvt_pk_bf16_f32 v3, v30, v31
	v_pk_mul_f32 v[128:129], v[194:195], v[128:129]
	v_pk_mul_f32 v[130:131], v[192:193], v[130:131]
	v_pk_mul_f32 v[132:133], v[190:191], v[132:133]
	v_pk_mul_f32 v[134:135], v[188:189], v[134:135]
	ds_write_b128 v211, v[0:3] offset:288
	v_cvt_pk_bf16_f32 v0, v68, v69
	v_cvt_pk_bf16_f32 v1, v88, v89
	v_cvt_pk_bf16_f32 v2, v124, v125
	v_cvt_pk_bf16_f32 v3, v126, v127
	v_pk_mul_f32 v[136:137], v[178:179], v[136:137]
	v_pk_mul_f32 v[138:139], v[176:177], v[138:139]
	v_pk_mul_f32 v[140:141], v[174:175], v[140:141]
	v_pk_mul_f32 v[142:143], v[172:173], v[142:143]
	ds_write_b128 v211, v[0:3] offset:432
	v_cvt_pk_bf16_f32 v0, v128, v129
	v_cvt_pk_bf16_f32 v1, v130, v131
	v_cvt_pk_bf16_f32 v2, v132, v133
	v_cvt_pk_bf16_f32 v3, v134, v135
	v_pk_mul_f32 v[144:145], v[164:165], v[144:145]
	v_pk_mul_f32 v[146:147], v[160:161], v[146:147]
	v_pk_mul_f32 v[74:75], v[84:85], v[148:149]
	ds_write_b128 v211, v[0:3] offset:576
	v_cvt_pk_bf16_f32 v0, v136, v137
	v_cvt_pk_bf16_f32 v1, v138, v139
	v_cvt_pk_bf16_f32 v2, v140, v141
	v_cvt_pk_bf16_f32 v3, v142, v143
	v_pk_mul_f32 v[4:5], v[4:5], v[82:83]
	v_pk_mul_f32 v[6:7], v[6:7], v[72:73]
	ds_write_b128 v211, v[0:3] offset:720
	v_cvt_pk_bf16_f32 v0, v144, v145
	v_cvt_pk_bf16_f32 v1, v146, v147
	v_cvt_pk_bf16_f32 v2, v86, v87
	v_cvt_pk_bf16_f32 v3, v74, v75
	ds_write_b128 v211, v[0:3] offset:864
	v_cvt_pk_bf16_f32 v0, v4, v5
	v_cvt_pk_bf16_f32 v1, v6, v7
	v_cvt_pk_bf16_f32 v2, v70, v71
	v_cvt_pk_bf16_f32 v3, v66, v67
	ds_write_b128 v212, v[0:3]
	v_mov_b32_e32 v8, s31
	ds_read_b128 v[0:3], v8 offset:18688
	ds_read_b128 v[4:7], v8 offset:18704
	s_waitcnt lgkmcnt(1)
	v_pk_mul_f32 v[0:1], v[122:123], v[0:1]
	v_pk_mul_f32 v[2:3], v[120:121], v[2:3]
	s_waitcnt lgkmcnt(0)
	v_pk_mul_f32 v[4:5], v[118:119], v[4:5]
	v_pk_mul_f32 v[6:7], v[116:117], v[6:7]
	v_cvt_pk_bf16_f32 v0, v0, v1
	v_cvt_pk_bf16_f32 v1, v2, v3
	v_cvt_pk_bf16_f32 v2, v4, v5
	v_cvt_pk_bf16_f32 v3, v6, v7
	ds_write_b128 v214, v[0:3] offset:9216
	ds_read_b128 v[0:3], v8 offset:18720
	ds_read_b128 v[4:7], v8 offset:18736
	s_waitcnt lgkmcnt(1)
	v_pk_mul_f32 v[0:1], v[114:115], v[0:1]
	v_pk_mul_f32 v[2:3], v[112:113], v[2:3]
	s_waitcnt lgkmcnt(0)
	v_pk_mul_f32 v[4:5], v[110:111], v[4:5]
	v_pk_mul_f32 v[6:7], v[108:109], v[6:7]
	v_cvt_pk_bf16_f32 v0, v0, v1
	v_cvt_pk_bf16_f32 v1, v2, v3
	v_cvt_pk_bf16_f32 v2, v4, v5
	v_cvt_pk_bf16_f32 v3, v6, v7
	ds_write_b128 v214, v[0:3] offset:9232
	ds_read_b128 v[0:3], v8 offset:18752
	ds_read_b128 v[4:7], v8 offset:18768
	s_waitcnt lgkmcnt(1)
	v_pk_mul_f32 v[0:1], v[106:107], v[0:1]
	v_pk_mul_f32 v[2:3], v[104:105], v[2:3]
	s_waitcnt lgkmcnt(0)
	v_pk_mul_f32 v[4:5], v[102:103], v[4:5]
	v_pk_mul_f32 v[6:7], v[100:101], v[6:7]
	v_cvt_pk_bf16_f32 v0, v0, v1
	v_cvt_pk_bf16_f32 v1, v2, v3
	v_cvt_pk_bf16_f32 v2, v4, v5
	v_cvt_pk_bf16_f32 v3, v6, v7
	ds_write_b128 v214, v[0:3] offset:9248
	ds_read_b128 v[0:3], v8 offset:18784
	ds_read_b128 v[4:7], v8 offset:18800
	s_waitcnt lgkmcnt(1)
	v_pk_mul_f32 v[0:1], v[98:99], v[0:1]
	v_pk_mul_f32 v[2:3], v[96:97], v[2:3]
	s_waitcnt lgkmcnt(0)
	v_pk_mul_f32 v[4:5], v[94:95], v[4:5]
	v_pk_mul_f32 v[6:7], v[62:63], v[6:7]
	v_cvt_pk_bf16_f32 v0, v0, v1
	v_cvt_pk_bf16_f32 v1, v2, v3
	v_cvt_pk_bf16_f32 v2, v4, v5
	v_cvt_pk_bf16_f32 v3, v6, v7
	ds_write_b128 v214, v[0:3] offset:9264
	ds_read_b128 v[0:3], v8 offset:18816
	ds_read_b128 v[4:7], v8 offset:18832
	s_waitcnt lgkmcnt(1)
	v_pk_mul_f32 v[0:1], v[60:61], v[0:1]
	v_pk_mul_f32 v[2:3], v[58:59], v[2:3]
	s_waitcnt lgkmcnt(0)
	v_pk_mul_f32 v[4:5], v[56:57], v[4:5]
	v_pk_mul_f32 v[6:7], v[54:55], v[6:7]
	v_cvt_pk_bf16_f32 v0, v0, v1
	v_cvt_pk_bf16_f32 v1, v2, v3
	v_cvt_pk_bf16_f32 v2, v4, v5
	v_cvt_pk_bf16_f32 v3, v6, v7
	ds_write_b128 v214, v[0:3] offset:9280
	ds_read_b128 v[0:3], v8 offset:18848
	ds_read_b128 v[4:7], v8 offset:18864
	s_waitcnt lgkmcnt(1)
	v_pk_mul_f32 v[0:1], v[52:53], v[0:1]
	v_pk_mul_f32 v[2:3], v[50:51], v[2:3]
	s_waitcnt lgkmcnt(0)
	v_pk_mul_f32 v[4:5], v[48:49], v[4:5]
	v_pk_mul_f32 v[6:7], v[46:47], v[6:7]
	v_cvt_pk_bf16_f32 v0, v0, v1
	v_cvt_pk_bf16_f32 v1, v2, v3
	v_cvt_pk_bf16_f32 v2, v4, v5
	v_cvt_pk_bf16_f32 v3, v6, v7
	ds_write_b128 v214, v[0:3] offset:9296
	ds_read_b128 v[0:3], v8 offset:18880
	ds_read_b128 v[4:7], v8 offset:18896
	s_waitcnt lgkmcnt(1)
	v_pk_mul_f32 v[0:1], v[44:45], v[0:1]
	v_pk_mul_f32 v[2:3], v[42:43], v[2:3]
	s_waitcnt lgkmcnt(0)
	v_pk_mul_f32 v[4:5], v[40:41], v[4:5]
	v_pk_mul_f32 v[6:7], v[38:39], v[6:7]
	v_cvt_pk_bf16_f32 v0, v0, v1
	v_cvt_pk_bf16_f32 v1, v2, v3
	v_cvt_pk_bf16_f32 v2, v4, v5
	v_cvt_pk_bf16_f32 v3, v6, v7
	ds_write_b128 v214, v[0:3] offset:9312
	ds_read_b128 v[0:3], v8 offset:18912
	ds_read_b128 v[4:7], v8 offset:18928
	v_add3_u32 v20, v213, v216, s69
	s_mov_b64 s[0:1], 0
	v_add_u32_e32 v21, v91, v215
	s_waitcnt lgkmcnt(1)
	v_pk_mul_f32 v[0:1], v[34:35], v[0:1]
	v_pk_mul_f32 v[2:3], v[32:33], v[2:3]
	s_waitcnt lgkmcnt(0)
	v_pk_mul_f32 v[4:5], v[36:37], v[4:5]
	v_pk_mul_f32 v[6:7], v[92:93], v[6:7]
	v_cvt_pk_bf16_f32 v0, v0, v1
	v_cvt_pk_bf16_f32 v1, v2, v3
	v_cvt_pk_bf16_f32 v2, v4, v5
	v_cvt_pk_bf16_f32 v3, v6, v7
	ds_write_b128 v214, v[0:3] offset:9328
	v_add_u32_e32 v0, v64, v90
	v_ashrrev_i32_e32 v1, 31, v0
	v_lshl_add_u64 v[16:17], s[50:51], 0, v[0:1]
	s_branch .LBB0_1070
